# v31 + spec_mul 0.5 and 1/N scalings folded into one constant (exact), redundant barrier of the Hyena gating stage removed
# speedup vs baseline: 1.0031x; 1.0031x over previous
.LBB0_433:
	v_add_u32_e32 v160, 0x11000, v155
	v_lshlrev_b32_e32 v161, 3, v154
	v_add_u32_e32 v161, 0x2200, v161
	v_add_u32_e32 v162, 0x11100, v156
	v_cmp_ne_u32_e32 vcc, 0, v32
	v_cndmask_b32_e32 v163, 0, v154, vcc
	v_lshlrev_b32_e32 v163, 3, v163
	v_add_u32_e32 v163, 0x11000, v163
	s_mov_b32 s100, 0x38800000
	s_mov_b32 s101, 0xb8800000
	ds_read_b64 v[214:215], v160 offset:0
	ds_read_b64 v[216:217], v163
	ds_read_b64 v[218:219], v160 offset:4352
	ds_read_b64 v[220:221], v162 offset:60928
	ds_read_b64 v[222:223], v160 offset:8704
	ds_read_b64 v[224:225], v161 offset:52224
	ds_read_b64 v[226:227], v160 offset:13056
	ds_read_b64 v[228:229], v162 offset:52224
	s_waitcnt lgkmcnt(6)
	v_add_f32_e32 v214, v214, v216
	v_sub_f32_e32 v216, v215, v217
	v_pk_mul_f32 v[216:217], v[6:7], v[216:217] op_sel:[1,0] op_sel_hi:[0,0]
	v_pk_fma_f32 v[158:159], v[6:7], v[214:215], v[216:217] neg_lo:[0,0,1] neg_hi:[0,0,1]
	v_pk_fma_f32 v[214:215], v[6:7], v[214:215], v[216:217] op_sel_hi:[1,0,1]
	s_nop 0
	v_mov_b32_e32 v159, v215
	v_pk_mul_f32 v[6:7], v[158:159], s[100:101]
	ds_write_b64 v155, v[6:7] offset:0
	s_waitcnt lgkmcnt(5)
	v_add_f32_e32 v218, v218, v220
	v_sub_f32_e32 v220, v219, v221
	v_pk_mul_f32 v[220:221], v[18:19], v[220:221] op_sel:[1,0] op_sel_hi:[0,0]
	v_pk_fma_f32 v[158:159], v[18:19], v[218:219], v[220:221] neg_lo:[0,0,1] neg_hi:[0,0,1]
	v_pk_fma_f32 v[218:219], v[18:19], v[218:219], v[220:221] op_sel_hi:[1,0,1]
	s_nop 0
	v_mov_b32_e32 v159, v219
	v_pk_mul_f32 v[18:19], v[158:159], s[100:101]
	ds_write_b64 v155, v[18:19] offset:4352
	ds_read_b64 v[230:231], v160 offset:17408
	ds_read_b64 v[232:233], v161 offset:43520
	ds_read_b64 v[234:235], v160 offset:21760
	ds_read_b64 v[236:237], v162 offset:43520
	s_waitcnt lgkmcnt(8)
	v_add_f32_e32 v222, v222, v224
	v_sub_f32_e32 v224, v223, v225
	v_pk_mul_f32 v[224:225], v[28:29], v[224:225] op_sel:[1,0] op_sel_hi:[0,0]
	v_pk_fma_f32 v[158:159], v[28:29], v[222:223], v[224:225] neg_lo:[0,0,1] neg_hi:[0,0,1]
	v_pk_fma_f32 v[222:223], v[28:29], v[222:223], v[224:225] op_sel_hi:[1,0,1]
	s_nop 0
	v_mov_b32_e32 v159, v223
	v_pk_mul_f32 v[28:29], v[158:159], s[100:101]
	ds_write_b64 v155, v[28:29] offset:8704
	s_waitcnt lgkmcnt(7)
	v_add_f32_e32 v226, v226, v228
	v_sub_f32_e32 v228, v227, v229
	v_pk_mul_f32 v[228:229], v[10:11], v[228:229] op_sel:[1,0] op_sel_hi:[0,0]
	v_pk_fma_f32 v[158:159], v[10:11], v[226:227], v[228:229] neg_lo:[0,0,1] neg_hi:[0,0,1]
	v_pk_fma_f32 v[226:227], v[10:11], v[226:227], v[228:229] op_sel_hi:[1,0,1]
	s_nop 0
	v_mov_b32_e32 v159, v227
	v_pk_mul_f32 v[10:11], v[158:159], s[100:101]
	ds_write_b64 v155, v[10:11] offset:13056
	ds_read_b64 v[214:215], v160 offset:26112
	ds_read_b64 v[216:217], v161 offset:34816
	ds_read_b64 v[218:219], v160 offset:30464
	ds_read_b64 v[220:221], v162 offset:34816
	s_waitcnt lgkmcnt(8)
	v_add_f32_e32 v230, v230, v232
	v_sub_f32_e32 v232, v231, v233
	v_pk_mul_f32 v[232:233], v[26:27], v[232:233] op_sel:[1,0] op_sel_hi:[0,0]
	v_pk_fma_f32 v[158:159], v[26:27], v[230:231], v[232:233] neg_lo:[0,0,1] neg_hi:[0,0,1]
	v_pk_fma_f32 v[230:231], v[26:27], v[230:231], v[232:233] op_sel_hi:[1,0,1]
	s_nop 0
	v_mov_b32_e32 v159, v231
	v_pk_mul_f32 v[26:27], v[158:159], s[100:101]
	ds_write_b64 v155, v[26:27] offset:17408
	s_waitcnt lgkmcnt(7)
	v_add_f32_e32 v234, v234, v236
	v_sub_f32_e32 v236, v235, v237
	v_pk_mul_f32 v[236:237], v[30:31], v[236:237] op_sel:[1,0] op_sel_hi:[0,0]
	v_pk_fma_f32 v[158:159], v[30:31], v[234:235], v[236:237] neg_lo:[0,0,1] neg_hi:[0,0,1]
	v_pk_fma_f32 v[234:235], v[30:31], v[234:235], v[236:237] op_sel_hi:[1,0,1]
	s_nop 0
	v_mov_b32_e32 v159, v235
	v_pk_mul_f32 v[30:31], v[158:159], s[100:101]
	ds_write_b64 v155, v[30:31] offset:21760
	ds_read_b64 v[222:223], v160 offset:34816
	ds_read_b64 v[224:225], v161 offset:26112
	ds_read_b64 v[226:227], v160 offset:39168
	ds_read_b64 v[228:229], v162 offset:26112
	s_waitcnt lgkmcnt(8)
	v_add_f32_e32 v214, v214, v216
	v_sub_f32_e32 v216, v215, v217
	v_pk_mul_f32 v[216:217], v[80:81], v[216:217] op_sel:[1,0] op_sel_hi:[0,0]
	v_pk_fma_f32 v[158:159], v[80:81], v[214:215], v[216:217] neg_lo:[0,0,1] neg_hi:[0,0,1]
	v_pk_fma_f32 v[214:215], v[80:81], v[214:215], v[216:217] op_sel_hi:[1,0,1]
	s_nop 0
	v_mov_b32_e32 v159, v215
	v_pk_mul_f32 v[80:81], v[158:159], s[100:101]
	ds_write_b64 v155, v[80:81] offset:26112
	s_waitcnt lgkmcnt(7)
	v_add_f32_e32 v218, v218, v220
	v_sub_f32_e32 v220, v219, v221
	v_pk_mul_f32 v[220:221], v[12:13], v[220:221] op_sel:[1,0] op_sel_hi:[0,0]
	v_pk_fma_f32 v[158:159], v[12:13], v[218:219], v[220:221] neg_lo:[0,0,1] neg_hi:[0,0,1]
	v_pk_fma_f32 v[218:219], v[12:13], v[218:219], v[220:221] op_sel_hi:[1,0,1]
	s_nop 0
	v_mov_b32_e32 v159, v219
	v_pk_mul_f32 v[12:13], v[158:159], s[100:101]
	ds_write_b64 v155, v[12:13] offset:30464
	ds_read_b64 v[230:231], v160 offset:43520
	ds_read_b64 v[232:233], v161 offset:17408
	ds_read_b64 v[234:235], v160 offset:47872
	ds_read_b64 v[236:237], v162 offset:17408
	s_waitcnt lgkmcnt(8)
	v_add_f32_e32 v222, v222, v224
	v_sub_f32_e32 v224, v223, v225
	v_pk_mul_f32 v[224:225], v[14:15], v[224:225] op_sel:[1,0] op_sel_hi:[0,0]
	v_pk_fma_f32 v[158:159], v[14:15], v[222:223], v[224:225] neg_lo:[0,0,1] neg_hi:[0,0,1]
	v_pk_fma_f32 v[222:223], v[14:15], v[222:223], v[224:225] op_sel_hi:[1,0,1]
	s_nop 0
	v_mov_b32_e32 v159, v223
	v_pk_mul_f32 v[14:15], v[158:159], s[100:101]
	ds_write_b64 v155, v[14:15] offset:34816
	s_waitcnt lgkmcnt(7)
	v_add_f32_e32 v226, v226, v228
	v_sub_f32_e32 v228, v227, v229
	v_pk_mul_f32 v[228:229], v[20:21], v[228:229] op_sel:[1,0] op_sel_hi:[0,0]
	v_pk_fma_f32 v[158:159], v[20:21], v[226:227], v[228:229] neg_lo:[0,0,1] neg_hi:[0,0,1]
	v_pk_fma_f32 v[226:227], v[20:21], v[226:227], v[228:229] op_sel_hi:[1,0,1]
	s_nop 0
	v_mov_b32_e32 v159, v227
	v_pk_mul_f32 v[20:21], v[158:159], s[100:101]
	ds_write_b64 v155, v[20:21] offset:39168
	ds_read_b64 v[214:215], v160 offset:52224
	ds_read_b64 v[216:217], v161 offset:8704
	ds_read_b64 v[218:219], v160 offset:56576
	ds_read_b64 v[220:221], v162 offset:8704
	s_waitcnt lgkmcnt(8)
	v_add_f32_e32 v230, v230, v232
	v_sub_f32_e32 v232, v231, v233
	v_pk_mul_f32 v[232:233], v[22:23], v[232:233] op_sel:[1,0] op_sel_hi:[0,0]
	v_pk_fma_f32 v[158:159], v[22:23], v[230:231], v[232:233] neg_lo:[0,0,1] neg_hi:[0,0,1]
	v_pk_fma_f32 v[230:231], v[22:23], v[230:231], v[232:233] op_sel_hi:[1,0,1]
	s_nop 0
	v_mov_b32_e32 v159, v231
	v_pk_mul_f32 v[22:23], v[158:159], s[100:101]
	ds_write_b64 v155, v[22:23] offset:43520
	s_waitcnt lgkmcnt(7)
	v_add_f32_e32 v234, v234, v236
	v_sub_f32_e32 v236, v235, v237
	v_pk_mul_f32 v[236:237], v[4:5], v[236:237] op_sel:[1,0] op_sel_hi:[0,0]
	v_pk_fma_f32 v[158:159], v[4:5], v[234:235], v[236:237] neg_lo:[0,0,1] neg_hi:[0,0,1]
	v_pk_fma_f32 v[234:235], v[4:5], v[234:235], v[236:237] op_sel_hi:[1,0,1]
	s_nop 0
	v_mov_b32_e32 v159, v235
	v_pk_mul_f32 v[4:5], v[158:159], s[100:101]
	ds_write_b64 v155, v[4:5] offset:47872
	ds_read_b64 v[222:223], v160 offset:60928
	ds_read_b64 v[224:225], v161 offset:0
	ds_read_b64 v[226:227], v160 offset:65280
	ds_read_b64 v[228:229], v162 offset:0
	s_waitcnt lgkmcnt(8)
	v_add_f32_e32 v214, v214, v216
	v_sub_f32_e32 v216, v215, v217
	v_pk_mul_f32 v[216:217], v[24:25], v[216:217] op_sel:[1,0] op_sel_hi:[0,0]
	v_pk_fma_f32 v[158:159], v[24:25], v[214:215], v[216:217] neg_lo:[0,0,1] neg_hi:[0,0,1]
	v_pk_fma_f32 v[214:215], v[24:25], v[214:215], v[216:217] op_sel_hi:[1,0,1]
	s_nop 0
	v_mov_b32_e32 v159, v215
	v_pk_mul_f32 v[24:25], v[158:159], s[100:101]
	ds_write_b64 v155, v[24:25] offset:52224
	s_waitcnt lgkmcnt(7)
	v_add_f32_e32 v218, v218, v220
	v_sub_f32_e32 v220, v219, v221
	v_pk_mul_f32 v[220:221], v[8:9], v[220:221] op_sel:[1,0] op_sel_hi:[0,0]
	v_pk_fma_f32 v[158:159], v[8:9], v[218:219], v[220:221] neg_lo:[0,0,1] neg_hi:[0,0,1]
	v_pk_fma_f32 v[218:219], v[8:9], v[218:219], v[220:221] op_sel_hi:[1,0,1]
	s_nop 0
	v_mov_b32_e32 v159, v219
	v_pk_mul_f32 v[8:9], v[158:159], s[100:101]
	ds_write_b64 v155, v[8:9] offset:56576
	s_waitcnt lgkmcnt(4)
	v_add_f32_e32 v222, v222, v224
	v_sub_f32_e32 v224, v223, v225
	v_pk_mul_f32 v[224:225], v[16:17], v[224:225] op_sel:[1,0] op_sel_hi:[0,0]
	v_pk_fma_f32 v[158:159], v[16:17], v[222:223], v[224:225] neg_lo:[0,0,1] neg_hi:[0,0,1]
	v_pk_fma_f32 v[222:223], v[16:17], v[222:223], v[224:225] op_sel_hi:[1,0,1]
	s_nop 0
	v_mov_b32_e32 v159, v223
	v_pk_mul_f32 v[16:17], v[158:159], s[100:101]
	ds_write_b64 v155, v[16:17] offset:60928
	s_waitcnt lgkmcnt(3)
	v_add_f32_e32 v226, v226, v228
	v_sub_f32_e32 v228, v227, v229
	v_pk_mul_f32 v[228:229], v[0:1], v[228:229] op_sel:[1,0] op_sel_hi:[0,0]
	v_pk_fma_f32 v[158:159], v[0:1], v[226:227], v[228:229] neg_lo:[0,0,1] neg_hi:[0,0,1]
	v_pk_fma_f32 v[226:227], v[0:1], v[226:227], v[228:229] op_sel_hi:[1,0,1]
	s_nop 0
	v_mov_b32_e32 v159, v227
	v_pk_mul_f32 v[0:1], v[158:159], s[100:101]
	ds_write_b64 v155, v[0:1] offset:65280
	s_mov_b32 s0, 16
	s_cmp_lg_u32 s0, 16
	s_waitcnt lgkmcnt(0)
	s_barrier
	s_and_saveexec_b64 s[0:1], s[40:41]
	s_cbranch_execz .LBB0_436
	ds_read_b64 v[0:1], v37 offset:2176
	ds_read_b64 v[2:3], v37 offset:4352
	ds_read_b64 v[4:5], v37 offset:6528
	ds_read_b64 v[6:7], v37 offset:8704
	ds_read_b64 v[8:9], v37 offset:10880
	ds_read_b64 v[10:11], v37 offset:13056
	ds_read_b64 v[12:13], v37 offset:15232
	ds_read_b64 v[14:15], v37 offset:17408
	ds_read_b64 v[16:17], v37 offset:19584
	ds_read_b64 v[18:19], v37 offset:21760
	ds_read_b64 v[20:21], v37 offset:23936
	ds_read_b64 v[22:23], v37 offset:26112
	ds_read_b64 v[24:25], v37 offset:34816
	ds_read_b64 v[26:27], v37 offset:36992
	ds_read_b64 v[28:29], v37 offset:39168
	ds_read_b64 v[30:31], v37 offset:41344
	ds_read_b64 v[102:103], v37 offset:43520
	ds_read_b64 v[110:111], v37 offset:45696
	ds_read_b64 v[118:119], v37 offset:47872
	ds_read_b64 v[120:121], v37 offset:50048
	ds_read_b64 v[122:123], v37 offset:52224
	ds_read_b64 v[124:125], v37 offset:54400
	ds_read_b64 v[126:127], v37 offset:56576
	ds_read_b64 v[128:129], v37 offset:58752
	ds_read_b64 v[130:131], v37
	ds_read_b64 v[132:133], v37 offset:60928
	ds_read_b64 v[134:135], v37 offset:63104
	ds_read_b64 v[136:137], v37 offset:65280
	s_mov_b32 s11, s14
	s_waitcnt lgkmcnt(3)
	v_pk_add_f32 v[158:159], v[130:131], v[24:25]
	v_pk_add_f32 v[24:25], v[130:131], v[24:25] neg_lo:[0,1] neg_hi:[0,1]
	v_pk_add_f32 v[130:131], v[0:1], v[26:27]
	v_pk_add_f32 v[0:1], v[0:1], v[26:27] neg_lo:[0,1] neg_hi:[0,1]
	s_mov_b32 s13, s86
	v_pk_mul_f32 v[26:27], v[0:1], s[16:17]
	s_mov_b32 s4, s21
	v_pk_fma_f32 v[0:1], v[0:1], s[6:7], v[26:27] op_sel:[0,0,1] op_sel_hi:[1,0,0]
	v_pk_add_f32 v[26:27], v[2:3], v[28:29]
	v_pk_add_f32 v[2:3], v[2:3], v[28:29] neg_lo:[0,1] neg_hi:[0,1]
	s_mov_b32 s35, s30
	v_pk_mul_f32 v[28:29], v[2:3], s[18:19]
	s_mov_b32 s8, s19
	v_pk_fma_f32 v[2:3], v[2:3], s[30:31], v[28:29] op_sel:[0,0,1] op_sel_hi:[1,0,0]
	v_pk_add_f32 v[28:29], v[4:5], v[30:31]
	v_pk_add_f32 v[4:5], v[4:5], v[30:31] neg_lo:[0,1] neg_hi:[0,1]
	s_mov_b32 s77, s6
	v_pk_mul_f32 v[30:31], v[4:5], s[20:21]
	s_mov_b32 s28, s17
	v_pk_fma_f32 v[4:5], v[4:5], s[86:87], v[30:31] op_sel:[0,0,1] op_sel_hi:[1,0,0]
	v_pk_add_f32 v[30:31], v[6:7], v[102:103]
	v_pk_add_f32 v[6:7], v[6:7], v[102:103] neg_lo:[0,1] neg_hi:[0,1]
	v_add_u32_e32 v47, 0x10780, v37
	v_pk_mul_f32 v[102:103], v[6:7], s[10:11]
	ds_read_b64 v[138:139], v37 offset:28288
	ds_read_b64 v[140:141], v37 offset:30464
	ds_read_b64 v[142:143], v37 offset:32640
	ds_read_b64 v[144:145], v47
	v_pk_fma_f32 v[6:7], v[6:7], s[14:15], v[102:103] op_sel:[0,0,1] op_sel_hi:[1,0,0]
	v_pk_add_f32 v[102:103], v[8:9], v[110:111]
	v_pk_add_f32 v[8:9], v[8:9], v[110:111] neg_lo:[0,1] neg_hi:[0,1]
	s_nop 0
	v_pk_mul_f32 v[110:111], v[8:9], s[12:13]
	s_nop 0
	v_pk_fma_f32 v[8:9], v[8:9], s[4:5], v[110:111] op_sel:[0,0,1] op_sel_hi:[1,0,0]
	v_pk_add_f32 v[110:111], v[10:11], v[118:119]
	v_pk_add_f32 v[10:11], v[10:11], v[118:119] neg_lo:[0,1] neg_hi:[0,1]
	s_nop 0
	v_pk_mul_f32 v[118:119], v[10:11], s[34:35]
	s_nop 0
	v_pk_fma_f32 v[10:11], v[10:11], s[8:9], v[118:119] op_sel:[0,0,1] op_sel_hi:[1,0,0]
	v_pk_add_f32 v[118:119], v[12:13], v[120:121]
	v_pk_add_f32 v[12:13], v[12:13], v[120:121] neg_lo:[0,1] neg_hi:[0,1]
	s_nop 0
	v_pk_mul_f32 v[120:121], v[12:13], s[76:77]
	s_nop 0
	v_pk_fma_f32 v[12:13], v[12:13], s[28:29], v[120:121] op_sel:[0,0,1] op_sel_hi:[1,0,0]
	v_pk_add_f32 v[120:121], v[14:15], v[122:123]
	v_pk_add_f32 v[14:15], v[14:15], v[122:123] neg_lo:[0,1] neg_hi:[0,1]
	v_pk_add_f32 v[122:123], v[16:17], v[124:125]
	v_pk_add_f32 v[16:17], v[16:17], v[124:125] neg_lo:[0,1] neg_hi:[0,1]
	s_nop 0
	v_pk_mul_f32 v[124:125], v[16:17], s[76:77]
	s_nop 0
	v_pk_fma_f32 v[16:17], v[16:17], s[28:29], v[124:125] op_sel:[0,0,1] op_sel_hi:[1,0,0] neg_lo:[1,0,0] neg_hi:[1,0,0]
	v_pk_add_f32 v[124:125], v[18:19], v[126:127]
	v_pk_add_f32 v[18:19], v[18:19], v[126:127] neg_lo:[0,1] neg_hi:[0,1]
	s_nop 0
	v_pk_mul_f32 v[126:127], v[18:19], s[34:35]
	s_nop 0
	v_pk_fma_f32 v[18:19], v[18:19], s[8:9], v[126:127] op_sel:[0,0,1] op_sel_hi:[1,0,0] neg_lo:[1,0,0] neg_hi:[1,0,0]
	v_pk_add_f32 v[126:127], v[20:21], v[128:129]
	v_pk_add_f32 v[20:21], v[20:21], v[128:129] neg_lo:[0,1] neg_hi:[0,1]
	s_nop 0
	v_pk_mul_f32 v[128:129], v[20:21], s[12:13]
	s_nop 0
	v_pk_fma_f32 v[20:21], v[20:21], s[4:5], v[128:129] op_sel:[0,0,1] op_sel_hi:[1,0,0] neg_lo:[1,0,0] neg_hi:[1,0,0]
	s_waitcnt lgkmcnt(6)
	v_pk_add_f32 v[128:129], v[22:23], v[132:133]
	v_pk_add_f32 v[22:23], v[22:23], v[132:133] neg_lo:[0,1] neg_hi:[0,1]
	s_nop 0
	v_pk_mul_f32 v[132:133], v[22:23], s[10:11]
	s_nop 0
	v_pk_fma_f32 v[22:23], v[22:23], s[14:15], v[132:133] op_sel:[0,0,1] op_sel_hi:[1,0,0] neg_lo:[1,0,0] neg_hi:[1,0,0]
	s_waitcnt lgkmcnt(3)
	v_pk_add_f32 v[132:133], v[138:139], v[134:135]
	v_pk_add_f32 v[134:135], v[138:139], v[134:135] neg_lo:[0,1] neg_hi:[0,1]
	s_nop 0
	v_pk_mul_f32 v[138:139], v[134:135], s[20:21]
	s_nop 0
	v_pk_fma_f32 v[134:135], v[134:135], s[86:87], v[138:139] op_sel:[0,0,1] op_sel_hi:[1,0,0] neg_lo:[1,0,0] neg_hi:[1,0,0]
	s_waitcnt lgkmcnt(2)
	v_pk_add_f32 v[138:139], v[140:141], v[136:137]
	v_pk_add_f32 v[136:137], v[140:141], v[136:137] neg_lo:[0,1] neg_hi:[0,1]
	s_nop 0
	v_pk_mul_f32 v[140:141], v[136:137], s[18:19]
	s_nop 0
	v_pk_fma_f32 v[136:137], v[136:137], s[30:31], v[140:141] op_sel:[0,0,1] op_sel_hi:[1,0,0] neg_lo:[1,0,0] neg_hi:[1,0,0]
	s_waitcnt lgkmcnt(0)
	v_pk_add_f32 v[140:141], v[142:143], v[144:145]
	v_pk_add_f32 v[142:143], v[142:143], v[144:145] neg_lo:[0,1] neg_hi:[0,1]
	s_nop 0
	v_pk_mul_f32 v[144:145], v[142:143], s[16:17]
	s_nop 0
	v_pk_fma_f32 v[142:143], v[142:143], s[6:7], v[144:145] op_sel:[0,0,1] op_sel_hi:[1,0,0] neg_lo:[1,0,0] neg_hi:[1,0,0]
	v_pk_add_f32 v[144:145], v[158:159], v[120:121]
	v_pk_add_f32 v[120:121], v[158:159], v[120:121] neg_lo:[0,1] neg_hi:[0,1]
	v_pk_add_f32 v[158:159], v[130:131], v[122:123]
	v_pk_add_f32 v[122:123], v[130:131], v[122:123] neg_lo:[0,1] neg_hi:[0,1]
	s_nop 0
	v_pk_mul_f32 v[130:131], v[122:123], s[18:19]
	s_nop 0
	v_pk_fma_f32 v[122:123], v[122:123], s[30:31], v[130:131] op_sel:[0,0,1] op_sel_hi:[1,0,0]
	v_pk_add_f32 v[130:131], v[26:27], v[124:125]
	v_pk_add_f32 v[26:27], v[26:27], v[124:125] neg_lo:[0,1] neg_hi:[0,1]
	s_nop 0
	v_pk_mul_f32 v[124:125], v[26:27], s[10:11]
	s_nop 0
	v_pk_fma_f32 v[26:27], v[26:27], s[14:15], v[124:125] op_sel:[0,0,1] op_sel_hi:[1,0,0]
	v_pk_add_f32 v[124:125], v[28:29], v[126:127]
	v_pk_add_f32 v[28:29], v[28:29], v[126:127] neg_lo:[0,1] neg_hi:[0,1]
	s_nop 0
	v_pk_mul_f32 v[126:127], v[28:29], s[34:35]
	s_nop 0
	v_pk_fma_f32 v[28:29], v[28:29], s[8:9], v[126:127] op_sel:[0,0,1] op_sel_hi:[1,0,0]
	v_pk_add_f32 v[126:127], v[30:31], v[128:129]
	v_pk_add_f32 v[30:31], v[30:31], v[128:129] neg_lo:[0,1] neg_hi:[0,1]
	v_pk_add_f32 v[128:129], v[102:103], v[132:133]
	v_pk_add_f32 v[102:103], v[102:103], v[132:133] neg_lo:[0,1] neg_hi:[0,1]
	s_nop 0
	v_pk_mul_f32 v[132:133], v[102:103], s[34:35]
	s_nop 0
	v_pk_fma_f32 v[102:103], v[102:103], s[8:9], v[132:133] op_sel:[0,0,1] op_sel_hi:[1,0,0] neg_lo:[1,0,0] neg_hi:[1,0,0]
	v_pk_add_f32 v[132:133], v[110:111], v[138:139]
	v_pk_add_f32 v[110:111], v[110:111], v[138:139] neg_lo:[0,1] neg_hi:[0,1]
	s_nop 0
	v_pk_mul_f32 v[138:139], v[110:111], s[10:11]
	s_nop 0
	v_pk_fma_f32 v[110:111], v[110:111], s[14:15], v[138:139] op_sel:[0,0,1] op_sel_hi:[1,0,0] neg_lo:[1,0,0] neg_hi:[1,0,0]
	v_pk_add_f32 v[138:139], v[118:119], v[140:141]
	v_pk_add_f32 v[118:119], v[118:119], v[140:141] neg_lo:[0,1] neg_hi:[0,1]
	s_nop 0
	v_pk_mul_f32 v[140:141], v[118:119], s[18:19]
	s_nop 0
	v_pk_fma_f32 v[118:119], v[118:119], s[30:31], v[140:141] op_sel:[0,0,1] op_sel_hi:[1,0,0] neg_lo:[1,0,0] neg_hi:[1,0,0]
	v_pk_add_f32 v[140:141], v[24:25], v[14:15] op_sel:[0,1] op_sel_hi:[1,0] neg_hi:[0,1]
	v_pk_add_f32 v[14:15], v[24:25], v[14:15] op_sel:[0,1] op_sel_hi:[1,0] neg_lo:[0,1]
	v_pk_add_f32 v[24:25], v[0:1], v[16:17]
	v_pk_add_f32 v[0:1], v[0:1], v[16:17] neg_lo:[0,1] neg_hi:[0,1]
	s_nop 0
	v_pk_mul_f32 v[16:17], v[0:1], s[18:19]
	s_nop 0
	v_pk_fma_f32 v[0:1], v[0:1], s[30:31], v[16:17] op_sel:[0,0,1] op_sel_hi:[1,0,0]
	v_pk_add_f32 v[16:17], v[2:3], v[18:19]
	v_pk_add_f32 v[2:3], v[2:3], v[18:19] neg_lo:[0,1] neg_hi:[0,1]
	s_nop 0
	v_pk_mul_f32 v[18:19], v[2:3], s[10:11]
	s_nop 0
	v_pk_fma_f32 v[2:3], v[2:3], s[14:15], v[18:19] op_sel:[0,0,1] op_sel_hi:[1,0,0]
	v_pk_add_f32 v[18:19], v[4:5], v[20:21]
	v_pk_add_f32 v[4:5], v[4:5], v[20:21] neg_lo:[0,1] neg_hi:[0,1]
	s_nop 0
	v_pk_mul_f32 v[20:21], v[4:5], s[34:35]
	s_nop 0
	v_pk_fma_f32 v[4:5], v[4:5], s[8:9], v[20:21] op_sel:[0,0,1] op_sel_hi:[1,0,0]
	v_pk_add_f32 v[20:21], v[6:7], v[22:23]
	v_pk_add_f32 v[6:7], v[6:7], v[22:23] neg_lo:[0,1] neg_hi:[0,1]
	v_pk_add_f32 v[22:23], v[8:9], v[134:135]
	v_pk_add_f32 v[8:9], v[8:9], v[134:135] neg_lo:[0,1] neg_hi:[0,1]
	s_nop 0
	v_pk_mul_f32 v[134:135], v[8:9], s[34:35]
	s_nop 0
	v_pk_fma_f32 v[8:9], v[8:9], s[8:9], v[134:135] op_sel:[0,0,1] op_sel_hi:[1,0,0] neg_lo:[1,0,0] neg_hi:[1,0,0]
	v_pk_add_f32 v[134:135], v[10:11], v[136:137]
	v_pk_add_f32 v[10:11], v[10:11], v[136:137] neg_lo:[0,1] neg_hi:[0,1]
	s_nop 0
	v_pk_mul_f32 v[136:137], v[10:11], s[10:11]
	s_nop 0
	v_pk_fma_f32 v[10:11], v[10:11], s[14:15], v[136:137] op_sel:[0,0,1] op_sel_hi:[1,0,0] neg_lo:[1,0,0] neg_hi:[1,0,0]
	v_pk_add_f32 v[136:137], v[12:13], v[142:143]
	v_pk_add_f32 v[12:13], v[12:13], v[142:143] neg_lo:[0,1] neg_hi:[0,1]
	s_nop 0
	v_pk_mul_f32 v[142:143], v[12:13], s[18:19]
	s_nop 0
	v_pk_fma_f32 v[12:13], v[12:13], s[30:31], v[142:143] op_sel:[0,0,1] op_sel_hi:[1,0,0] neg_lo:[1,0,0] neg_hi:[1,0,0]
	v_pk_add_f32 v[142:143], v[144:145], v[126:127]
	v_pk_add_f32 v[126:127], v[144:145], v[126:127] neg_lo:[0,1] neg_hi:[0,1]
	v_pk_add_f32 v[144:145], v[158:159], v[128:129]
	v_pk_add_f32 v[128:129], v[158:159], v[128:129] neg_lo:[0,1] neg_hi:[0,1]
	s_nop 0
	v_pk_mul_f32 v[158:159], v[128:129], s[10:11]
	s_nop 0
	v_pk_fma_f32 v[128:129], v[128:129], s[14:15], v[158:159] op_sel:[0,0,1] op_sel_hi:[1,0,0]
	v_pk_add_f32 v[158:159], v[130:131], v[132:133]
	v_pk_add_f32 v[130:131], v[130:131], v[132:133] neg_lo:[0,1] neg_hi:[0,1]
	v_pk_add_f32 v[132:133], v[124:125], v[138:139]
	v_pk_add_f32 v[124:125], v[124:125], v[138:139] neg_lo:[0,1] neg_hi:[0,1]
	s_nop 0
	v_pk_mul_f32 v[138:139], v[124:125], s[10:11]
	s_nop 0
	v_pk_fma_f32 v[124:125], v[124:125], s[14:15], v[138:139] op_sel:[0,0,1] op_sel_hi:[1,0,0] neg_lo:[1,0,0] neg_hi:[1,0,0]
	v_pk_add_f32 v[138:139], v[120:121], v[30:31] op_sel:[0,1] op_sel_hi:[1,0] neg_hi:[0,1]
	v_pk_add_f32 v[30:31], v[120:121], v[30:31] op_sel:[0,1] op_sel_hi:[1,0] neg_lo:[0,1]
	v_pk_add_f32 v[120:121], v[122:123], v[102:103]
	v_pk_add_f32 v[102:103], v[122:123], v[102:103] neg_lo:[0,1] neg_hi:[0,1]
	v_pk_add_f32 v[160:161], v[128:129], v[124:125]
	v_pk_mul_f32 v[122:123], v[102:103], s[10:11]
	v_pk_add_f32 v[124:125], v[128:129], v[124:125] neg_lo:[0,1] neg_hi:[0,1]
	v_pk_fma_f32 v[102:103], v[102:103], s[14:15], v[122:123] op_sel:[0,0,1] op_sel_hi:[1,0,0]
	v_pk_add_f32 v[122:123], v[26:27], v[110:111]
	v_pk_add_f32 v[26:27], v[26:27], v[110:111] neg_lo:[0,1] neg_hi:[0,1]
	v_pk_add_f32 v[110:111], v[28:29], v[118:119]
	v_pk_add_f32 v[28:29], v[28:29], v[118:119] neg_lo:[0,1] neg_hi:[0,1]
	s_nop 0
	v_pk_mul_f32 v[118:119], v[28:29], s[10:11]
	v_pk_add_f32 v[166:167], v[120:121], v[110:111]
	v_pk_fma_f32 v[28:29], v[28:29], s[14:15], v[118:119] op_sel:[0,0,1] op_sel_hi:[1,0,0] neg_lo:[1,0,0] neg_hi:[1,0,0]
	v_pk_add_f32 v[118:119], v[140:141], v[20:21]
	v_pk_add_f32 v[20:21], v[140:141], v[20:21] neg_lo:[0,1] neg_hi:[0,1]
	v_pk_add_f32 v[140:141], v[24:25], v[22:23]
	v_pk_add_f32 v[22:23], v[24:25], v[22:23] neg_lo:[0,1] neg_hi:[0,1]
	v_pk_add_f32 v[110:111], v[120:121], v[110:111] neg_lo:[0,1] neg_hi:[0,1]
	v_pk_mul_f32 v[24:25], v[22:23], s[10:11]
	v_pk_add_f32 v[168:169], v[30:31], v[26:27] op_sel:[0,1] op_sel_hi:[1,0] neg_hi:[0,1]
	v_pk_fma_f32 v[22:23], v[22:23], s[14:15], v[24:25] op_sel:[0,0,1] op_sel_hi:[1,0,0]
	v_pk_add_f32 v[24:25], v[16:17], v[134:135]
	v_pk_add_f32 v[16:17], v[16:17], v[134:135] neg_lo:[0,1] neg_hi:[0,1]
	v_pk_add_f32 v[134:135], v[18:19], v[136:137]
	v_pk_add_f32 v[18:19], v[18:19], v[136:137] neg_lo:[0,1] neg_hi:[0,1]
	s_nop 0
	v_pk_mul_f32 v[136:137], v[18:19], s[10:11]
	v_pk_add_f32 v[26:27], v[30:31], v[26:27] op_sel:[0,1] op_sel_hi:[1,0] neg_lo:[0,1]
	v_pk_fma_f32 v[18:19], v[18:19], s[14:15], v[136:137] op_sel:[0,0,1] op_sel_hi:[1,0,0] neg_lo:[1,0,0] neg_hi:[1,0,0]
	v_pk_add_f32 v[136:137], v[14:15], v[6:7] op_sel:[0,1] op_sel_hi:[1,0] neg_hi:[0,1]
	v_pk_add_f32 v[6:7], v[14:15], v[6:7] op_sel:[0,1] op_sel_hi:[1,0] neg_lo:[0,1]
	v_pk_add_f32 v[14:15], v[0:1], v[8:9]
	v_pk_add_f32 v[0:1], v[0:1], v[8:9] neg_lo:[0,1] neg_hi:[0,1]
	v_pk_add_f32 v[30:31], v[102:103], v[28:29]
	v_pk_mul_f32 v[8:9], v[0:1], s[10:11]
	v_pk_add_f32 v[28:29], v[102:103], v[28:29] neg_lo:[0,1] neg_hi:[0,1]
	v_pk_fma_f32 v[0:1], v[0:1], s[14:15], v[8:9] op_sel:[0,0,1] op_sel_hi:[1,0,0]
	v_pk_add_f32 v[8:9], v[2:3], v[10:11]
	v_pk_add_f32 v[2:3], v[2:3], v[10:11] neg_lo:[0,1] neg_hi:[0,1]
	v_pk_add_f32 v[10:11], v[4:5], v[12:13]
	v_pk_add_f32 v[4:5], v[4:5], v[12:13] neg_lo:[0,1] neg_hi:[0,1]
	s_nop 0
	v_pk_mul_f32 v[12:13], v[4:5], s[10:11]
	v_pk_add_f32 v[170:171], v[118:119], v[24:25]
	v_pk_fma_f32 v[4:5], v[4:5], s[14:15], v[12:13] op_sel:[0,0,1] op_sel_hi:[1,0,0] neg_lo:[1,0,0] neg_hi:[1,0,0]
	v_pk_add_f32 v[12:13], v[142:143], v[158:159]
	v_pk_add_f32 v[142:143], v[142:143], v[158:159] neg_lo:[0,1] neg_hi:[0,1]
	v_pk_add_f32 v[158:159], v[144:145], v[132:133]
	v_pk_add_f32 v[132:133], v[144:145], v[132:133] neg_lo:[0,1] neg_hi:[0,1]
	v_pk_add_f32 v[182:183], v[118:119], v[24:25] neg_lo:[0,1] neg_hi:[0,1]
	v_pk_add_f32 v[184:185], v[140:141], v[134:135]
	v_pk_add_f32 v[24:25], v[140:141], v[134:135] neg_lo:[0,1] neg_hi:[0,1]
	v_pk_add_f32 v[140:141], v[20:21], v[16:17] op_sel:[0,1] op_sel_hi:[1,0] neg_hi:[0,1]
	v_pk_add_f32 v[186:187], v[20:21], v[16:17] op_sel:[0,1] op_sel_hi:[1,0] neg_lo:[0,1]
	v_pk_add_f32 v[16:17], v[22:23], v[18:19] neg_lo:[0,1] neg_hi:[0,1]
	v_pk_add_f32 v[192:193], v[136:137], v[8:9]
	v_pk_add_f32 v[194:195], v[136:137], v[8:9] neg_lo:[0,1] neg_hi:[0,1]
	v_pk_add_f32 v[8:9], v[14:15], v[10:11] neg_lo:[0,1] neg_hi:[0,1]
	v_pk_add_f32 v[198:199], v[6:7], v[2:3] op_sel:[0,1] op_sel_hi:[1,0] neg_hi:[0,1]
	v_pk_add_f32 v[200:201], v[6:7], v[2:3] op_sel:[0,1] op_sel_hi:[1,0] neg_lo:[0,1]
	v_pk_add_f32 v[2:3], v[0:1], v[4:5]
	v_pk_add_f32 v[0:1], v[0:1], v[4:5] neg_lo:[0,1] neg_hi:[0,1]
	v_pk_add_f32 v[144:145], v[126:127], v[130:131] op_sel:[0,1] op_sel_hi:[1,0] neg_hi:[0,1]
	v_pk_add_f32 v[130:131], v[126:127], v[130:131] op_sel:[0,1] op_sel_hi:[1,0] neg_lo:[0,1]
	v_pk_mul_f32 v[162:163], v[124:125], s[22:23]
	v_pk_add_f32 v[164:165], v[138:139], v[122:123]
	v_pk_add_f32 v[138:139], v[138:139], v[122:123] neg_lo:[0,1] neg_hi:[0,1]
	v_pk_mul_f32 v[102:103], v[28:29], s[22:23]
	v_pk_mul_f32 v[134:135], v[24:25], s[22:23]
	v_pk_add_f32 v[188:189], v[22:23], v[18:19]
	v_pk_mul_f32 v[190:191], v[16:17], s[22:23]
	v_pk_add_f32 v[136:137], v[14:15], v[10:11]
	v_pk_mul_f32 v[196:197], v[8:9], s[22:23]
	v_pk_mul_f32 v[202:203], v[0:1], s[22:23]
	v_pk_add_f32 v[28:29], v[12:13], v[158:159]
	v_pk_add_f32 v[128:129], v[12:13], v[158:159] neg_lo:[0,1] neg_hi:[0,1]
	v_pk_add_f32 v[24:25], v[142:143], v[132:133] op_sel:[0,1] op_sel_hi:[1,0] neg_hi:[0,1]
	v_pk_add_f32 v[126:127], v[142:143], v[132:133] op_sel:[0,1] op_sel_hi:[1,0] neg_lo:[0,1]
	v_pk_add_f32 v[20:21], v[144:145], v[160:161]
	v_pk_add_f32 v[124:125], v[144:145], v[160:161] neg_lo:[0,1] neg_hi:[0,1]
	v_pk_add_f32 v[16:17], v[130:131], v[162:163] op_sel:[0,1] op_sel_hi:[1,0]
	v_pk_add_f32 v[122:123], v[130:131], v[162:163] op_sel:[0,1] op_sel_hi:[1,0] neg_lo:[0,1] neg_hi:[0,1]
	v_pk_add_f32 v[12:13], v[164:165], v[166:167]
	v_pk_add_f32 v[120:121], v[164:165], v[166:167] neg_lo:[0,1] neg_hi:[0,1]
	v_pk_add_f32 v[8:9], v[138:139], v[110:111] op_sel:[0,1] op_sel_hi:[1,0] neg_hi:[0,1]
	v_pk_add_f32 v[118:119], v[138:139], v[110:111] op_sel:[0,1] op_sel_hi:[1,0] neg_lo:[0,1]
	v_pk_add_f32 v[4:5], v[168:169], v[30:31]
	v_pk_add_f32 v[110:111], v[168:169], v[30:31] neg_lo:[0,1] neg_hi:[0,1]
	v_pk_add_f32 v[0:1], v[26:27], v[102:103] op_sel:[0,1] op_sel_hi:[1,0]
	v_pk_add_f32 v[102:103], v[26:27], v[102:103] op_sel:[0,1] op_sel_hi:[1,0] neg_lo:[0,1] neg_hi:[0,1]
	v_pk_add_f32 v[30:31], v[170:171], v[184:185]
	v_pk_add_f32 v[144:145], v[170:171], v[184:185] neg_lo:[0,1] neg_hi:[0,1]
	v_pk_add_f32 v[26:27], v[182:183], v[134:135] op_sel:[0,1] op_sel_hi:[1,0]
	v_pk_add_f32 v[142:143], v[182:183], v[134:135] op_sel:[0,1] op_sel_hi:[1,0] neg_lo:[0,1] neg_hi:[0,1]
	v_pk_add_f32 v[22:23], v[140:141], v[188:189]
	v_pk_add_f32 v[140:141], v[140:141], v[188:189] neg_lo:[0,1] neg_hi:[0,1]
	v_pk_add_f32 v[18:19], v[186:187], v[190:191] op_sel:[0,1] op_sel_hi:[1,0]
	v_pk_add_f32 v[138:139], v[186:187], v[190:191] op_sel:[0,1] op_sel_hi:[1,0] neg_lo:[0,1] neg_hi:[0,1]
	v_pk_add_f32 v[14:15], v[192:193], v[136:137]
	v_pk_add_f32 v[136:137], v[192:193], v[136:137] neg_lo:[0,1] neg_hi:[0,1]
	v_pk_add_f32 v[10:11], v[194:195], v[196:197] op_sel:[0,1] op_sel_hi:[1,0]
	v_pk_add_f32 v[134:135], v[194:195], v[196:197] op_sel:[0,1] op_sel_hi:[1,0] neg_lo:[0,1] neg_hi:[0,1]
	v_pk_add_f32 v[6:7], v[198:199], v[2:3]
	v_pk_add_f32 v[132:133], v[198:199], v[2:3] neg_lo:[0,1] neg_hi:[0,1]
	v_pk_add_f32 v[2:3], v[200:201], v[202:203] op_sel:[0,1] op_sel_hi:[1,0]
	v_pk_add_f32 v[130:131], v[200:201], v[202:203] op_sel:[0,1] op_sel_hi:[1,0] neg_lo:[0,1] neg_hi:[0,1]

.LBB0_480:
	s_or_b64 exec, exec, s[0:1]
	ds_write2_b64 v152, v[110:111], v[102:103] offset1:1
	ds_write2_b64 v152, v[94:95], v[88:89] offset0:2 offset1:3
	ds_write2_b64 v152, v[112:113], v[104:105] offset0:4 offset1:5
	ds_write2_b64 v152, v[96:97], v[90:91] offset0:6 offset1:7
	ds_write2_b64 v152, v[114:115], v[106:107] offset0:8 offset1:9
	ds_write2_b64 v152, v[98:99], v[92:93] offset0:10 offset1:11
	ds_write2_b64 v152, v[116:117], v[108:109] offset0:12 offset1:13
	ds_write2_b64 v152, v[100:101], v[86:87] offset0:14 offset1:15
	s_waitcnt lgkmcnt(0)
	s_barrier
	s_and_saveexec_b64 s[0:1], s[40:41]
	s_cbranch_execz .LBB0_482
	ds_read_b64 v[0:1], v37 offset:2176
	ds_read_b64 v[2:3], v37 offset:4352
	ds_read_b64 v[4:5], v37 offset:6528
	ds_read_b64 v[6:7], v37 offset:8704
	ds_read_b64 v[8:9], v37 offset:10880
	ds_read_b64 v[10:11], v37 offset:13056
	ds_read_b64 v[12:13], v37 offset:15232
	ds_read_b64 v[14:15], v37 offset:17408
	ds_read_b64 v[16:17], v37 offset:19584
	ds_read_b64 v[18:19], v37 offset:21760
	ds_read_b64 v[20:21], v37 offset:23936
	ds_read_b64 v[22:23], v37 offset:26112
	ds_read_b64 v[24:25], v37 offset:34816
	ds_read_b64 v[26:27], v37 offset:36992
	ds_read_b64 v[28:29], v37 offset:39168
	ds_read_b64 v[30:31], v37 offset:41344
	ds_read_b64 v[82:83], v37 offset:43520
	ds_read_b64 v[84:85], v37 offset:45696
	ds_read_b64 v[118:119], v37 offset:47872
	ds_read_b64 v[120:121], v37 offset:50048
	ds_read_b64 v[122:123], v37 offset:52224
	ds_read_b64 v[124:125], v37 offset:54400
	ds_read_b64 v[126:127], v37 offset:56576
	ds_read_b64 v[128:129], v37 offset:58752
	ds_read_b64 v[130:131], v37
	ds_read_b64 v[132:133], v37 offset:60928
	ds_read_b64 v[134:135], v37 offset:63104
	ds_read_b64 v[136:137], v37 offset:65280
	s_mov_b32 s11, s14
	s_waitcnt lgkmcnt(3)
	v_pk_add_f32 v[158:159], v[130:131], v[24:25]
	v_pk_add_f32 v[24:25], v[130:131], v[24:25] neg_lo:[0,1] neg_hi:[0,1]
	v_pk_add_f32 v[130:131], v[0:1], v[26:27]
	v_pk_add_f32 v[0:1], v[0:1], v[26:27] neg_lo:[0,1] neg_hi:[0,1]
	s_mov_b32 s13, s86
	v_pk_mul_f32 v[26:27], v[0:1], s[16:17]
	s_mov_b32 s4, s21
	v_pk_fma_f32 v[0:1], v[0:1], s[6:7], v[26:27] op_sel:[0,0,1] op_sel_hi:[1,0,0]
	v_pk_add_f32 v[26:27], v[2:3], v[28:29]
	v_pk_add_f32 v[2:3], v[2:3], v[28:29] neg_lo:[0,1] neg_hi:[0,1]
	s_mov_b32 s35, s30
	v_pk_mul_f32 v[28:29], v[2:3], s[18:19]
	s_mov_b32 s8, s19
	v_pk_fma_f32 v[2:3], v[2:3], s[30:31], v[28:29] op_sel:[0,0,1] op_sel_hi:[1,0,0]
	v_pk_add_f32 v[28:29], v[4:5], v[30:31]
	v_pk_add_f32 v[4:5], v[4:5], v[30:31] neg_lo:[0,1] neg_hi:[0,1]
	s_mov_b32 s77, s6
	v_pk_mul_f32 v[30:31], v[4:5], s[20:21]
	s_mov_b32 s28, s17
	v_pk_fma_f32 v[4:5], v[4:5], s[86:87], v[30:31] op_sel:[0,0,1] op_sel_hi:[1,0,0]
	v_pk_add_f32 v[30:31], v[6:7], v[82:83]
	v_pk_add_f32 v[6:7], v[6:7], v[82:83] neg_lo:[0,1] neg_hi:[0,1]
	v_add_u32_e32 v47, 0x10780, v37
	v_pk_mul_f32 v[82:83], v[6:7], s[10:11]
	ds_read_b64 v[138:139], v37 offset:28288
	ds_read_b64 v[140:141], v37 offset:30464
	ds_read_b64 v[142:143], v37 offset:32640
	ds_read_b64 v[144:145], v47
	v_pk_fma_f32 v[6:7], v[6:7], s[14:15], v[82:83] op_sel:[0,0,1] op_sel_hi:[1,0,0]
	v_pk_add_f32 v[82:83], v[8:9], v[84:85]
	v_pk_add_f32 v[8:9], v[8:9], v[84:85] neg_lo:[0,1] neg_hi:[0,1]
	s_nop 0
	v_pk_mul_f32 v[84:85], v[8:9], s[12:13]
	s_nop 0
	v_pk_fma_f32 v[8:9], v[8:9], s[4:5], v[84:85] op_sel:[0,0,1] op_sel_hi:[1,0,0]
	v_pk_add_f32 v[84:85], v[10:11], v[118:119]
	v_pk_add_f32 v[10:11], v[10:11], v[118:119] neg_lo:[0,1] neg_hi:[0,1]
	s_nop 0
	v_pk_mul_f32 v[118:119], v[10:11], s[34:35]
	s_nop 0
	v_pk_fma_f32 v[10:11], v[10:11], s[8:9], v[118:119] op_sel:[0,0,1] op_sel_hi:[1,0,0]
	v_pk_add_f32 v[118:119], v[12:13], v[120:121]
	v_pk_add_f32 v[12:13], v[12:13], v[120:121] neg_lo:[0,1] neg_hi:[0,1]
	s_nop 0
	v_pk_mul_f32 v[120:121], v[12:13], s[76:77]
	s_nop 0
	v_pk_fma_f32 v[12:13], v[12:13], s[28:29], v[120:121] op_sel:[0,0,1] op_sel_hi:[1,0,0]
	v_pk_add_f32 v[120:121], v[14:15], v[122:123]
	v_pk_add_f32 v[14:15], v[14:15], v[122:123] neg_lo:[0,1] neg_hi:[0,1]
	v_pk_add_f32 v[122:123], v[16:17], v[124:125]
	v_pk_add_f32 v[16:17], v[16:17], v[124:125] neg_lo:[0,1] neg_hi:[0,1]
	s_nop 0
	v_pk_mul_f32 v[124:125], v[16:17], s[76:77]
	s_nop 0
	v_pk_fma_f32 v[16:17], v[16:17], s[28:29], v[124:125] op_sel:[0,0,1] op_sel_hi:[1,0,0] neg_lo:[1,0,0] neg_hi:[1,0,0]
	v_pk_add_f32 v[124:125], v[18:19], v[126:127]
	v_pk_add_f32 v[18:19], v[18:19], v[126:127] neg_lo:[0,1] neg_hi:[0,1]
	s_nop 0
	v_pk_mul_f32 v[126:127], v[18:19], s[34:35]
	s_nop 0
	v_pk_fma_f32 v[18:19], v[18:19], s[8:9], v[126:127] op_sel:[0,0,1] op_sel_hi:[1,0,0] neg_lo:[1,0,0] neg_hi:[1,0,0]
	v_pk_add_f32 v[126:127], v[20:21], v[128:129]
	v_pk_add_f32 v[20:21], v[20:21], v[128:129] neg_lo:[0,1] neg_hi:[0,1]
	s_nop 0
	v_pk_mul_f32 v[128:129], v[20:21], s[12:13]
	s_nop 0
	v_pk_fma_f32 v[20:21], v[20:21], s[4:5], v[128:129] op_sel:[0,0,1] op_sel_hi:[1,0,0] neg_lo:[1,0,0] neg_hi:[1,0,0]
	s_waitcnt lgkmcnt(6)
	v_pk_add_f32 v[128:129], v[22:23], v[132:133]
	v_pk_add_f32 v[22:23], v[22:23], v[132:133] neg_lo:[0,1] neg_hi:[0,1]
	s_nop 0
	v_pk_mul_f32 v[132:133], v[22:23], s[10:11]
	s_nop 0
	v_pk_fma_f32 v[22:23], v[22:23], s[14:15], v[132:133] op_sel:[0,0,1] op_sel_hi:[1,0,0] neg_lo:[1,0,0] neg_hi:[1,0,0]
	s_waitcnt lgkmcnt(3)
	v_pk_add_f32 v[132:133], v[138:139], v[134:135]
	v_pk_add_f32 v[134:135], v[138:139], v[134:135] neg_lo:[0,1] neg_hi:[0,1]
	s_nop 0
	v_pk_mul_f32 v[138:139], v[134:135], s[20:21]
	s_nop 0
	v_pk_fma_f32 v[134:135], v[134:135], s[86:87], v[138:139] op_sel:[0,0,1] op_sel_hi:[1,0,0] neg_lo:[1,0,0] neg_hi:[1,0,0]
	s_waitcnt lgkmcnt(2)
	v_pk_add_f32 v[138:139], v[140:141], v[136:137]
	v_pk_add_f32 v[136:137], v[140:141], v[136:137] neg_lo:[0,1] neg_hi:[0,1]
	s_nop 0
	v_pk_mul_f32 v[140:141], v[136:137], s[18:19]
	s_nop 0
	v_pk_fma_f32 v[136:137], v[136:137], s[30:31], v[140:141] op_sel:[0,0,1] op_sel_hi:[1,0,0] neg_lo:[1,0,0] neg_hi:[1,0,0]
	s_waitcnt lgkmcnt(0)
	v_pk_add_f32 v[140:141], v[142:143], v[144:145]
	v_pk_add_f32 v[142:143], v[142:143], v[144:145] neg_lo:[0,1] neg_hi:[0,1]
	s_nop 0
	v_pk_mul_f32 v[144:145], v[142:143], s[16:17]
	s_nop 0
	v_pk_fma_f32 v[142:143], v[142:143], s[6:7], v[144:145] op_sel:[0,0,1] op_sel_hi:[1,0,0] neg_lo:[1,0,0] neg_hi:[1,0,0]
	v_pk_add_f32 v[144:145], v[158:159], v[120:121]
	v_pk_add_f32 v[120:121], v[158:159], v[120:121] neg_lo:[0,1] neg_hi:[0,1]
	v_pk_add_f32 v[158:159], v[130:131], v[122:123]
	v_pk_add_f32 v[122:123], v[130:131], v[122:123] neg_lo:[0,1] neg_hi:[0,1]
	s_nop 0
	v_pk_mul_f32 v[130:131], v[122:123], s[18:19]
	s_nop 0
	v_pk_fma_f32 v[122:123], v[122:123], s[30:31], v[130:131] op_sel:[0,0,1] op_sel_hi:[1,0,0]
	v_pk_add_f32 v[130:131], v[26:27], v[124:125]
	v_pk_add_f32 v[26:27], v[26:27], v[124:125] neg_lo:[0,1] neg_hi:[0,1]
	s_nop 0
	v_pk_mul_f32 v[124:125], v[26:27], s[10:11]
	s_nop 0
	v_pk_fma_f32 v[26:27], v[26:27], s[14:15], v[124:125] op_sel:[0,0,1] op_sel_hi:[1,0,0]
	v_pk_add_f32 v[124:125], v[28:29], v[126:127]
	v_pk_add_f32 v[28:29], v[28:29], v[126:127] neg_lo:[0,1] neg_hi:[0,1]
	s_nop 0
	v_pk_mul_f32 v[126:127], v[28:29], s[34:35]
	s_nop 0
	v_pk_fma_f32 v[28:29], v[28:29], s[8:9], v[126:127] op_sel:[0,0,1] op_sel_hi:[1,0,0]
	v_pk_add_f32 v[126:127], v[30:31], v[128:129]
	v_pk_add_f32 v[30:31], v[30:31], v[128:129] neg_lo:[0,1] neg_hi:[0,1]
	v_pk_add_f32 v[128:129], v[82:83], v[132:133]
	v_pk_add_f32 v[82:83], v[82:83], v[132:133] neg_lo:[0,1] neg_hi:[0,1]
	s_nop 0
	v_pk_mul_f32 v[132:133], v[82:83], s[34:35]
	s_nop 0
	v_pk_fma_f32 v[82:83], v[82:83], s[8:9], v[132:133] op_sel:[0,0,1] op_sel_hi:[1,0,0] neg_lo:[1,0,0] neg_hi:[1,0,0]
	v_pk_add_f32 v[132:133], v[84:85], v[138:139]
	v_pk_add_f32 v[84:85], v[84:85], v[138:139] neg_lo:[0,1] neg_hi:[0,1]
	s_nop 0
	v_pk_mul_f32 v[138:139], v[84:85], s[10:11]
	s_nop 0
	v_pk_fma_f32 v[84:85], v[84:85], s[14:15], v[138:139] op_sel:[0,0,1] op_sel_hi:[1,0,0] neg_lo:[1,0,0] neg_hi:[1,0,0]
	v_pk_add_f32 v[138:139], v[118:119], v[140:141]
	v_pk_add_f32 v[118:119], v[118:119], v[140:141] neg_lo:[0,1] neg_hi:[0,1]
	s_nop 0
	v_pk_mul_f32 v[140:141], v[118:119], s[18:19]
	s_nop 0
	v_pk_fma_f32 v[118:119], v[118:119], s[30:31], v[140:141] op_sel:[0,0,1] op_sel_hi:[1,0,0] neg_lo:[1,0,0] neg_hi:[1,0,0]
	v_pk_add_f32 v[140:141], v[24:25], v[14:15] op_sel:[0,1] op_sel_hi:[1,0] neg_hi:[0,1]
	v_pk_add_f32 v[14:15], v[24:25], v[14:15] op_sel:[0,1] op_sel_hi:[1,0] neg_lo:[0,1]
	v_pk_add_f32 v[24:25], v[0:1], v[16:17]
	v_pk_add_f32 v[0:1], v[0:1], v[16:17] neg_lo:[0,1] neg_hi:[0,1]
	s_nop 0
	v_pk_mul_f32 v[16:17], v[0:1], s[18:19]
	s_nop 0
	v_pk_fma_f32 v[0:1], v[0:1], s[30:31], v[16:17] op_sel:[0,0,1] op_sel_hi:[1,0,0]
	v_pk_add_f32 v[16:17], v[2:3], v[18:19]
	v_pk_add_f32 v[2:3], v[2:3], v[18:19] neg_lo:[0,1] neg_hi:[0,1]
	s_nop 0
	v_pk_mul_f32 v[18:19], v[2:3], s[10:11]
	s_nop 0
	v_pk_fma_f32 v[2:3], v[2:3], s[14:15], v[18:19] op_sel:[0,0,1] op_sel_hi:[1,0,0]
	v_pk_add_f32 v[18:19], v[4:5], v[20:21]
	v_pk_add_f32 v[4:5], v[4:5], v[20:21] neg_lo:[0,1] neg_hi:[0,1]
	s_nop 0
	v_pk_mul_f32 v[20:21], v[4:5], s[34:35]
	s_nop 0
	v_pk_fma_f32 v[4:5], v[4:5], s[8:9], v[20:21] op_sel:[0,0,1] op_sel_hi:[1,0,0]
	v_pk_add_f32 v[20:21], v[6:7], v[22:23]
	v_pk_add_f32 v[6:7], v[6:7], v[22:23] neg_lo:[0,1] neg_hi:[0,1]
	v_pk_add_f32 v[22:23], v[8:9], v[134:135]
	v_pk_add_f32 v[8:9], v[8:9], v[134:135] neg_lo:[0,1] neg_hi:[0,1]
	s_nop 0
	v_pk_mul_f32 v[134:135], v[8:9], s[34:35]
	s_nop 0
	v_pk_fma_f32 v[8:9], v[8:9], s[8:9], v[134:135] op_sel:[0,0,1] op_sel_hi:[1,0,0] neg_lo:[1,0,0] neg_hi:[1,0,0]
	v_pk_add_f32 v[134:135], v[10:11], v[136:137]
	v_pk_add_f32 v[10:11], v[10:11], v[136:137] neg_lo:[0,1] neg_hi:[0,1]
	s_nop 0
	v_pk_mul_f32 v[136:137], v[10:11], s[10:11]
	s_nop 0
	v_pk_fma_f32 v[10:11], v[10:11], s[14:15], v[136:137] op_sel:[0,0,1] op_sel_hi:[1,0,0] neg_lo:[1,0,0] neg_hi:[1,0,0]
	v_pk_add_f32 v[136:137], v[12:13], v[142:143]
	v_pk_add_f32 v[12:13], v[12:13], v[142:143] neg_lo:[0,1] neg_hi:[0,1]
	s_nop 0
	v_pk_mul_f32 v[142:143], v[12:13], s[18:19]
	s_nop 0
	v_pk_fma_f32 v[12:13], v[12:13], s[30:31], v[142:143] op_sel:[0,0,1] op_sel_hi:[1,0,0] neg_lo:[1,0,0] neg_hi:[1,0,0]
	v_pk_add_f32 v[142:143], v[144:145], v[126:127]
	v_pk_add_f32 v[126:127], v[144:145], v[126:127] neg_lo:[0,1] neg_hi:[0,1]
	v_pk_add_f32 v[144:145], v[158:159], v[128:129]
	v_pk_add_f32 v[128:129], v[158:159], v[128:129] neg_lo:[0,1] neg_hi:[0,1]
	s_nop 0
	v_pk_mul_f32 v[158:159], v[128:129], s[10:11]
	s_nop 0
	v_pk_fma_f32 v[128:129], v[128:129], s[14:15], v[158:159] op_sel:[0,0,1] op_sel_hi:[1,0,0]
	v_pk_add_f32 v[158:159], v[130:131], v[132:133]
	v_pk_add_f32 v[130:131], v[130:131], v[132:133] neg_lo:[0,1] neg_hi:[0,1]
	v_pk_add_f32 v[132:133], v[124:125], v[138:139]
	v_pk_add_f32 v[124:125], v[124:125], v[138:139] neg_lo:[0,1] neg_hi:[0,1]
	s_nop 0
	v_pk_mul_f32 v[138:139], v[124:125], s[10:11]
	s_nop 0
	v_pk_fma_f32 v[124:125], v[124:125], s[14:15], v[138:139] op_sel:[0,0,1] op_sel_hi:[1,0,0] neg_lo:[1,0,0] neg_hi:[1,0,0]
	v_pk_add_f32 v[138:139], v[120:121], v[30:31] op_sel:[0,1] op_sel_hi:[1,0] neg_hi:[0,1]
	v_pk_add_f32 v[30:31], v[120:121], v[30:31] op_sel:[0,1] op_sel_hi:[1,0] neg_lo:[0,1]
	v_pk_add_f32 v[120:121], v[122:123], v[82:83]
	v_pk_add_f32 v[82:83], v[122:123], v[82:83] neg_lo:[0,1] neg_hi:[0,1]
	v_pk_add_f32 v[160:161], v[128:129], v[124:125]
	v_pk_mul_f32 v[122:123], v[82:83], s[10:11]
	v_pk_add_f32 v[124:125], v[128:129], v[124:125] neg_lo:[0,1] neg_hi:[0,1]
	v_pk_fma_f32 v[82:83], v[82:83], s[14:15], v[122:123] op_sel:[0,0,1] op_sel_hi:[1,0,0]
	v_pk_add_f32 v[122:123], v[26:27], v[84:85]
	v_pk_add_f32 v[26:27], v[26:27], v[84:85] neg_lo:[0,1] neg_hi:[0,1]
	v_pk_add_f32 v[84:85], v[28:29], v[118:119]
	v_pk_add_f32 v[28:29], v[28:29], v[118:119] neg_lo:[0,1] neg_hi:[0,1]
	s_nop 0
	v_pk_mul_f32 v[118:119], v[28:29], s[10:11]
	v_pk_add_f32 v[166:167], v[120:121], v[84:85]
	v_pk_fma_f32 v[28:29], v[28:29], s[14:15], v[118:119] op_sel:[0,0,1] op_sel_hi:[1,0,0] neg_lo:[1,0,0] neg_hi:[1,0,0]
	v_pk_add_f32 v[118:119], v[140:141], v[20:21]
	v_pk_add_f32 v[20:21], v[140:141], v[20:21] neg_lo:[0,1] neg_hi:[0,1]
	v_pk_add_f32 v[140:141], v[24:25], v[22:23]
	v_pk_add_f32 v[22:23], v[24:25], v[22:23] neg_lo:[0,1] neg_hi:[0,1]
	v_pk_add_f32 v[84:85], v[120:121], v[84:85] neg_lo:[0,1] neg_hi:[0,1]
	v_pk_mul_f32 v[24:25], v[22:23], s[10:11]
	v_pk_add_f32 v[168:169], v[30:31], v[26:27] op_sel:[0,1] op_sel_hi:[1,0] neg_hi:[0,1]
	v_pk_fma_f32 v[22:23], v[22:23], s[14:15], v[24:25] op_sel:[0,0,1] op_sel_hi:[1,0,0]
	v_pk_add_f32 v[24:25], v[16:17], v[134:135]
	v_pk_add_f32 v[16:17], v[16:17], v[134:135] neg_lo:[0,1] neg_hi:[0,1]
	v_pk_add_f32 v[134:135], v[18:19], v[136:137]
	v_pk_add_f32 v[18:19], v[18:19], v[136:137] neg_lo:[0,1] neg_hi:[0,1]
	s_nop 0
	v_pk_mul_f32 v[136:137], v[18:19], s[10:11]
	v_pk_add_f32 v[26:27], v[30:31], v[26:27] op_sel:[0,1] op_sel_hi:[1,0] neg_lo:[0,1]
	v_pk_fma_f32 v[18:19], v[18:19], s[14:15], v[136:137] op_sel:[0,0,1] op_sel_hi:[1,0,0] neg_lo:[1,0,0] neg_hi:[1,0,0]
	v_pk_add_f32 v[136:137], v[14:15], v[6:7] op_sel:[0,1] op_sel_hi:[1,0] neg_hi:[0,1]
	v_pk_add_f32 v[6:7], v[14:15], v[6:7] op_sel:[0,1] op_sel_hi:[1,0] neg_lo:[0,1]
	v_pk_add_f32 v[14:15], v[0:1], v[8:9]
	v_pk_add_f32 v[0:1], v[0:1], v[8:9] neg_lo:[0,1] neg_hi:[0,1]
	v_pk_add_f32 v[30:31], v[82:83], v[28:29]
	v_pk_mul_f32 v[8:9], v[0:1], s[10:11]
	v_pk_add_f32 v[28:29], v[82:83], v[28:29] neg_lo:[0,1] neg_hi:[0,1]
	v_pk_fma_f32 v[0:1], v[0:1], s[14:15], v[8:9] op_sel:[0,0,1] op_sel_hi:[1,0,0]
	v_pk_add_f32 v[8:9], v[2:3], v[10:11]
	v_pk_add_f32 v[2:3], v[2:3], v[10:11] neg_lo:[0,1] neg_hi:[0,1]
	v_pk_add_f32 v[10:11], v[4:5], v[12:13]
	v_pk_add_f32 v[4:5], v[4:5], v[12:13] neg_lo:[0,1] neg_hi:[0,1]
	s_nop 0
	v_pk_mul_f32 v[12:13], v[4:5], s[10:11]
	v_pk_add_f32 v[170:171], v[118:119], v[24:25]
	v_pk_fma_f32 v[4:5], v[4:5], s[14:15], v[12:13] op_sel:[0,0,1] op_sel_hi:[1,0,0] neg_lo:[1,0,0] neg_hi:[1,0,0]
	v_pk_add_f32 v[12:13], v[142:143], v[158:159]
	v_pk_add_f32 v[142:143], v[142:143], v[158:159] neg_lo:[0,1] neg_hi:[0,1]
	v_pk_add_f32 v[158:159], v[144:145], v[132:133]
	v_pk_add_f32 v[132:133], v[144:145], v[132:133] neg_lo:[0,1] neg_hi:[0,1]
	v_pk_add_f32 v[182:183], v[118:119], v[24:25] neg_lo:[0,1] neg_hi:[0,1]
	v_pk_add_f32 v[184:185], v[140:141], v[134:135]
	v_pk_add_f32 v[24:25], v[140:141], v[134:135] neg_lo:[0,1] neg_hi:[0,1]
	v_pk_add_f32 v[140:141], v[20:21], v[16:17] op_sel:[0,1] op_sel_hi:[1,0] neg_hi:[0,1]
	v_pk_add_f32 v[186:187], v[20:21], v[16:17] op_sel:[0,1] op_sel_hi:[1,0] neg_lo:[0,1]
	v_pk_add_f32 v[16:17], v[22:23], v[18:19] neg_lo:[0,1] neg_hi:[0,1]
	v_pk_add_f32 v[192:193], v[136:137], v[8:9]
	v_pk_add_f32 v[194:195], v[136:137], v[8:9] neg_lo:[0,1] neg_hi:[0,1]
	v_pk_add_f32 v[8:9], v[14:15], v[10:11] neg_lo:[0,1] neg_hi:[0,1]
	v_pk_add_f32 v[198:199], v[6:7], v[2:3] op_sel:[0,1] op_sel_hi:[1,0] neg_hi:[0,1]
	v_pk_add_f32 v[200:201], v[6:7], v[2:3] op_sel:[0,1] op_sel_hi:[1,0] neg_lo:[0,1]
	v_pk_add_f32 v[2:3], v[0:1], v[4:5]
	v_pk_add_f32 v[0:1], v[0:1], v[4:5] neg_lo:[0,1] neg_hi:[0,1]
	v_pk_add_f32 v[144:145], v[126:127], v[130:131] op_sel:[0,1] op_sel_hi:[1,0] neg_hi:[0,1]
	v_pk_add_f32 v[130:131], v[126:127], v[130:131] op_sel:[0,1] op_sel_hi:[1,0] neg_lo:[0,1]
	v_pk_mul_f32 v[162:163], v[124:125], s[22:23]
	v_pk_add_f32 v[164:165], v[138:139], v[122:123]
	v_pk_add_f32 v[138:139], v[138:139], v[122:123] neg_lo:[0,1] neg_hi:[0,1]
	v_pk_mul_f32 v[82:83], v[28:29], s[22:23]
	v_pk_mul_f32 v[134:135], v[24:25], s[22:23]
	v_pk_add_f32 v[188:189], v[22:23], v[18:19]
	v_pk_mul_f32 v[190:191], v[16:17], s[22:23]
	v_pk_add_f32 v[136:137], v[14:15], v[10:11]
	v_pk_mul_f32 v[196:197], v[8:9], s[22:23]
	v_pk_mul_f32 v[202:203], v[0:1], s[22:23]
	v_pk_add_f32 v[28:29], v[12:13], v[158:159]
	v_pk_add_f32 v[128:129], v[12:13], v[158:159] neg_lo:[0,1] neg_hi:[0,1]
	v_pk_add_f32 v[24:25], v[142:143], v[132:133] op_sel:[0,1] op_sel_hi:[1,0] neg_hi:[0,1]
	v_pk_add_f32 v[126:127], v[142:143], v[132:133] op_sel:[0,1] op_sel_hi:[1,0] neg_lo:[0,1]
	v_pk_add_f32 v[20:21], v[144:145], v[160:161]
	v_pk_add_f32 v[124:125], v[144:145], v[160:161] neg_lo:[0,1] neg_hi:[0,1]
	v_pk_add_f32 v[16:17], v[130:131], v[162:163] op_sel:[0,1] op_sel_hi:[1,0]
	v_pk_add_f32 v[122:123], v[130:131], v[162:163] op_sel:[0,1] op_sel_hi:[1,0] neg_lo:[0,1] neg_hi:[0,1]
	v_pk_add_f32 v[12:13], v[164:165], v[166:167]
	v_pk_add_f32 v[120:121], v[164:165], v[166:167] neg_lo:[0,1] neg_hi:[0,1]
	v_pk_add_f32 v[8:9], v[138:139], v[84:85] op_sel:[0,1] op_sel_hi:[1,0] neg_hi:[0,1]
	v_pk_add_f32 v[118:119], v[138:139], v[84:85] op_sel:[0,1] op_sel_hi:[1,0] neg_lo:[0,1]
	v_pk_add_f32 v[4:5], v[168:169], v[30:31]
	v_pk_add_f32 v[84:85], v[168:169], v[30:31] neg_lo:[0,1] neg_hi:[0,1]
	v_pk_add_f32 v[0:1], v[26:27], v[82:83] op_sel:[0,1] op_sel_hi:[1,0]
	v_pk_add_f32 v[82:83], v[26:27], v[82:83] op_sel:[0,1] op_sel_hi:[1,0] neg_lo:[0,1] neg_hi:[0,1]
	v_pk_add_f32 v[30:31], v[170:171], v[184:185]
	v_pk_add_f32 v[144:145], v[170:171], v[184:185] neg_lo:[0,1] neg_hi:[0,1]
	v_pk_add_f32 v[26:27], v[182:183], v[134:135] op_sel:[0,1] op_sel_hi:[1,0]
	v_pk_add_f32 v[142:143], v[182:183], v[134:135] op_sel:[0,1] op_sel_hi:[1,0] neg_lo:[0,1] neg_hi:[0,1]
	v_pk_add_f32 v[22:23], v[140:141], v[188:189]
	v_pk_add_f32 v[140:141], v[140:141], v[188:189] neg_lo:[0,1] neg_hi:[0,1]
	v_pk_add_f32 v[18:19], v[186:187], v[190:191] op_sel:[0,1] op_sel_hi:[1,0]
	v_pk_add_f32 v[138:139], v[186:187], v[190:191] op_sel:[0,1] op_sel_hi:[1,0] neg_lo:[0,1] neg_hi:[0,1]
	v_pk_add_f32 v[14:15], v[192:193], v[136:137]
	v_pk_add_f32 v[136:137], v[192:193], v[136:137] neg_lo:[0,1] neg_hi:[0,1]
	v_pk_add_f32 v[10:11], v[194:195], v[196:197] op_sel:[0,1] op_sel_hi:[1,0]
	v_pk_add_f32 v[134:135], v[194:195], v[196:197] op_sel:[0,1] op_sel_hi:[1,0] neg_lo:[0,1] neg_hi:[0,1]
	v_pk_add_f32 v[6:7], v[198:199], v[2:3]
	v_pk_add_f32 v[132:133], v[198:199], v[2:3] neg_lo:[0,1] neg_hi:[0,1]
	v_pk_add_f32 v[2:3], v[200:201], v[202:203] op_sel:[0,1] op_sel_hi:[1,0]
	v_pk_add_f32 v[130:131], v[200:201], v[202:203] op_sel:[0,1] op_sel_hi:[1,0] neg_lo:[0,1] neg_hi:[0,1]

.LBB0_485:
	v_add_u32_e32 v160, 0x11000, v155
	v_lshlrev_b32_e32 v161, 3, v154
	v_add_u32_e32 v161, 0x2200, v161
	v_add_u32_e32 v162, 0x11100, v156
	v_cmp_ne_u32_e32 vcc, 0, v32
	v_cndmask_b32_e32 v163, 0, v154, vcc
	v_lshlrev_b32_e32 v163, 3, v163
	v_add_u32_e32 v163, 0x11000, v163
	s_mov_b32 s100, 0x38800000
	s_mov_b32 s101, 0xb8800000
	ds_read_b64 v[214:215], v160 offset:0
	ds_read_b64 v[216:217], v163
	ds_read_b64 v[218:219], v160 offset:4352
	ds_read_b64 v[220:221], v162 offset:60928
	ds_read_b64 v[222:223], v160 offset:8704
	ds_read_b64 v[224:225], v161 offset:52224
	ds_read_b64 v[226:227], v160 offset:13056
	ds_read_b64 v[228:229], v162 offset:52224
	s_waitcnt lgkmcnt(6)
	v_sub_f32_e32 v216, v216, v214
	v_add_f32_e32 v214, v215, v217
	v_pk_mul_f32 v[216:217], v[6:7], v[216:217] op_sel:[1,0] op_sel_hi:[0,0]
	v_pk_fma_f32 v[158:159], v[6:7], v[214:215], v[216:217] neg_lo:[0,0,1] neg_hi:[0,0,1]
	v_pk_fma_f32 v[214:215], v[6:7], v[214:215], v[216:217] op_sel_hi:[1,0,1]
	s_nop 0
	v_mov_b32_e32 v159, v215
	v_pk_mul_f32 v[6:7], v[158:159], s[100:101]
	ds_write_b64 v155, v[6:7] offset:0
	s_waitcnt lgkmcnt(5)
	v_sub_f32_e32 v220, v220, v218
	v_add_f32_e32 v218, v219, v221
	v_pk_mul_f32 v[220:221], v[18:19], v[220:221] op_sel:[1,0] op_sel_hi:[0,0]
	v_pk_fma_f32 v[158:159], v[18:19], v[218:219], v[220:221] neg_lo:[0,0,1] neg_hi:[0,0,1]
	v_pk_fma_f32 v[218:219], v[18:19], v[218:219], v[220:221] op_sel_hi:[1,0,1]
	s_nop 0
	v_mov_b32_e32 v159, v219
	v_pk_mul_f32 v[18:19], v[158:159], s[100:101]
	ds_write_b64 v155, v[18:19] offset:4352
	ds_read_b64 v[230:231], v160 offset:17408
	ds_read_b64 v[232:233], v161 offset:43520
	ds_read_b64 v[234:235], v160 offset:21760
	ds_read_b64 v[236:237], v162 offset:43520
	s_waitcnt lgkmcnt(8)
	v_sub_f32_e32 v224, v224, v222
	v_add_f32_e32 v222, v223, v225
	v_pk_mul_f32 v[224:225], v[28:29], v[224:225] op_sel:[1,0] op_sel_hi:[0,0]
	v_pk_fma_f32 v[158:159], v[28:29], v[222:223], v[224:225] neg_lo:[0,0,1] neg_hi:[0,0,1]
	v_pk_fma_f32 v[222:223], v[28:29], v[222:223], v[224:225] op_sel_hi:[1,0,1]
	s_nop 0
	v_mov_b32_e32 v159, v223
	v_pk_mul_f32 v[28:29], v[158:159], s[100:101]
	ds_write_b64 v155, v[28:29] offset:8704
	s_waitcnt lgkmcnt(7)
	v_sub_f32_e32 v228, v228, v226
	v_add_f32_e32 v226, v227, v229
	v_pk_mul_f32 v[228:229], v[10:11], v[228:229] op_sel:[1,0] op_sel_hi:[0,0]
	v_pk_fma_f32 v[158:159], v[10:11], v[226:227], v[228:229] neg_lo:[0,0,1] neg_hi:[0,0,1]
	v_pk_fma_f32 v[226:227], v[10:11], v[226:227], v[228:229] op_sel_hi:[1,0,1]
	s_nop 0
	v_mov_b32_e32 v159, v227
	v_pk_mul_f32 v[10:11], v[158:159], s[100:101]
	ds_write_b64 v155, v[10:11] offset:13056
	ds_read_b64 v[214:215], v160 offset:26112
	ds_read_b64 v[216:217], v161 offset:34816
	ds_read_b64 v[218:219], v160 offset:30464
	ds_read_b64 v[220:221], v162 offset:34816
	s_waitcnt lgkmcnt(8)
	v_sub_f32_e32 v232, v232, v230
	v_add_f32_e32 v230, v231, v233
	v_pk_mul_f32 v[232:233], v[26:27], v[232:233] op_sel:[1,0] op_sel_hi:[0,0]
	v_pk_fma_f32 v[158:159], v[26:27], v[230:231], v[232:233] neg_lo:[0,0,1] neg_hi:[0,0,1]
	v_pk_fma_f32 v[230:231], v[26:27], v[230:231], v[232:233] op_sel_hi:[1,0,1]
	s_nop 0
	v_mov_b32_e32 v159, v231
	v_pk_mul_f32 v[26:27], v[158:159], s[100:101]
	ds_write_b64 v155, v[26:27] offset:17408
	s_waitcnt lgkmcnt(7)
	v_sub_f32_e32 v236, v236, v234
	v_add_f32_e32 v234, v235, v237
	v_pk_mul_f32 v[236:237], v[30:31], v[236:237] op_sel:[1,0] op_sel_hi:[0,0]
	v_pk_fma_f32 v[158:159], v[30:31], v[234:235], v[236:237] neg_lo:[0,0,1] neg_hi:[0,0,1]
	v_pk_fma_f32 v[234:235], v[30:31], v[234:235], v[236:237] op_sel_hi:[1,0,1]
	s_nop 0
	v_mov_b32_e32 v159, v235
	v_pk_mul_f32 v[30:31], v[158:159], s[100:101]
	ds_write_b64 v155, v[30:31] offset:21760
	ds_read_b64 v[222:223], v160 offset:34816
	ds_read_b64 v[224:225], v161 offset:26112
	ds_read_b64 v[226:227], v160 offset:39168
	ds_read_b64 v[228:229], v162 offset:26112
	s_waitcnt lgkmcnt(8)
	v_sub_f32_e32 v216, v216, v214
	v_add_f32_e32 v214, v215, v217
	v_pk_mul_f32 v[216:217], v[82:83], v[216:217] op_sel:[1,0] op_sel_hi:[0,0]
	v_pk_fma_f32 v[158:159], v[82:83], v[214:215], v[216:217] neg_lo:[0,0,1] neg_hi:[0,0,1]
	v_pk_fma_f32 v[214:215], v[82:83], v[214:215], v[216:217] op_sel_hi:[1,0,1]
	s_nop 0
	v_mov_b32_e32 v159, v215
	v_pk_mul_f32 v[82:83], v[158:159], s[100:101]
	ds_write_b64 v155, v[82:83] offset:26112
	s_waitcnt lgkmcnt(7)
	v_sub_f32_e32 v220, v220, v218
	v_add_f32_e32 v218, v219, v221
	v_pk_mul_f32 v[220:221], v[12:13], v[220:221] op_sel:[1,0] op_sel_hi:[0,0]
	v_pk_fma_f32 v[158:159], v[12:13], v[218:219], v[220:221] neg_lo:[0,0,1] neg_hi:[0,0,1]
	v_pk_fma_f32 v[218:219], v[12:13], v[218:219], v[220:221] op_sel_hi:[1,0,1]
	s_nop 0
	v_mov_b32_e32 v159, v219
	v_pk_mul_f32 v[12:13], v[158:159], s[100:101]
	ds_write_b64 v155, v[12:13] offset:30464
	ds_read_b64 v[230:231], v160 offset:43520
	ds_read_b64 v[232:233], v161 offset:17408
	ds_read_b64 v[234:235], v160 offset:47872
	ds_read_b64 v[236:237], v162 offset:17408
	s_waitcnt lgkmcnt(8)
	v_sub_f32_e32 v224, v224, v222
	v_add_f32_e32 v222, v223, v225
	v_pk_mul_f32 v[224:225], v[14:15], v[224:225] op_sel:[1,0] op_sel_hi:[0,0]
	v_pk_fma_f32 v[158:159], v[14:15], v[222:223], v[224:225] neg_lo:[0,0,1] neg_hi:[0,0,1]
	v_pk_fma_f32 v[222:223], v[14:15], v[222:223], v[224:225] op_sel_hi:[1,0,1]
	s_nop 0
	v_mov_b32_e32 v159, v223
	v_pk_mul_f32 v[14:15], v[158:159], s[100:101]
	ds_write_b64 v155, v[14:15] offset:34816
	s_waitcnt lgkmcnt(7)
	v_sub_f32_e32 v228, v228, v226
	v_add_f32_e32 v226, v227, v229
	v_pk_mul_f32 v[228:229], v[20:21], v[228:229] op_sel:[1,0] op_sel_hi:[0,0]
	v_pk_fma_f32 v[158:159], v[20:21], v[226:227], v[228:229] neg_lo:[0,0,1] neg_hi:[0,0,1]
	v_pk_fma_f32 v[226:227], v[20:21], v[226:227], v[228:229] op_sel_hi:[1,0,1]
	s_nop 0
	v_mov_b32_e32 v159, v227
	v_pk_mul_f32 v[20:21], v[158:159], s[100:101]
	ds_write_b64 v155, v[20:21] offset:39168
	ds_read_b64 v[214:215], v160 offset:52224
	ds_read_b64 v[216:217], v161 offset:8704
	ds_read_b64 v[218:219], v160 offset:56576
	ds_read_b64 v[220:221], v162 offset:8704
	s_waitcnt lgkmcnt(8)
	v_sub_f32_e32 v232, v232, v230
	v_add_f32_e32 v230, v231, v233
	v_pk_mul_f32 v[232:233], v[22:23], v[232:233] op_sel:[1,0] op_sel_hi:[0,0]
	v_pk_fma_f32 v[158:159], v[22:23], v[230:231], v[232:233] neg_lo:[0,0,1] neg_hi:[0,0,1]
	v_pk_fma_f32 v[230:231], v[22:23], v[230:231], v[232:233] op_sel_hi:[1,0,1]
	s_nop 0
	v_mov_b32_e32 v159, v231
	v_pk_mul_f32 v[22:23], v[158:159], s[100:101]
	ds_write_b64 v155, v[22:23] offset:43520
	s_waitcnt lgkmcnt(7)
	v_sub_f32_e32 v236, v236, v234
	v_add_f32_e32 v234, v235, v237
	v_pk_mul_f32 v[236:237], v[4:5], v[236:237] op_sel:[1,0] op_sel_hi:[0,0]
	v_pk_fma_f32 v[158:159], v[4:5], v[234:235], v[236:237] neg_lo:[0,0,1] neg_hi:[0,0,1]
	v_pk_fma_f32 v[234:235], v[4:5], v[234:235], v[236:237] op_sel_hi:[1,0,1]
	s_nop 0
	v_mov_b32_e32 v159, v235
	v_pk_mul_f32 v[4:5], v[158:159], s[100:101]
	ds_write_b64 v155, v[4:5] offset:47872
	ds_read_b64 v[222:223], v160 offset:60928
	ds_read_b64 v[224:225], v161 offset:0
	ds_read_b64 v[226:227], v160 offset:65280
	ds_read_b64 v[228:229], v162 offset:0
	s_waitcnt lgkmcnt(8)
	v_sub_f32_e32 v216, v216, v214
	v_add_f32_e32 v214, v215, v217
	v_pk_mul_f32 v[216:217], v[24:25], v[216:217] op_sel:[1,0] op_sel_hi:[0,0]
	v_pk_fma_f32 v[158:159], v[24:25], v[214:215], v[216:217] neg_lo:[0,0,1] neg_hi:[0,0,1]
	v_pk_fma_f32 v[214:215], v[24:25], v[214:215], v[216:217] op_sel_hi:[1,0,1]
	s_nop 0
	v_mov_b32_e32 v159, v215
	v_pk_mul_f32 v[24:25], v[158:159], s[100:101]
	ds_write_b64 v155, v[24:25] offset:52224
	s_waitcnt lgkmcnt(7)
	v_sub_f32_e32 v220, v220, v218
	v_add_f32_e32 v218, v219, v221
	v_pk_mul_f32 v[220:221], v[8:9], v[220:221] op_sel:[1,0] op_sel_hi:[0,0]
	v_pk_fma_f32 v[158:159], v[8:9], v[218:219], v[220:221] neg_lo:[0,0,1] neg_hi:[0,0,1]
	v_pk_fma_f32 v[218:219], v[8:9], v[218:219], v[220:221] op_sel_hi:[1,0,1]
	s_nop 0
	v_mov_b32_e32 v159, v219
	v_pk_mul_f32 v[8:9], v[158:159], s[100:101]
	ds_write_b64 v155, v[8:9] offset:56576
	s_waitcnt lgkmcnt(4)
	v_sub_f32_e32 v224, v224, v222
	v_add_f32_e32 v222, v223, v225
	v_pk_mul_f32 v[224:225], v[16:17], v[224:225] op_sel:[1,0] op_sel_hi:[0,0]
	v_pk_fma_f32 v[158:159], v[16:17], v[222:223], v[224:225] neg_lo:[0,0,1] neg_hi:[0,0,1]
	v_pk_fma_f32 v[222:223], v[16:17], v[222:223], v[224:225] op_sel_hi:[1,0,1]
	s_nop 0
	v_mov_b32_e32 v159, v223
	v_pk_mul_f32 v[16:17], v[158:159], s[100:101]
	ds_write_b64 v155, v[16:17] offset:60928
	s_waitcnt lgkmcnt(3)
	v_sub_f32_e32 v228, v228, v226
	v_add_f32_e32 v226, v227, v229
	v_pk_mul_f32 v[228:229], v[0:1], v[228:229] op_sel:[1,0] op_sel_hi:[0,0]
	v_pk_fma_f32 v[158:159], v[0:1], v[226:227], v[228:229] neg_lo:[0,0,1] neg_hi:[0,0,1]
	v_pk_fma_f32 v[226:227], v[0:1], v[226:227], v[228:229] op_sel_hi:[1,0,1]
	s_nop 0
	v_mov_b32_e32 v159, v227
	v_pk_mul_f32 v[0:1], v[158:159], s[100:101]
	ds_write_b64 v155, v[0:1] offset:65280
	s_mov_b32 s0, 16
	s_cmp_lg_u32 s0, 16
	s_waitcnt lgkmcnt(0)
	s_barrier
	s_and_saveexec_b64 s[0:1], s[40:41]
	s_cbranch_execz .LBB0_488
	ds_read_b64 v[0:1], v37 offset:2176
	ds_read_b64 v[2:3], v37 offset:4352
	ds_read_b64 v[4:5], v37 offset:6528
	ds_read_b64 v[6:7], v37 offset:8704
	ds_read_b64 v[8:9], v37 offset:10880
	ds_read_b64 v[10:11], v37 offset:13056
	ds_read_b64 v[12:13], v37 offset:15232
	ds_read_b64 v[14:15], v37 offset:17408
	ds_read_b64 v[16:17], v37 offset:19584
	ds_read_b64 v[18:19], v37 offset:21760
	ds_read_b64 v[20:21], v37 offset:23936
	ds_read_b64 v[22:23], v37 offset:26112
	ds_read_b64 v[24:25], v37 offset:34816
	ds_read_b64 v[26:27], v37 offset:36992
	ds_read_b64 v[28:29], v37 offset:39168
	ds_read_b64 v[30:31], v37 offset:41344
	ds_read_b64 v[82:83], v37 offset:43520
	ds_read_b64 v[84:85], v37 offset:45696
	ds_read_b64 v[118:119], v37 offset:47872
	ds_read_b64 v[120:121], v37 offset:50048
	ds_read_b64 v[122:123], v37 offset:52224
	ds_read_b64 v[124:125], v37 offset:54400
	ds_read_b64 v[126:127], v37 offset:56576
	ds_read_b64 v[128:129], v37 offset:58752
	ds_read_b64 v[130:131], v37
	ds_read_b64 v[132:133], v37 offset:60928
	ds_read_b64 v[134:135], v37 offset:63104
	ds_read_b64 v[136:137], v37 offset:65280
	s_mov_b32 s11, s14
	s_waitcnt lgkmcnt(3)
	v_pk_add_f32 v[158:159], v[130:131], v[24:25]
	v_pk_add_f32 v[24:25], v[130:131], v[24:25] neg_lo:[0,1] neg_hi:[0,1]
	v_pk_add_f32 v[130:131], v[0:1], v[26:27]
	v_pk_add_f32 v[0:1], v[0:1], v[26:27] neg_lo:[0,1] neg_hi:[0,1]
	s_mov_b32 s13, s86
	v_pk_mul_f32 v[26:27], v[0:1], s[16:17]
	s_mov_b32 s4, s21
	v_pk_fma_f32 v[0:1], v[0:1], s[6:7], v[26:27] op_sel:[0,0,1] op_sel_hi:[1,0,0]
	v_pk_add_f32 v[26:27], v[2:3], v[28:29]
	v_pk_add_f32 v[2:3], v[2:3], v[28:29] neg_lo:[0,1] neg_hi:[0,1]
	s_mov_b32 s35, s30
	v_pk_mul_f32 v[28:29], v[2:3], s[18:19]
	s_mov_b32 s8, s19
	v_pk_fma_f32 v[2:3], v[2:3], s[30:31], v[28:29] op_sel:[0,0,1] op_sel_hi:[1,0,0]
	v_pk_add_f32 v[28:29], v[4:5], v[30:31]
	v_pk_add_f32 v[4:5], v[4:5], v[30:31] neg_lo:[0,1] neg_hi:[0,1]
	s_mov_b32 s77, s6
	v_pk_mul_f32 v[30:31], v[4:5], s[20:21]
	s_mov_b32 s28, s17
	v_pk_fma_f32 v[4:5], v[4:5], s[86:87], v[30:31] op_sel:[0,0,1] op_sel_hi:[1,0,0]
	v_pk_add_f32 v[30:31], v[6:7], v[82:83]
	v_pk_add_f32 v[6:7], v[6:7], v[82:83] neg_lo:[0,1] neg_hi:[0,1]
	v_add_u32_e32 v47, 0x10780, v37
	v_pk_mul_f32 v[82:83], v[6:7], s[10:11]
	ds_read_b64 v[138:139], v37 offset:28288
	ds_read_b64 v[140:141], v37 offset:30464
	ds_read_b64 v[142:143], v37 offset:32640
	ds_read_b64 v[144:145], v47
	v_pk_fma_f32 v[6:7], v[6:7], s[14:15], v[82:83] op_sel:[0,0,1] op_sel_hi:[1,0,0]
	v_pk_add_f32 v[82:83], v[8:9], v[84:85]
	v_pk_add_f32 v[8:9], v[8:9], v[84:85] neg_lo:[0,1] neg_hi:[0,1]
	s_nop 0
	v_pk_mul_f32 v[84:85], v[8:9], s[12:13]
	s_nop 0
	v_pk_fma_f32 v[8:9], v[8:9], s[4:5], v[84:85] op_sel:[0,0,1] op_sel_hi:[1,0,0]
	v_pk_add_f32 v[84:85], v[10:11], v[118:119]
	v_pk_add_f32 v[10:11], v[10:11], v[118:119] neg_lo:[0,1] neg_hi:[0,1]
	s_nop 0
	v_pk_mul_f32 v[118:119], v[10:11], s[34:35]
	s_nop 0
	v_pk_fma_f32 v[10:11], v[10:11], s[8:9], v[118:119] op_sel:[0,0,1] op_sel_hi:[1,0,0]
	v_pk_add_f32 v[118:119], v[12:13], v[120:121]
	v_pk_add_f32 v[12:13], v[12:13], v[120:121] neg_lo:[0,1] neg_hi:[0,1]
	s_nop 0
	v_pk_mul_f32 v[120:121], v[12:13], s[76:77]
	s_nop 0
	v_pk_fma_f32 v[12:13], v[12:13], s[28:29], v[120:121] op_sel:[0,0,1] op_sel_hi:[1,0,0]
	v_pk_add_f32 v[120:121], v[14:15], v[122:123]
	v_pk_add_f32 v[14:15], v[14:15], v[122:123] neg_lo:[0,1] neg_hi:[0,1]
	v_pk_add_f32 v[122:123], v[16:17], v[124:125]
	v_pk_add_f32 v[16:17], v[16:17], v[124:125] neg_lo:[0,1] neg_hi:[0,1]
	s_nop 0
	v_pk_mul_f32 v[124:125], v[16:17], s[76:77]
	s_nop 0
	v_pk_fma_f32 v[16:17], v[16:17], s[28:29], v[124:125] op_sel:[0,0,1] op_sel_hi:[1,0,0] neg_lo:[1,0,0] neg_hi:[1,0,0]
	v_pk_add_f32 v[124:125], v[18:19], v[126:127]
	v_pk_add_f32 v[18:19], v[18:19], v[126:127] neg_lo:[0,1] neg_hi:[0,1]
	s_nop 0
	v_pk_mul_f32 v[126:127], v[18:19], s[34:35]
	s_nop 0
	v_pk_fma_f32 v[18:19], v[18:19], s[8:9], v[126:127] op_sel:[0,0,1] op_sel_hi:[1,0,0] neg_lo:[1,0,0] neg_hi:[1,0,0]
	v_pk_add_f32 v[126:127], v[20:21], v[128:129]
	v_pk_add_f32 v[20:21], v[20:21], v[128:129] neg_lo:[0,1] neg_hi:[0,1]
	s_nop 0
	v_pk_mul_f32 v[128:129], v[20:21], s[12:13]
	s_nop 0
	v_pk_fma_f32 v[20:21], v[20:21], s[4:5], v[128:129] op_sel:[0,0,1] op_sel_hi:[1,0,0] neg_lo:[1,0,0] neg_hi:[1,0,0]
	s_waitcnt lgkmcnt(6)
	v_pk_add_f32 v[128:129], v[22:23], v[132:133]
	v_pk_add_f32 v[22:23], v[22:23], v[132:133] neg_lo:[0,1] neg_hi:[0,1]
	s_nop 0
	v_pk_mul_f32 v[132:133], v[22:23], s[10:11]
	s_nop 0
	v_pk_fma_f32 v[22:23], v[22:23], s[14:15], v[132:133] op_sel:[0,0,1] op_sel_hi:[1,0,0] neg_lo:[1,0,0] neg_hi:[1,0,0]
	s_waitcnt lgkmcnt(3)
	v_pk_add_f32 v[132:133], v[138:139], v[134:135]
	v_pk_add_f32 v[134:135], v[138:139], v[134:135] neg_lo:[0,1] neg_hi:[0,1]
	s_nop 0
	v_pk_mul_f32 v[138:139], v[134:135], s[20:21]
	s_nop 0
	v_pk_fma_f32 v[134:135], v[134:135], s[86:87], v[138:139] op_sel:[0,0,1] op_sel_hi:[1,0,0] neg_lo:[1,0,0] neg_hi:[1,0,0]
	s_waitcnt lgkmcnt(2)
	v_pk_add_f32 v[138:139], v[140:141], v[136:137]
	v_pk_add_f32 v[136:137], v[140:141], v[136:137] neg_lo:[0,1] neg_hi:[0,1]
	s_nop 0
	v_pk_mul_f32 v[140:141], v[136:137], s[18:19]
	s_nop 0
	v_pk_fma_f32 v[136:137], v[136:137], s[30:31], v[140:141] op_sel:[0,0,1] op_sel_hi:[1,0,0] neg_lo:[1,0,0] neg_hi:[1,0,0]
	s_waitcnt lgkmcnt(0)
	v_pk_add_f32 v[140:141], v[142:143], v[144:145]
	v_pk_add_f32 v[142:143], v[142:143], v[144:145] neg_lo:[0,1] neg_hi:[0,1]
	s_nop 0
	v_pk_mul_f32 v[144:145], v[142:143], s[16:17]
	s_nop 0
	v_pk_fma_f32 v[142:143], v[142:143], s[6:7], v[144:145] op_sel:[0,0,1] op_sel_hi:[1,0,0] neg_lo:[1,0,0] neg_hi:[1,0,0]
	v_pk_add_f32 v[144:145], v[158:159], v[120:121]
	v_pk_add_f32 v[120:121], v[158:159], v[120:121] neg_lo:[0,1] neg_hi:[0,1]
	v_pk_add_f32 v[158:159], v[130:131], v[122:123]
	v_pk_add_f32 v[122:123], v[130:131], v[122:123] neg_lo:[0,1] neg_hi:[0,1]
	s_nop 0
	v_pk_mul_f32 v[130:131], v[122:123], s[18:19]
	s_nop 0
	v_pk_fma_f32 v[122:123], v[122:123], s[30:31], v[130:131] op_sel:[0,0,1] op_sel_hi:[1,0,0]
	v_pk_add_f32 v[130:131], v[26:27], v[124:125]
	v_pk_add_f32 v[26:27], v[26:27], v[124:125] neg_lo:[0,1] neg_hi:[0,1]
	s_nop 0
	v_pk_mul_f32 v[124:125], v[26:27], s[10:11]
	s_nop 0
	v_pk_fma_f32 v[26:27], v[26:27], s[14:15], v[124:125] op_sel:[0,0,1] op_sel_hi:[1,0,0]
	v_pk_add_f32 v[124:125], v[28:29], v[126:127]
	v_pk_add_f32 v[28:29], v[28:29], v[126:127] neg_lo:[0,1] neg_hi:[0,1]
	s_nop 0
	v_pk_mul_f32 v[126:127], v[28:29], s[34:35]
	s_nop 0
	v_pk_fma_f32 v[28:29], v[28:29], s[8:9], v[126:127] op_sel:[0,0,1] op_sel_hi:[1,0,0]
	v_pk_add_f32 v[126:127], v[30:31], v[128:129]
	v_pk_add_f32 v[30:31], v[30:31], v[128:129] neg_lo:[0,1] neg_hi:[0,1]
	v_pk_add_f32 v[128:129], v[82:83], v[132:133]
	v_pk_add_f32 v[82:83], v[82:83], v[132:133] neg_lo:[0,1] neg_hi:[0,1]
	s_nop 0
	v_pk_mul_f32 v[132:133], v[82:83], s[34:35]
	s_nop 0
	v_pk_fma_f32 v[82:83], v[82:83], s[8:9], v[132:133] op_sel:[0,0,1] op_sel_hi:[1,0,0] neg_lo:[1,0,0] neg_hi:[1,0,0]
	v_pk_add_f32 v[132:133], v[84:85], v[138:139]
	v_pk_add_f32 v[84:85], v[84:85], v[138:139] neg_lo:[0,1] neg_hi:[0,1]
	s_nop 0
	v_pk_mul_f32 v[138:139], v[84:85], s[10:11]
	s_nop 0
	v_pk_fma_f32 v[84:85], v[84:85], s[14:15], v[138:139] op_sel:[0,0,1] op_sel_hi:[1,0,0] neg_lo:[1,0,0] neg_hi:[1,0,0]
	v_pk_add_f32 v[138:139], v[118:119], v[140:141]
	v_pk_add_f32 v[118:119], v[118:119], v[140:141] neg_lo:[0,1] neg_hi:[0,1]
	s_nop 0
	v_pk_mul_f32 v[140:141], v[118:119], s[18:19]
	s_nop 0
	v_pk_fma_f32 v[118:119], v[118:119], s[30:31], v[140:141] op_sel:[0,0,1] op_sel_hi:[1,0,0] neg_lo:[1,0,0] neg_hi:[1,0,0]
	v_pk_add_f32 v[140:141], v[24:25], v[14:15] op_sel:[0,1] op_sel_hi:[1,0] neg_hi:[0,1]
	v_pk_add_f32 v[14:15], v[24:25], v[14:15] op_sel:[0,1] op_sel_hi:[1,0] neg_lo:[0,1]
	v_pk_add_f32 v[24:25], v[0:1], v[16:17]
	v_pk_add_f32 v[0:1], v[0:1], v[16:17] neg_lo:[0,1] neg_hi:[0,1]
	s_nop 0
	v_pk_mul_f32 v[16:17], v[0:1], s[18:19]
	s_nop 0
	v_pk_fma_f32 v[0:1], v[0:1], s[30:31], v[16:17] op_sel:[0,0,1] op_sel_hi:[1,0,0]
	v_pk_add_f32 v[16:17], v[2:3], v[18:19]
	v_pk_add_f32 v[2:3], v[2:3], v[18:19] neg_lo:[0,1] neg_hi:[0,1]
	s_nop 0
	v_pk_mul_f32 v[18:19], v[2:3], s[10:11]
	s_nop 0
	v_pk_fma_f32 v[2:3], v[2:3], s[14:15], v[18:19] op_sel:[0,0,1] op_sel_hi:[1,0,0]
	v_pk_add_f32 v[18:19], v[4:5], v[20:21]
	v_pk_add_f32 v[4:5], v[4:5], v[20:21] neg_lo:[0,1] neg_hi:[0,1]
	s_nop 0
	v_pk_mul_f32 v[20:21], v[4:5], s[34:35]
	s_nop 0
	v_pk_fma_f32 v[4:5], v[4:5], s[8:9], v[20:21] op_sel:[0,0,1] op_sel_hi:[1,0,0]
	v_pk_add_f32 v[20:21], v[6:7], v[22:23]
	v_pk_add_f32 v[6:7], v[6:7], v[22:23] neg_lo:[0,1] neg_hi:[0,1]
	v_pk_add_f32 v[22:23], v[8:9], v[134:135]
	v_pk_add_f32 v[8:9], v[8:9], v[134:135] neg_lo:[0,1] neg_hi:[0,1]
	s_nop 0
	v_pk_mul_f32 v[134:135], v[8:9], s[34:35]
	s_nop 0
	v_pk_fma_f32 v[8:9], v[8:9], s[8:9], v[134:135] op_sel:[0,0,1] op_sel_hi:[1,0,0] neg_lo:[1,0,0] neg_hi:[1,0,0]
	v_pk_add_f32 v[134:135], v[10:11], v[136:137]
	v_pk_add_f32 v[10:11], v[10:11], v[136:137] neg_lo:[0,1] neg_hi:[0,1]
	s_nop 0
	v_pk_mul_f32 v[136:137], v[10:11], s[10:11]
	s_nop 0
	v_pk_fma_f32 v[10:11], v[10:11], s[14:15], v[136:137] op_sel:[0,0,1] op_sel_hi:[1,0,0] neg_lo:[1,0,0] neg_hi:[1,0,0]
	v_pk_add_f32 v[136:137], v[12:13], v[142:143]
	v_pk_add_f32 v[12:13], v[12:13], v[142:143] neg_lo:[0,1] neg_hi:[0,1]
	s_nop 0
	v_pk_mul_f32 v[142:143], v[12:13], s[18:19]
	s_nop 0
	v_pk_fma_f32 v[12:13], v[12:13], s[30:31], v[142:143] op_sel:[0,0,1] op_sel_hi:[1,0,0] neg_lo:[1,0,0] neg_hi:[1,0,0]
	v_pk_add_f32 v[142:143], v[144:145], v[126:127]
	v_pk_add_f32 v[126:127], v[144:145], v[126:127] neg_lo:[0,1] neg_hi:[0,1]
	v_pk_add_f32 v[144:145], v[158:159], v[128:129]
	v_pk_add_f32 v[128:129], v[158:159], v[128:129] neg_lo:[0,1] neg_hi:[0,1]
	s_nop 0
	v_pk_mul_f32 v[158:159], v[128:129], s[10:11]
	s_nop 0
	v_pk_fma_f32 v[128:129], v[128:129], s[14:15], v[158:159] op_sel:[0,0,1] op_sel_hi:[1,0,0]
	v_pk_add_f32 v[158:159], v[130:131], v[132:133]
	v_pk_add_f32 v[130:131], v[130:131], v[132:133] neg_lo:[0,1] neg_hi:[0,1]
	v_pk_add_f32 v[132:133], v[124:125], v[138:139]
	v_pk_add_f32 v[124:125], v[124:125], v[138:139] neg_lo:[0,1] neg_hi:[0,1]
	s_nop 0
	v_pk_mul_f32 v[138:139], v[124:125], s[10:11]
	s_nop 0
	v_pk_fma_f32 v[124:125], v[124:125], s[14:15], v[138:139] op_sel:[0,0,1] op_sel_hi:[1,0,0] neg_lo:[1,0,0] neg_hi:[1,0,0]
	v_pk_add_f32 v[138:139], v[120:121], v[30:31] op_sel:[0,1] op_sel_hi:[1,0] neg_hi:[0,1]
	v_pk_add_f32 v[30:31], v[120:121], v[30:31] op_sel:[0,1] op_sel_hi:[1,0] neg_lo:[0,1]
	v_pk_add_f32 v[120:121], v[122:123], v[82:83]
	v_pk_add_f32 v[82:83], v[122:123], v[82:83] neg_lo:[0,1] neg_hi:[0,1]
	v_pk_add_f32 v[160:161], v[128:129], v[124:125]
	v_pk_mul_f32 v[122:123], v[82:83], s[10:11]
	v_pk_add_f32 v[124:125], v[128:129], v[124:125] neg_lo:[0,1] neg_hi:[0,1]
	v_pk_fma_f32 v[82:83], v[82:83], s[14:15], v[122:123] op_sel:[0,0,1] op_sel_hi:[1,0,0]
	v_pk_add_f32 v[122:123], v[26:27], v[84:85]
	v_pk_add_f32 v[26:27], v[26:27], v[84:85] neg_lo:[0,1] neg_hi:[0,1]
	v_pk_add_f32 v[84:85], v[28:29], v[118:119]
	v_pk_add_f32 v[28:29], v[28:29], v[118:119] neg_lo:[0,1] neg_hi:[0,1]
	s_nop 0
	v_pk_mul_f32 v[118:119], v[28:29], s[10:11]
	v_pk_add_f32 v[166:167], v[120:121], v[84:85]
	v_pk_fma_f32 v[28:29], v[28:29], s[14:15], v[118:119] op_sel:[0,0,1] op_sel_hi:[1,0,0] neg_lo:[1,0,0] neg_hi:[1,0,0]
	v_pk_add_f32 v[118:119], v[140:141], v[20:21]
	v_pk_add_f32 v[20:21], v[140:141], v[20:21] neg_lo:[0,1] neg_hi:[0,1]
	v_pk_add_f32 v[140:141], v[24:25], v[22:23]
	v_pk_add_f32 v[22:23], v[24:25], v[22:23] neg_lo:[0,1] neg_hi:[0,1]
	v_pk_add_f32 v[84:85], v[120:121], v[84:85] neg_lo:[0,1] neg_hi:[0,1]
	v_pk_mul_f32 v[24:25], v[22:23], s[10:11]
	v_pk_add_f32 v[168:169], v[30:31], v[26:27] op_sel:[0,1] op_sel_hi:[1,0] neg_hi:[0,1]
	v_pk_fma_f32 v[22:23], v[22:23], s[14:15], v[24:25] op_sel:[0,0,1] op_sel_hi:[1,0,0]
	v_pk_add_f32 v[24:25], v[16:17], v[134:135]
	v_pk_add_f32 v[16:17], v[16:17], v[134:135] neg_lo:[0,1] neg_hi:[0,1]
	v_pk_add_f32 v[134:135], v[18:19], v[136:137]
	v_pk_add_f32 v[18:19], v[18:19], v[136:137] neg_lo:[0,1] neg_hi:[0,1]
	s_nop 0
	v_pk_mul_f32 v[136:137], v[18:19], s[10:11]
	v_pk_add_f32 v[26:27], v[30:31], v[26:27] op_sel:[0,1] op_sel_hi:[1,0] neg_lo:[0,1]
	v_pk_fma_f32 v[18:19], v[18:19], s[14:15], v[136:137] op_sel:[0,0,1] op_sel_hi:[1,0,0] neg_lo:[1,0,0] neg_hi:[1,0,0]
	v_pk_add_f32 v[136:137], v[14:15], v[6:7] op_sel:[0,1] op_sel_hi:[1,0] neg_hi:[0,1]
	v_pk_add_f32 v[6:7], v[14:15], v[6:7] op_sel:[0,1] op_sel_hi:[1,0] neg_lo:[0,1]
	v_pk_add_f32 v[14:15], v[0:1], v[8:9]
	v_pk_add_f32 v[0:1], v[0:1], v[8:9] neg_lo:[0,1] neg_hi:[0,1]
	v_pk_add_f32 v[30:31], v[82:83], v[28:29]
	v_pk_mul_f32 v[8:9], v[0:1], s[10:11]
	v_pk_add_f32 v[28:29], v[82:83], v[28:29] neg_lo:[0,1] neg_hi:[0,1]
	v_pk_fma_f32 v[0:1], v[0:1], s[14:15], v[8:9] op_sel:[0,0,1] op_sel_hi:[1,0,0]
	v_pk_add_f32 v[8:9], v[2:3], v[10:11]
	v_pk_add_f32 v[2:3], v[2:3], v[10:11] neg_lo:[0,1] neg_hi:[0,1]
	v_pk_add_f32 v[10:11], v[4:5], v[12:13]
	v_pk_add_f32 v[4:5], v[4:5], v[12:13] neg_lo:[0,1] neg_hi:[0,1]
	s_nop 0
	v_pk_mul_f32 v[12:13], v[4:5], s[10:11]
	v_pk_add_f32 v[170:171], v[118:119], v[24:25]
	v_pk_fma_f32 v[4:5], v[4:5], s[14:15], v[12:13] op_sel:[0,0,1] op_sel_hi:[1,0,0] neg_lo:[1,0,0] neg_hi:[1,0,0]
	v_pk_add_f32 v[12:13], v[142:143], v[158:159]
	v_pk_add_f32 v[142:143], v[142:143], v[158:159] neg_lo:[0,1] neg_hi:[0,1]
	v_pk_add_f32 v[158:159], v[144:145], v[132:133]
	v_pk_add_f32 v[132:133], v[144:145], v[132:133] neg_lo:[0,1] neg_hi:[0,1]
	v_pk_add_f32 v[182:183], v[118:119], v[24:25] neg_lo:[0,1] neg_hi:[0,1]
	v_pk_add_f32 v[184:185], v[140:141], v[134:135]
	v_pk_add_f32 v[24:25], v[140:141], v[134:135] neg_lo:[0,1] neg_hi:[0,1]
	v_pk_add_f32 v[140:141], v[20:21], v[16:17] op_sel:[0,1] op_sel_hi:[1,0] neg_hi:[0,1]
	v_pk_add_f32 v[186:187], v[20:21], v[16:17] op_sel:[0,1] op_sel_hi:[1,0] neg_lo:[0,1]
	v_pk_add_f32 v[16:17], v[22:23], v[18:19] neg_lo:[0,1] neg_hi:[0,1]
	v_pk_add_f32 v[192:193], v[136:137], v[8:9]
	v_pk_add_f32 v[194:195], v[136:137], v[8:9] neg_lo:[0,1] neg_hi:[0,1]
	v_pk_add_f32 v[8:9], v[14:15], v[10:11] neg_lo:[0,1] neg_hi:[0,1]
	v_pk_add_f32 v[198:199], v[6:7], v[2:3] op_sel:[0,1] op_sel_hi:[1,0] neg_hi:[0,1]
	v_pk_add_f32 v[200:201], v[6:7], v[2:3] op_sel:[0,1] op_sel_hi:[1,0] neg_lo:[0,1]
	v_pk_add_f32 v[2:3], v[0:1], v[4:5]
	v_pk_add_f32 v[0:1], v[0:1], v[4:5] neg_lo:[0,1] neg_hi:[0,1]
	v_pk_add_f32 v[144:145], v[126:127], v[130:131] op_sel:[0,1] op_sel_hi:[1,0] neg_hi:[0,1]
	v_pk_add_f32 v[130:131], v[126:127], v[130:131] op_sel:[0,1] op_sel_hi:[1,0] neg_lo:[0,1]
	v_pk_mul_f32 v[162:163], v[124:125], s[22:23]
	v_pk_add_f32 v[164:165], v[138:139], v[122:123]
	v_pk_add_f32 v[138:139], v[138:139], v[122:123] neg_lo:[0,1] neg_hi:[0,1]
	v_pk_mul_f32 v[82:83], v[28:29], s[22:23]
	v_pk_mul_f32 v[134:135], v[24:25], s[22:23]
	v_pk_add_f32 v[188:189], v[22:23], v[18:19]
	v_pk_mul_f32 v[190:191], v[16:17], s[22:23]
	v_pk_add_f32 v[136:137], v[14:15], v[10:11]
	v_pk_mul_f32 v[196:197], v[8:9], s[22:23]
	v_pk_mul_f32 v[202:203], v[0:1], s[22:23]
	v_pk_add_f32 v[28:29], v[12:13], v[158:159]
	v_pk_add_f32 v[128:129], v[12:13], v[158:159] neg_lo:[0,1] neg_hi:[0,1]
	v_pk_add_f32 v[24:25], v[142:143], v[132:133] op_sel:[0,1] op_sel_hi:[1,0] neg_hi:[0,1]
	v_pk_add_f32 v[126:127], v[142:143], v[132:133] op_sel:[0,1] op_sel_hi:[1,0] neg_lo:[0,1]
	v_pk_add_f32 v[20:21], v[144:145], v[160:161]
	v_pk_add_f32 v[124:125], v[144:145], v[160:161] neg_lo:[0,1] neg_hi:[0,1]
	v_pk_add_f32 v[16:17], v[130:131], v[162:163] op_sel:[0,1] op_sel_hi:[1,0]
	v_pk_add_f32 v[122:123], v[130:131], v[162:163] op_sel:[0,1] op_sel_hi:[1,0] neg_lo:[0,1] neg_hi:[0,1]
	v_pk_add_f32 v[12:13], v[164:165], v[166:167]
	v_pk_add_f32 v[120:121], v[164:165], v[166:167] neg_lo:[0,1] neg_hi:[0,1]
	v_pk_add_f32 v[8:9], v[138:139], v[84:85] op_sel:[0,1] op_sel_hi:[1,0] neg_hi:[0,1]
	v_pk_add_f32 v[118:119], v[138:139], v[84:85] op_sel:[0,1] op_sel_hi:[1,0] neg_lo:[0,1]
	v_pk_add_f32 v[4:5], v[168:169], v[30:31]
	v_pk_add_f32 v[84:85], v[168:169], v[30:31] neg_lo:[0,1] neg_hi:[0,1]
	v_pk_add_f32 v[0:1], v[26:27], v[82:83] op_sel:[0,1] op_sel_hi:[1,0]
	v_pk_add_f32 v[82:83], v[26:27], v[82:83] op_sel:[0,1] op_sel_hi:[1,0] neg_lo:[0,1] neg_hi:[0,1]
	v_pk_add_f32 v[30:31], v[170:171], v[184:185]
	v_pk_add_f32 v[144:145], v[170:171], v[184:185] neg_lo:[0,1] neg_hi:[0,1]
	v_pk_add_f32 v[26:27], v[182:183], v[134:135] op_sel:[0,1] op_sel_hi:[1,0]
	v_pk_add_f32 v[142:143], v[182:183], v[134:135] op_sel:[0,1] op_sel_hi:[1,0] neg_lo:[0,1] neg_hi:[0,1]
	v_pk_add_f32 v[22:23], v[140:141], v[188:189]
	v_pk_add_f32 v[140:141], v[140:141], v[188:189] neg_lo:[0,1] neg_hi:[0,1]
	v_pk_add_f32 v[18:19], v[186:187], v[190:191] op_sel:[0,1] op_sel_hi:[1,0]
	v_pk_add_f32 v[138:139], v[186:187], v[190:191] op_sel:[0,1] op_sel_hi:[1,0] neg_lo:[0,1] neg_hi:[0,1]
	v_pk_add_f32 v[14:15], v[192:193], v[136:137]
	v_pk_add_f32 v[136:137], v[192:193], v[136:137] neg_lo:[0,1] neg_hi:[0,1]
	v_pk_add_f32 v[10:11], v[194:195], v[196:197] op_sel:[0,1] op_sel_hi:[1,0]
	v_pk_add_f32 v[134:135], v[194:195], v[196:197] op_sel:[0,1] op_sel_hi:[1,0] neg_lo:[0,1] neg_hi:[0,1]
	v_pk_add_f32 v[6:7], v[198:199], v[2:3]
	v_pk_add_f32 v[132:133], v[198:199], v[2:3] neg_lo:[0,1] neg_hi:[0,1]
	v_pk_add_f32 v[2:3], v[200:201], v[202:203] op_sel:[0,1] op_sel_hi:[1,0]
	v_pk_add_f32 v[130:131], v[200:201], v[202:203] op_sel:[0,1] op_sel_hi:[1,0] neg_lo:[0,1] neg_hi:[0,1]

.LBB0_618:
	v_add_u32_e32 v160, 0x11000, v155
	v_lshlrev_b32_e32 v161, 3, v154
	v_add_u32_e32 v161, 0x2200, v161
	v_add_u32_e32 v162, 0x11100, v156
	v_cmp_ne_u32_e32 vcc, 0, v32
	v_cndmask_b32_e32 v163, 0, v154, vcc
	v_lshlrev_b32_e32 v163, 3, v163
	v_add_u32_e32 v163, 0x11000, v163
	s_mov_b32 s100, 0x38800000
	s_mov_b32 s101, 0xb8800000
	ds_read_b64 v[214:215], v160 offset:0
	ds_read_b64 v[216:217], v163
	ds_read_b64 v[218:219], v160 offset:4352
	ds_read_b64 v[220:221], v162 offset:60928
	ds_read_b64 v[222:223], v160 offset:8704
	ds_read_b64 v[224:225], v161 offset:52224
	ds_read_b64 v[226:227], v160 offset:13056
	ds_read_b64 v[228:229], v162 offset:52224
	s_waitcnt lgkmcnt(6)
	v_add_f32_e32 v214, v214, v216
	v_sub_f32_e32 v216, v215, v217
	v_pk_mul_f32 v[216:217], v[6:7], v[216:217] op_sel:[1,0] op_sel_hi:[0,0]
	v_pk_fma_f32 v[158:159], v[6:7], v[214:215], v[216:217] neg_lo:[0,0,1] neg_hi:[0,0,1]
	v_pk_fma_f32 v[214:215], v[6:7], v[214:215], v[216:217] op_sel_hi:[1,0,1]
	s_nop 0
	v_mov_b32_e32 v159, v215
	v_pk_mul_f32 v[6:7], v[158:159], s[100:101]
	ds_write_b64 v122, v[6:7] offset:0
	s_waitcnt lgkmcnt(5)
	v_add_f32_e32 v218, v218, v220
	v_sub_f32_e32 v220, v219, v221
	v_pk_mul_f32 v[220:221], v[18:19], v[220:221] op_sel:[1,0] op_sel_hi:[0,0]
	v_pk_fma_f32 v[158:159], v[18:19], v[218:219], v[220:221] neg_lo:[0,0,1] neg_hi:[0,0,1]
	v_pk_fma_f32 v[218:219], v[18:19], v[218:219], v[220:221] op_sel_hi:[1,0,1]
	s_nop 0
	v_mov_b32_e32 v159, v219
	v_pk_mul_f32 v[18:19], v[158:159], s[100:101]
	ds_write_b64 v122, v[18:19] offset:4352
	ds_read_b64 v[230:231], v160 offset:17408
	ds_read_b64 v[232:233], v161 offset:43520
	ds_read_b64 v[234:235], v160 offset:21760
	ds_read_b64 v[236:237], v162 offset:43520
	s_waitcnt lgkmcnt(8)
	v_add_f32_e32 v222, v222, v224
	v_sub_f32_e32 v224, v223, v225
	v_pk_mul_f32 v[224:225], v[28:29], v[224:225] op_sel:[1,0] op_sel_hi:[0,0]
	v_pk_fma_f32 v[158:159], v[28:29], v[222:223], v[224:225] neg_lo:[0,0,1] neg_hi:[0,0,1]
	v_pk_fma_f32 v[222:223], v[28:29], v[222:223], v[224:225] op_sel_hi:[1,0,1]
	s_nop 0
	v_mov_b32_e32 v159, v223
	v_pk_mul_f32 v[28:29], v[158:159], s[100:101]
	ds_write_b64 v122, v[28:29] offset:8704
	s_waitcnt lgkmcnt(7)
	v_add_f32_e32 v226, v226, v228
	v_sub_f32_e32 v228, v227, v229
	v_pk_mul_f32 v[228:229], v[10:11], v[228:229] op_sel:[1,0] op_sel_hi:[0,0]
	v_pk_fma_f32 v[158:159], v[10:11], v[226:227], v[228:229] neg_lo:[0,0,1] neg_hi:[0,0,1]
	v_pk_fma_f32 v[226:227], v[10:11], v[226:227], v[228:229] op_sel_hi:[1,0,1]
	s_nop 0
	v_mov_b32_e32 v159, v227
	v_pk_mul_f32 v[10:11], v[158:159], s[100:101]
	ds_write_b64 v122, v[10:11] offset:13056
	ds_read_b64 v[214:215], v160 offset:26112
	ds_read_b64 v[216:217], v161 offset:34816
	ds_read_b64 v[218:219], v160 offset:30464
	ds_read_b64 v[220:221], v162 offset:34816
	s_waitcnt lgkmcnt(8)
	v_add_f32_e32 v230, v230, v232
	v_sub_f32_e32 v232, v231, v233
	v_pk_mul_f32 v[232:233], v[26:27], v[232:233] op_sel:[1,0] op_sel_hi:[0,0]
	v_pk_fma_f32 v[158:159], v[26:27], v[230:231], v[232:233] neg_lo:[0,0,1] neg_hi:[0,0,1]
	v_pk_fma_f32 v[230:231], v[26:27], v[230:231], v[232:233] op_sel_hi:[1,0,1]
	s_nop 0
	v_mov_b32_e32 v159, v231
	v_pk_mul_f32 v[26:27], v[158:159], s[100:101]
	ds_write_b64 v122, v[26:27] offset:17408
	s_waitcnt lgkmcnt(7)
	v_add_f32_e32 v234, v234, v236
	v_sub_f32_e32 v236, v235, v237
	v_pk_mul_f32 v[236:237], v[30:31], v[236:237] op_sel:[1,0] op_sel_hi:[0,0]
	v_pk_fma_f32 v[158:159], v[30:31], v[234:235], v[236:237] neg_lo:[0,0,1] neg_hi:[0,0,1]
	v_pk_fma_f32 v[234:235], v[30:31], v[234:235], v[236:237] op_sel_hi:[1,0,1]
	s_nop 0
	v_mov_b32_e32 v159, v235
	v_pk_mul_f32 v[30:31], v[158:159], s[100:101]
	ds_write_b64 v122, v[30:31] offset:21760
	ds_read_b64 v[222:223], v160 offset:34816
	ds_read_b64 v[224:225], v161 offset:26112
	ds_read_b64 v[226:227], v160 offset:39168
	ds_read_b64 v[228:229], v162 offset:26112
	s_waitcnt lgkmcnt(8)
	v_add_f32_e32 v214, v214, v216
	v_sub_f32_e32 v216, v215, v217
	v_pk_mul_f32 v[216:217], v[86:87], v[216:217] op_sel:[1,0] op_sel_hi:[0,0]
	v_pk_fma_f32 v[158:159], v[86:87], v[214:215], v[216:217] neg_lo:[0,0,1] neg_hi:[0,0,1]
	v_pk_fma_f32 v[214:215], v[86:87], v[214:215], v[216:217] op_sel_hi:[1,0,1]
	s_nop 0
	v_mov_b32_e32 v159, v215
	v_pk_mul_f32 v[86:87], v[158:159], s[100:101]
	ds_write_b64 v122, v[86:87] offset:26112
	s_waitcnt lgkmcnt(7)
	v_add_f32_e32 v218, v218, v220
	v_sub_f32_e32 v220, v219, v221
	v_pk_mul_f32 v[220:221], v[12:13], v[220:221] op_sel:[1,0] op_sel_hi:[0,0]
	v_pk_fma_f32 v[158:159], v[12:13], v[218:219], v[220:221] neg_lo:[0,0,1] neg_hi:[0,0,1]
	v_pk_fma_f32 v[218:219], v[12:13], v[218:219], v[220:221] op_sel_hi:[1,0,1]
	s_nop 0
	v_mov_b32_e32 v159, v219
	v_pk_mul_f32 v[12:13], v[158:159], s[100:101]
	ds_write_b64 v122, v[12:13] offset:30464
	ds_read_b64 v[230:231], v160 offset:43520
	ds_read_b64 v[232:233], v161 offset:17408
	ds_read_b64 v[234:235], v160 offset:47872
	ds_read_b64 v[236:237], v162 offset:17408
	s_waitcnt lgkmcnt(8)
	v_add_f32_e32 v222, v222, v224
	v_sub_f32_e32 v224, v223, v225
	v_pk_mul_f32 v[224:225], v[14:15], v[224:225] op_sel:[1,0] op_sel_hi:[0,0]
	v_pk_fma_f32 v[158:159], v[14:15], v[222:223], v[224:225] neg_lo:[0,0,1] neg_hi:[0,0,1]
	v_pk_fma_f32 v[222:223], v[14:15], v[222:223], v[224:225] op_sel_hi:[1,0,1]
	s_nop 0
	v_mov_b32_e32 v159, v223
	v_pk_mul_f32 v[14:15], v[158:159], s[100:101]
	ds_write_b64 v122, v[14:15] offset:34816
	s_waitcnt lgkmcnt(7)
	v_add_f32_e32 v226, v226, v228
	v_sub_f32_e32 v228, v227, v229
	v_pk_mul_f32 v[228:229], v[20:21], v[228:229] op_sel:[1,0] op_sel_hi:[0,0]
	v_pk_fma_f32 v[158:159], v[20:21], v[226:227], v[228:229] neg_lo:[0,0,1] neg_hi:[0,0,1]
	v_pk_fma_f32 v[226:227], v[20:21], v[226:227], v[228:229] op_sel_hi:[1,0,1]
	s_nop 0
	v_mov_b32_e32 v159, v227
	v_pk_mul_f32 v[20:21], v[158:159], s[100:101]
	ds_write_b64 v122, v[20:21] offset:39168
	ds_read_b64 v[214:215], v160 offset:52224
	ds_read_b64 v[216:217], v161 offset:8704
	ds_read_b64 v[218:219], v160 offset:56576
	ds_read_b64 v[220:221], v162 offset:8704
	s_waitcnt lgkmcnt(8)
	v_add_f32_e32 v230, v230, v232
	v_sub_f32_e32 v232, v231, v233
	v_pk_mul_f32 v[232:233], v[22:23], v[232:233] op_sel:[1,0] op_sel_hi:[0,0]
	v_pk_fma_f32 v[158:159], v[22:23], v[230:231], v[232:233] neg_lo:[0,0,1] neg_hi:[0,0,1]
	v_pk_fma_f32 v[230:231], v[22:23], v[230:231], v[232:233] op_sel_hi:[1,0,1]
	s_nop 0
	v_mov_b32_e32 v159, v231
	v_pk_mul_f32 v[22:23], v[158:159], s[100:101]
	ds_write_b64 v122, v[22:23] offset:43520
	s_waitcnt lgkmcnt(7)
	v_add_f32_e32 v234, v234, v236
	v_sub_f32_e32 v236, v235, v237
	v_pk_mul_f32 v[236:237], v[4:5], v[236:237] op_sel:[1,0] op_sel_hi:[0,0]
	v_pk_fma_f32 v[158:159], v[4:5], v[234:235], v[236:237] neg_lo:[0,0,1] neg_hi:[0,0,1]
	v_pk_fma_f32 v[234:235], v[4:5], v[234:235], v[236:237] op_sel_hi:[1,0,1]
	s_nop 0
	v_mov_b32_e32 v159, v235
	v_pk_mul_f32 v[4:5], v[158:159], s[100:101]
	ds_write_b64 v122, v[4:5] offset:47872
	ds_read_b64 v[222:223], v160 offset:60928
	ds_read_b64 v[224:225], v161 offset:0
	ds_read_b64 v[226:227], v160 offset:65280
	ds_read_b64 v[228:229], v162 offset:0
	s_waitcnt lgkmcnt(8)
	v_add_f32_e32 v214, v214, v216
	v_sub_f32_e32 v216, v215, v217
	v_pk_mul_f32 v[216:217], v[24:25], v[216:217] op_sel:[1,0] op_sel_hi:[0,0]
	v_pk_fma_f32 v[158:159], v[24:25], v[214:215], v[216:217] neg_lo:[0,0,1] neg_hi:[0,0,1]
	v_pk_fma_f32 v[214:215], v[24:25], v[214:215], v[216:217] op_sel_hi:[1,0,1]
	s_nop 0
	v_mov_b32_e32 v159, v215
	v_pk_mul_f32 v[24:25], v[158:159], s[100:101]
	ds_write_b64 v122, v[24:25] offset:52224
	s_waitcnt lgkmcnt(7)
	v_add_f32_e32 v218, v218, v220
	v_sub_f32_e32 v220, v219, v221
	v_pk_mul_f32 v[220:221], v[8:9], v[220:221] op_sel:[1,0] op_sel_hi:[0,0]
	v_pk_fma_f32 v[158:159], v[8:9], v[218:219], v[220:221] neg_lo:[0,0,1] neg_hi:[0,0,1]
	v_pk_fma_f32 v[218:219], v[8:9], v[218:219], v[220:221] op_sel_hi:[1,0,1]
	s_nop 0
	v_mov_b32_e32 v159, v219
	v_pk_mul_f32 v[8:9], v[158:159], s[100:101]
	ds_write_b64 v122, v[8:9] offset:56576
	s_waitcnt lgkmcnt(4)
	v_add_f32_e32 v222, v222, v224
	v_sub_f32_e32 v224, v223, v225
	v_pk_mul_f32 v[224:225], v[16:17], v[224:225] op_sel:[1,0] op_sel_hi:[0,0]
	v_pk_fma_f32 v[158:159], v[16:17], v[222:223], v[224:225] neg_lo:[0,0,1] neg_hi:[0,0,1]
	v_pk_fma_f32 v[222:223], v[16:17], v[222:223], v[224:225] op_sel_hi:[1,0,1]
	s_nop 0
	v_mov_b32_e32 v159, v223
	v_pk_mul_f32 v[16:17], v[158:159], s[100:101]
	ds_write_b64 v122, v[16:17] offset:60928
	s_waitcnt lgkmcnt(3)
	v_add_f32_e32 v226, v226, v228
	v_sub_f32_e32 v228, v227, v229
	v_pk_mul_f32 v[228:229], v[0:1], v[228:229] op_sel:[1,0] op_sel_hi:[0,0]
	v_pk_fma_f32 v[158:159], v[0:1], v[226:227], v[228:229] neg_lo:[0,0,1] neg_hi:[0,0,1]
	v_pk_fma_f32 v[226:227], v[0:1], v[226:227], v[228:229] op_sel_hi:[1,0,1]
	s_nop 0
	v_mov_b32_e32 v159, v227
	v_pk_mul_f32 v[0:1], v[158:159], s[100:101]
	ds_write_b64 v122, v[0:1] offset:65280
	s_mov_b32 s4, 16
	s_cmp_lg_u32 s4, 16
	s_waitcnt lgkmcnt(0)
	s_barrier
	s_and_saveexec_b64 s[28:29], s[40:41]
	s_cbranch_execz .LBB0_621
	ds_read_b64 v[0:1], v153
	ds_read_b64 v[2:3], v153 offset:2176
	ds_read_b64 v[4:5], v153 offset:4352
	ds_read_b64 v[6:7], v153 offset:6528
	ds_read_b64 v[8:9], v153 offset:8704
	ds_read_b64 v[10:11], v153 offset:10880
	ds_read_b64 v[12:13], v153 offset:13056
	ds_read_b64 v[14:15], v153 offset:15232
	ds_read_b64 v[16:17], v153 offset:17408
	ds_read_b64 v[18:19], v153 offset:19584
	ds_read_b64 v[20:21], v153 offset:21760
	ds_read_b64 v[22:23], v153 offset:23936
	ds_read_b64 v[24:25], v153 offset:26112
	ds_read_b64 v[26:27], v153 offset:28288
	ds_read_b64 v[28:29], v153 offset:30464
	ds_read_b64 v[30:31], v153 offset:32640
	ds_read_b64 v[86:87], v153 offset:34816
	ds_read_b64 v[92:93], v153 offset:41344
	ds_read_b64 v[94:95], v153 offset:43520
	ds_read_b64 v[96:97], v153 offset:45696
	ds_read_b64 v[98:99], v153 offset:47872
	ds_read_b64 v[100:101], v153 offset:50048
	ds_read_b64 v[102:103], v153 offset:52224
	ds_read_b64 v[104:105], v153 offset:54400
	ds_read_b64 v[106:107], v153 offset:56576
	ds_read_b64 v[108:109], v153 offset:58752
	ds_read_b64 v[110:111], v153 offset:60928
	ds_read_b64 v[112:113], v153 offset:63104
	ds_read_b64 v[114:115], v153 offset:65280
	ds_read_b64 v[116:117], v153 offset:36992
	ds_read_b64 v[118:119], v153 offset:39168
	ds_read_b64 v[120:121], v33
	s_waitcnt lgkmcnt(14)
	v_pk_add_f32 v[124:125], v[0:1], v[86:87]
	v_pk_add_f32 v[0:1], v[0:1], v[86:87] neg_lo:[0,1] neg_hi:[0,1]
	s_waitcnt lgkmcnt(2)
	v_pk_add_f32 v[86:87], v[2:3], v[116:117]
	v_pk_add_f32 v[2:3], v[2:3], v[116:117] neg_lo:[0,1] neg_hi:[0,1]
	s_mov_b32 s11, s14
	v_pk_mul_f32 v[116:117], v[2:3], s[16:17]
	s_mov_b32 s13, s86
	v_pk_fma_f32 v[2:3], v[2:3], s[6:7], v[116:117] op_sel:[0,0,1] op_sel_hi:[1,0,0]
	s_waitcnt lgkmcnt(1)
	v_pk_add_f32 v[116:117], v[4:5], v[118:119]
	v_pk_add_f32 v[4:5], v[4:5], v[118:119] neg_lo:[0,1] neg_hi:[0,1]
	s_mov_b32 s4, s21
	v_pk_mul_f32 v[118:119], v[4:5], s[18:19]
	s_mov_b32 s35, s30
	v_pk_fma_f32 v[4:5], v[4:5], s[30:31], v[118:119] op_sel:[0,0,1] op_sel_hi:[1,0,0]
	v_pk_add_f32 v[118:119], v[6:7], v[92:93]
	v_pk_add_f32 v[6:7], v[6:7], v[92:93] neg_lo:[0,1] neg_hi:[0,1]
	s_mov_b32 s8, s19
	v_pk_mul_f32 v[92:93], v[6:7], s[20:21]
	s_mov_b32 s77, s6
	v_pk_fma_f32 v[6:7], v[6:7], s[86:87], v[92:93] op_sel:[0,0,1] op_sel_hi:[1,0,0]
	v_pk_add_f32 v[92:93], v[8:9], v[94:95]
	v_pk_add_f32 v[8:9], v[8:9], v[94:95] neg_lo:[0,1] neg_hi:[0,1]
	s_mov_b32 s26, s17
	v_pk_mul_f32 v[94:95], v[8:9], s[10:11]
	s_nop 0
	v_pk_fma_f32 v[8:9], v[8:9], s[14:15], v[94:95] op_sel:[0,0,1] op_sel_hi:[1,0,0]
	v_pk_add_f32 v[94:95], v[10:11], v[96:97]
	v_pk_add_f32 v[10:11], v[10:11], v[96:97] neg_lo:[0,1] neg_hi:[0,1]
	s_nop 0
	v_pk_mul_f32 v[96:97], v[10:11], s[12:13]
	s_nop 0
	v_pk_fma_f32 v[10:11], v[10:11], s[4:5], v[96:97] op_sel:[0,0,1] op_sel_hi:[1,0,0]
	v_pk_add_f32 v[96:97], v[12:13], v[98:99]
	v_pk_add_f32 v[12:13], v[12:13], v[98:99] neg_lo:[0,1] neg_hi:[0,1]
	s_nop 0
	v_pk_mul_f32 v[98:99], v[12:13], s[34:35]
	s_nop 0
	v_pk_fma_f32 v[12:13], v[12:13], s[8:9], v[98:99] op_sel:[0,0,1] op_sel_hi:[1,0,0]
	v_pk_add_f32 v[98:99], v[14:15], v[100:101]
	v_pk_add_f32 v[14:15], v[14:15], v[100:101] neg_lo:[0,1] neg_hi:[0,1]
	s_nop 0
	v_pk_mul_f32 v[100:101], v[14:15], s[76:77]
	s_nop 0
	v_pk_fma_f32 v[14:15], v[14:15], s[26:27], v[100:101] op_sel:[0,0,1] op_sel_hi:[1,0,0]
	v_pk_add_f32 v[100:101], v[16:17], v[102:103]
	v_pk_add_f32 v[16:17], v[16:17], v[102:103] neg_lo:[0,1] neg_hi:[0,1]
	v_pk_add_f32 v[102:103], v[18:19], v[104:105]
	v_pk_add_f32 v[18:19], v[18:19], v[104:105] neg_lo:[0,1] neg_hi:[0,1]
	s_nop 0
	v_pk_mul_f32 v[104:105], v[18:19], s[76:77]
	s_nop 0
	v_pk_fma_f32 v[18:19], v[18:19], s[26:27], v[104:105] op_sel:[0,0,1] op_sel_hi:[1,0,0] neg_lo:[1,0,0] neg_hi:[1,0,0]
	v_pk_add_f32 v[104:105], v[20:21], v[106:107]
	v_pk_add_f32 v[20:21], v[20:21], v[106:107] neg_lo:[0,1] neg_hi:[0,1]
	s_nop 0
	v_pk_mul_f32 v[106:107], v[20:21], s[34:35]
	s_nop 0
	v_pk_fma_f32 v[20:21], v[20:21], s[8:9], v[106:107] op_sel:[0,0,1] op_sel_hi:[1,0,0] neg_lo:[1,0,0] neg_hi:[1,0,0]
	v_pk_add_f32 v[106:107], v[22:23], v[108:109]
	v_pk_add_f32 v[22:23], v[22:23], v[108:109] neg_lo:[0,1] neg_hi:[0,1]
	s_nop 0
	v_pk_mul_f32 v[108:109], v[22:23], s[12:13]
	s_nop 0
	v_pk_fma_f32 v[22:23], v[22:23], s[4:5], v[108:109] op_sel:[0,0,1] op_sel_hi:[1,0,0] neg_lo:[1,0,0] neg_hi:[1,0,0]
	v_pk_add_f32 v[108:109], v[24:25], v[110:111]
	v_pk_add_f32 v[24:25], v[24:25], v[110:111] neg_lo:[0,1] neg_hi:[0,1]
	s_nop 0
	v_pk_mul_f32 v[110:111], v[24:25], s[10:11]
	s_nop 0
	v_pk_fma_f32 v[24:25], v[24:25], s[14:15], v[110:111] op_sel:[0,0,1] op_sel_hi:[1,0,0] neg_lo:[1,0,0] neg_hi:[1,0,0]
	v_pk_add_f32 v[110:111], v[26:27], v[112:113]
	v_pk_add_f32 v[26:27], v[26:27], v[112:113] neg_lo:[0,1] neg_hi:[0,1]
	s_nop 0
	v_pk_mul_f32 v[112:113], v[26:27], s[20:21]
	s_nop 0
	v_pk_fma_f32 v[26:27], v[26:27], s[86:87], v[112:113] op_sel:[0,0,1] op_sel_hi:[1,0,0] neg_lo:[1,0,0] neg_hi:[1,0,0]
	v_pk_add_f32 v[112:113], v[28:29], v[114:115]
	v_pk_add_f32 v[28:29], v[28:29], v[114:115] neg_lo:[0,1] neg_hi:[0,1]
	s_nop 0
	v_pk_mul_f32 v[114:115], v[28:29], s[18:19]
	s_nop 0
	v_pk_fma_f32 v[28:29], v[28:29], s[30:31], v[114:115] op_sel:[0,0,1] op_sel_hi:[1,0,0] neg_lo:[1,0,0] neg_hi:[1,0,0]
	s_waitcnt lgkmcnt(0)
	v_pk_add_f32 v[114:115], v[30:31], v[120:121]
	v_pk_add_f32 v[30:31], v[30:31], v[120:121] neg_lo:[0,1] neg_hi:[0,1]
	s_nop 0
	v_pk_mul_f32 v[120:121], v[30:31], s[16:17]
	s_nop 0
	v_pk_fma_f32 v[30:31], v[30:31], s[6:7], v[120:121] op_sel:[0,0,1] op_sel_hi:[1,0,0] neg_lo:[1,0,0] neg_hi:[1,0,0]
	v_pk_add_f32 v[120:121], v[124:125], v[100:101]
	v_pk_add_f32 v[100:101], v[124:125], v[100:101] neg_lo:[0,1] neg_hi:[0,1]
	v_pk_add_f32 v[124:125], v[86:87], v[102:103]
	v_pk_add_f32 v[86:87], v[86:87], v[102:103] neg_lo:[0,1] neg_hi:[0,1]
	s_nop 0
	v_pk_mul_f32 v[102:103], v[86:87], s[18:19]
	s_nop 0
	v_pk_fma_f32 v[86:87], v[86:87], s[30:31], v[102:103] op_sel:[0,0,1] op_sel_hi:[1,0,0]
	v_pk_add_f32 v[102:103], v[116:117], v[104:105]
	v_pk_add_f32 v[104:105], v[116:117], v[104:105] neg_lo:[0,1] neg_hi:[0,1]
	s_nop 0
	v_pk_mul_f32 v[116:117], v[104:105], s[10:11]
	s_nop 0
	v_pk_fma_f32 v[104:105], v[104:105], s[14:15], v[116:117] op_sel:[0,0,1] op_sel_hi:[1,0,0]
	v_pk_add_f32 v[116:117], v[118:119], v[106:107]
	v_pk_add_f32 v[106:107], v[118:119], v[106:107] neg_lo:[0,1] neg_hi:[0,1]
	s_nop 0
	v_pk_mul_f32 v[118:119], v[106:107], s[34:35]
	s_nop 0
	v_pk_fma_f32 v[106:107], v[106:107], s[8:9], v[118:119] op_sel:[0,0,1] op_sel_hi:[1,0,0]
	v_pk_add_f32 v[118:119], v[92:93], v[108:109]
	v_pk_add_f32 v[92:93], v[92:93], v[108:109] neg_lo:[0,1] neg_hi:[0,1]
	v_pk_add_f32 v[108:109], v[94:95], v[110:111]
	v_pk_add_f32 v[94:95], v[94:95], v[110:111] neg_lo:[0,1] neg_hi:[0,1]
	s_nop 0
	v_pk_mul_f32 v[110:111], v[94:95], s[34:35]
	s_nop 0
	v_pk_fma_f32 v[94:95], v[94:95], s[8:9], v[110:111] op_sel:[0,0,1] op_sel_hi:[1,0,0] neg_lo:[1,0,0] neg_hi:[1,0,0]
	v_pk_add_f32 v[110:111], v[96:97], v[112:113]
	v_pk_add_f32 v[96:97], v[96:97], v[112:113] neg_lo:[0,1] neg_hi:[0,1]
	s_nop 0
	v_pk_mul_f32 v[112:113], v[96:97], s[10:11]
	s_nop 0
	v_pk_fma_f32 v[96:97], v[96:97], s[14:15], v[112:113] op_sel:[0,0,1] op_sel_hi:[1,0,0] neg_lo:[1,0,0] neg_hi:[1,0,0]
	v_pk_add_f32 v[112:113], v[98:99], v[114:115]
	v_pk_add_f32 v[98:99], v[98:99], v[114:115] neg_lo:[0,1] neg_hi:[0,1]
	s_nop 0
	v_pk_mul_f32 v[114:115], v[98:99], s[18:19]
	s_nop 0
	v_pk_fma_f32 v[98:99], v[98:99], s[30:31], v[114:115] op_sel:[0,0,1] op_sel_hi:[1,0,0] neg_lo:[1,0,0] neg_hi:[1,0,0]
	v_pk_add_f32 v[114:115], v[0:1], v[16:17] op_sel:[0,1] op_sel_hi:[1,0] neg_hi:[0,1]
	v_pk_add_f32 v[0:1], v[0:1], v[16:17] op_sel:[0,1] op_sel_hi:[1,0] neg_lo:[0,1]
	v_pk_add_f32 v[16:17], v[2:3], v[18:19]
	v_pk_add_f32 v[2:3], v[2:3], v[18:19] neg_lo:[0,1] neg_hi:[0,1]
	s_nop 0
	v_pk_mul_f32 v[18:19], v[2:3], s[18:19]
	s_nop 0
	v_pk_fma_f32 v[2:3], v[2:3], s[30:31], v[18:19] op_sel:[0,0,1] op_sel_hi:[1,0,0]
	v_pk_add_f32 v[18:19], v[4:5], v[20:21]
	v_pk_add_f32 v[4:5], v[4:5], v[20:21] neg_lo:[0,1] neg_hi:[0,1]
	s_nop 0
	v_pk_mul_f32 v[20:21], v[4:5], s[10:11]
	s_nop 0
	v_pk_fma_f32 v[4:5], v[4:5], s[14:15], v[20:21] op_sel:[0,0,1] op_sel_hi:[1,0,0]
	v_pk_add_f32 v[20:21], v[6:7], v[22:23]
	v_pk_add_f32 v[6:7], v[6:7], v[22:23] neg_lo:[0,1] neg_hi:[0,1]
	s_nop 0
	v_pk_mul_f32 v[22:23], v[6:7], s[34:35]
	s_nop 0
	v_pk_fma_f32 v[6:7], v[6:7], s[8:9], v[22:23] op_sel:[0,0,1] op_sel_hi:[1,0,0]
	v_pk_add_f32 v[22:23], v[8:9], v[24:25]
	v_pk_add_f32 v[8:9], v[8:9], v[24:25] neg_lo:[0,1] neg_hi:[0,1]
	v_pk_add_f32 v[24:25], v[10:11], v[26:27]
	v_pk_add_f32 v[10:11], v[10:11], v[26:27] neg_lo:[0,1] neg_hi:[0,1]
	s_nop 0
	v_pk_mul_f32 v[26:27], v[10:11], s[34:35]
	s_nop 0
	v_pk_fma_f32 v[10:11], v[10:11], s[8:9], v[26:27] op_sel:[0,0,1] op_sel_hi:[1,0,0] neg_lo:[1,0,0] neg_hi:[1,0,0]
	v_pk_add_f32 v[26:27], v[12:13], v[28:29]
	v_pk_add_f32 v[12:13], v[12:13], v[28:29] neg_lo:[0,1] neg_hi:[0,1]
	s_nop 0
	v_pk_mul_f32 v[28:29], v[12:13], s[10:11]
	s_nop 0
	v_pk_fma_f32 v[12:13], v[12:13], s[14:15], v[28:29] op_sel:[0,0,1] op_sel_hi:[1,0,0] neg_lo:[1,0,0] neg_hi:[1,0,0]
	v_pk_add_f32 v[28:29], v[14:15], v[30:31]
	v_pk_add_f32 v[14:15], v[14:15], v[30:31] neg_lo:[0,1] neg_hi:[0,1]
	s_nop 0
	v_pk_mul_f32 v[30:31], v[14:15], s[18:19]
	s_nop 0
	v_pk_fma_f32 v[14:15], v[14:15], s[30:31], v[30:31] op_sel:[0,0,1] op_sel_hi:[1,0,0] neg_lo:[1,0,0] neg_hi:[1,0,0]
	v_pk_add_f32 v[30:31], v[120:121], v[118:119]
	v_pk_add_f32 v[118:119], v[120:121], v[118:119] neg_lo:[0,1] neg_hi:[0,1]
	v_pk_add_f32 v[120:121], v[124:125], v[108:109]
	v_pk_add_f32 v[108:109], v[124:125], v[108:109] neg_lo:[0,1] neg_hi:[0,1]
	s_nop 0
	v_pk_mul_f32 v[124:125], v[108:109], s[10:11]
	s_nop 0
	v_pk_fma_f32 v[108:109], v[108:109], s[14:15], v[124:125] op_sel:[0,0,1] op_sel_hi:[1,0,0]
	v_pk_add_f32 v[124:125], v[102:103], v[110:111]
	v_pk_add_f32 v[102:103], v[102:103], v[110:111] neg_lo:[0,1] neg_hi:[0,1]
	v_pk_add_f32 v[110:111], v[116:117], v[112:113]
	v_pk_add_f32 v[112:113], v[116:117], v[112:113] neg_lo:[0,1] neg_hi:[0,1]
	s_nop 0
	v_pk_mul_f32 v[116:117], v[112:113], s[10:11]
	s_nop 0
	v_pk_fma_f32 v[112:113], v[112:113], s[14:15], v[116:117] op_sel:[0,0,1] op_sel_hi:[1,0,0] neg_lo:[1,0,0] neg_hi:[1,0,0]
	v_pk_add_f32 v[116:117], v[100:101], v[92:93] op_sel:[0,1] op_sel_hi:[1,0] neg_hi:[0,1]
	v_pk_add_f32 v[92:93], v[100:101], v[92:93] op_sel:[0,1] op_sel_hi:[1,0] neg_lo:[0,1]
	v_pk_add_f32 v[100:101], v[86:87], v[94:95]
	v_pk_add_f32 v[86:87], v[86:87], v[94:95] neg_lo:[0,1] neg_hi:[0,1]
	v_pk_add_f32 v[126:127], v[108:109], v[112:113]
	v_pk_mul_f32 v[94:95], v[86:87], s[10:11]
	s_nop 0
	v_pk_fma_f32 v[86:87], v[86:87], s[14:15], v[94:95] op_sel:[0,0,1] op_sel_hi:[1,0,0]
	v_pk_add_f32 v[94:95], v[104:105], v[96:97]
	v_pk_add_f32 v[96:97], v[104:105], v[96:97] neg_lo:[0,1] neg_hi:[0,1]
	v_pk_add_f32 v[104:105], v[106:107], v[98:99]
	v_pk_add_f32 v[98:99], v[106:107], v[98:99] neg_lo:[0,1] neg_hi:[0,1]
	s_nop 0
	v_pk_mul_f32 v[106:107], v[98:99], s[10:11]
	v_pk_add_f32 v[130:131], v[92:93], v[96:97] op_sel:[0,1] op_sel_hi:[1,0] neg_hi:[0,1]
	v_pk_fma_f32 v[98:99], v[98:99], s[14:15], v[106:107] op_sel:[0,0,1] op_sel_hi:[1,0,0] neg_lo:[1,0,0] neg_hi:[1,0,0]
	v_pk_add_f32 v[106:107], v[114:115], v[22:23]
	v_pk_add_f32 v[22:23], v[114:115], v[22:23] neg_lo:[0,1] neg_hi:[0,1]
	v_pk_add_f32 v[114:115], v[16:17], v[24:25]
	v_pk_add_f32 v[16:17], v[16:17], v[24:25] neg_lo:[0,1] neg_hi:[0,1]
	v_pk_add_f32 v[132:133], v[92:93], v[96:97] op_sel:[0,1] op_sel_hi:[1,0] neg_lo:[0,1]
	v_pk_mul_f32 v[24:25], v[16:17], s[10:11]
	v_pk_add_f32 v[92:93], v[86:87], v[98:99]
	v_pk_fma_f32 v[16:17], v[16:17], s[14:15], v[24:25] op_sel:[0,0,1] op_sel_hi:[1,0,0]
	v_pk_add_f32 v[24:25], v[18:19], v[26:27]
	v_pk_add_f32 v[18:19], v[18:19], v[26:27] neg_lo:[0,1] neg_hi:[0,1]
	v_pk_add_f32 v[26:27], v[20:21], v[28:29]
	v_pk_add_f32 v[20:21], v[20:21], v[28:29] neg_lo:[0,1] neg_hi:[0,1]
	s_nop 0
	v_pk_mul_f32 v[28:29], v[20:21], s[10:11]
	v_pk_add_f32 v[86:87], v[86:87], v[98:99] neg_lo:[0,1] neg_hi:[0,1]
	v_pk_fma_f32 v[20:21], v[20:21], s[14:15], v[28:29] op_sel:[0,0,1] op_sel_hi:[1,0,0] neg_lo:[1,0,0] neg_hi:[1,0,0]
	v_pk_add_f32 v[28:29], v[0:1], v[8:9] op_sel:[0,1] op_sel_hi:[1,0] neg_hi:[0,1]
	v_pk_add_f32 v[0:1], v[0:1], v[8:9] op_sel:[0,1] op_sel_hi:[1,0] neg_lo:[0,1]
	v_pk_add_f32 v[8:9], v[2:3], v[10:11]
	v_pk_add_f32 v[2:3], v[2:3], v[10:11] neg_lo:[0,1] neg_hi:[0,1]
	v_pk_add_f32 v[134:135], v[106:107], v[24:25]
	v_pk_mul_f32 v[10:11], v[2:3], s[10:11]
	v_pk_add_f32 v[106:107], v[106:107], v[24:25] neg_lo:[0,1] neg_hi:[0,1]
	v_pk_fma_f32 v[2:3], v[2:3], s[14:15], v[10:11] op_sel:[0,0,1] op_sel_hi:[1,0,0]
	v_pk_add_f32 v[10:11], v[4:5], v[12:13]
	v_pk_add_f32 v[4:5], v[4:5], v[12:13] neg_lo:[0,1] neg_hi:[0,1]
	v_pk_add_f32 v[12:13], v[6:7], v[14:15]
	v_pk_add_f32 v[6:7], v[6:7], v[14:15] neg_lo:[0,1] neg_hi:[0,1]
	s_nop 0
	v_pk_mul_f32 v[14:15], v[6:7], s[10:11]
	v_pk_add_f32 v[24:25], v[114:115], v[26:27] neg_lo:[0,1] neg_hi:[0,1]
	v_pk_fma_f32 v[6:7], v[6:7], s[14:15], v[14:15] op_sel:[0,0,1] op_sel_hi:[1,0,0] neg_lo:[1,0,0] neg_hi:[1,0,0]
	v_pk_add_f32 v[14:15], v[30:31], v[124:125]
	v_pk_add_f32 v[30:31], v[30:31], v[124:125] neg_lo:[0,1] neg_hi:[0,1]
	v_pk_add_f32 v[124:125], v[120:121], v[110:111]
	v_pk_add_f32 v[110:111], v[120:121], v[110:111] neg_lo:[0,1] neg_hi:[0,1]
	v_pk_add_f32 v[120:121], v[118:119], v[102:103] op_sel:[0,1] op_sel_hi:[1,0] neg_hi:[0,1]
	v_pk_add_f32 v[118:119], v[118:119], v[102:103] op_sel:[0,1] op_sel_hi:[1,0] neg_lo:[0,1]
	v_pk_add_f32 v[102:103], v[108:109], v[112:113] neg_lo:[0,1] neg_hi:[0,1]
	v_pk_add_f32 v[112:113], v[116:117], v[94:95]
	v_pk_add_f32 v[94:95], v[116:117], v[94:95] neg_lo:[0,1] neg_hi:[0,1]
	v_pk_add_f32 v[116:117], v[100:101], v[104:105]
	v_pk_add_f32 v[100:101], v[100:101], v[104:105] neg_lo:[0,1] neg_hi:[0,1]
	v_pk_add_f32 v[138:139], v[22:23], v[18:19] op_sel:[0,1] op_sel_hi:[1,0] neg_hi:[0,1]
	v_pk_add_f32 v[140:141], v[22:23], v[18:19] op_sel:[0,1] op_sel_hi:[1,0] neg_lo:[0,1]
	v_pk_add_f32 v[18:19], v[16:17], v[20:21]
	v_pk_add_f32 v[16:17], v[16:17], v[20:21] neg_lo:[0,1] neg_hi:[0,1]
	v_pk_add_f32 v[144:145], v[28:29], v[10:11]
	v_pk_add_f32 v[158:159], v[28:29], v[10:11] neg_lo:[0,1] neg_hi:[0,1]
	v_pk_add_f32 v[10:11], v[8:9], v[12:13]
	v_pk_add_f32 v[8:9], v[8:9], v[12:13] neg_lo:[0,1] neg_hi:[0,1]
	v_pk_add_f32 v[162:163], v[0:1], v[4:5] op_sel:[0,1] op_sel_hi:[1,0] neg_hi:[0,1]
	v_pk_add_f32 v[164:165], v[0:1], v[4:5] op_sel:[0,1] op_sel_hi:[1,0] neg_lo:[0,1]
	v_pk_add_f32 v[0:1], v[2:3], v[6:7] neg_lo:[0,1] neg_hi:[0,1]
	v_pk_mul_f32 v[108:109], v[102:103], s[22:23]
	v_pk_mul_f32 v[128:129], v[100:101], s[22:23]
	v_pk_add_f32 v[136:137], v[114:115], v[26:27]
	v_pk_mul_f32 v[114:115], v[24:25], s[22:23]
	v_pk_mul_f32 v[142:143], v[16:17], s[22:23]
	v_pk_mul_f32 v[160:161], v[8:9], s[22:23]
	v_pk_add_f32 v[166:167], v[2:3], v[6:7]
	v_pk_mul_f32 v[168:169], v[0:1], s[22:23]
	v_pk_add_f32 v[28:29], v[14:15], v[124:125]
	v_pk_add_f32 v[104:105], v[14:15], v[124:125] neg_lo:[0,1] neg_hi:[0,1]
	v_pk_add_f32 v[24:25], v[30:31], v[110:111] op_sel:[0,1] op_sel_hi:[1,0] neg_hi:[0,1]
	v_pk_add_f32 v[102:103], v[30:31], v[110:111] op_sel:[0,1] op_sel_hi:[1,0] neg_lo:[0,1]
	v_pk_add_f32 v[20:21], v[120:121], v[126:127]
	v_pk_add_f32 v[100:101], v[120:121], v[126:127] neg_lo:[0,1] neg_hi:[0,1]
	v_pk_add_f32 v[16:17], v[118:119], v[108:109] op_sel:[0,1] op_sel_hi:[1,0]
	v_pk_add_f32 v[98:99], v[118:119], v[108:109] op_sel:[0,1] op_sel_hi:[1,0] neg_lo:[0,1] neg_hi:[0,1]
	v_pk_add_f32 v[12:13], v[112:113], v[116:117]
	v_pk_add_f32 v[96:97], v[112:113], v[116:117] neg_lo:[0,1] neg_hi:[0,1]
	v_pk_add_f32 v[8:9], v[94:95], v[128:129] op_sel:[0,1] op_sel_hi:[1,0]
	v_pk_add_f32 v[94:95], v[94:95], v[128:129] op_sel:[0,1] op_sel_hi:[1,0] neg_lo:[0,1] neg_hi:[0,1]
	v_pk_add_f32 v[4:5], v[130:131], v[92:93]
	v_pk_add_f32 v[92:93], v[130:131], v[92:93] neg_lo:[0,1] neg_hi:[0,1]
	v_pk_add_f32 v[0:1], v[132:133], v[86:87] op_sel:[0,1] op_sel_hi:[1,0] neg_hi:[0,1]
	v_pk_add_f32 v[86:87], v[132:133], v[86:87] op_sel:[0,1] op_sel_hi:[1,0] neg_lo:[0,1]
	v_pk_add_f32 v[30:31], v[134:135], v[136:137]
	v_pk_add_f32 v[120:121], v[134:135], v[136:137] neg_lo:[0,1] neg_hi:[0,1]
	v_pk_add_f32 v[26:27], v[106:107], v[114:115] op_sel:[0,1] op_sel_hi:[1,0]
	v_pk_add_f32 v[118:119], v[106:107], v[114:115] op_sel:[0,1] op_sel_hi:[1,0] neg_lo:[0,1] neg_hi:[0,1]
	v_pk_add_f32 v[22:23], v[138:139], v[18:19]
	v_pk_add_f32 v[116:117], v[138:139], v[18:19] neg_lo:[0,1] neg_hi:[0,1]
	v_pk_add_f32 v[18:19], v[140:141], v[142:143] op_sel:[0,1] op_sel_hi:[1,0]
	v_pk_add_f32 v[114:115], v[140:141], v[142:143] op_sel:[0,1] op_sel_hi:[1,0] neg_lo:[0,1] neg_hi:[0,1]
	v_pk_add_f32 v[14:15], v[144:145], v[10:11]
	v_pk_add_f32 v[112:113], v[144:145], v[10:11] neg_lo:[0,1] neg_hi:[0,1]
	v_pk_add_f32 v[10:11], v[158:159], v[160:161] op_sel:[0,1] op_sel_hi:[1,0]
	v_pk_add_f32 v[110:111], v[158:159], v[160:161] op_sel:[0,1] op_sel_hi:[1,0] neg_lo:[0,1] neg_hi:[0,1]
	v_pk_add_f32 v[6:7], v[162:163], v[166:167]
	v_pk_add_f32 v[108:109], v[162:163], v[166:167] neg_lo:[0,1] neg_hi:[0,1]
	v_pk_add_f32 v[2:3], v[164:165], v[168:169] op_sel:[0,1] op_sel_hi:[1,0]
	v_pk_add_f32 v[106:107], v[164:165], v[168:169] op_sel:[0,1] op_sel_hi:[1,0] neg_lo:[0,1] neg_hi:[0,1]

.LBB0_665:
	s_or_b64 exec, exec, s[4:5]
	ds_write2_b64 v152, v[92:93], v[86:87] offset1:1
	ds_write2_b64 v152, v[76:77], v[70:71] offset0:2 offset1:3
	ds_write2_b64 v152, v[90:91], v[82:83] offset0:4 offset1:5
	ds_write2_b64 v152, v[74:75], v[66:67] offset0:6 offset1:7
	ds_write2_b64 v152, v[88:89], v[80:81] offset0:8 offset1:9
	ds_write2_b64 v152, v[72:73], v[64:65] offset0:10 offset1:11
	ds_write2_b64 v152, v[84:85], v[78:79] offset0:12 offset1:13
	ds_write2_b64 v152, v[68:69], v[62:63] offset0:14 offset1:15
	s_waitcnt lgkmcnt(0)
	s_barrier
	s_and_saveexec_b64 s[28:29], s[40:41]
	s_cbranch_execz .LBB0_667
	ds_read_b64 v[0:1], v153
	ds_read_b64 v[2:3], v153 offset:2176
	ds_read_b64 v[4:5], v153 offset:4352
	ds_read_b64 v[6:7], v153 offset:6528
	ds_read_b64 v[8:9], v153 offset:8704
	ds_read_b64 v[10:11], v153 offset:10880
	ds_read_b64 v[12:13], v153 offset:13056
	ds_read_b64 v[14:15], v153 offset:15232
	ds_read_b64 v[16:17], v153 offset:17408
	ds_read_b64 v[18:19], v153 offset:19584
	ds_read_b64 v[20:21], v153 offset:21760
	ds_read_b64 v[22:23], v153 offset:23936
	ds_read_b64 v[24:25], v153 offset:26112
	ds_read_b64 v[26:27], v153 offset:28288
	ds_read_b64 v[28:29], v153 offset:30464
	ds_read_b64 v[30:31], v153 offset:32640
	ds_read_b64 v[58:59], v153 offset:34816
	ds_read_b64 v[60:61], v153 offset:41344
	ds_read_b64 v[94:95], v153 offset:43520
	ds_read_b64 v[96:97], v153 offset:45696
	ds_read_b64 v[98:99], v153 offset:47872
	ds_read_b64 v[100:101], v153 offset:50048
	ds_read_b64 v[102:103], v153 offset:52224
	ds_read_b64 v[104:105], v153 offset:54400
	ds_read_b64 v[106:107], v153 offset:56576
	ds_read_b64 v[108:109], v153 offset:58752
	ds_read_b64 v[110:111], v153 offset:60928
	ds_read_b64 v[112:113], v153 offset:63104
	ds_read_b64 v[114:115], v153 offset:65280
	ds_read_b64 v[116:117], v153 offset:36992
	ds_read_b64 v[118:119], v153 offset:39168
	ds_read_b64 v[120:121], v33
	s_waitcnt lgkmcnt(14)
	v_pk_add_f32 v[124:125], v[0:1], v[58:59]
	v_pk_add_f32 v[0:1], v[0:1], v[58:59] neg_lo:[0,1] neg_hi:[0,1]
	s_waitcnt lgkmcnt(2)
	v_pk_add_f32 v[58:59], v[2:3], v[116:117]
	v_pk_add_f32 v[2:3], v[2:3], v[116:117] neg_lo:[0,1] neg_hi:[0,1]
	s_mov_b32 s11, s14
	v_pk_mul_f32 v[116:117], v[2:3], s[16:17]
	s_mov_b32 s13, s86
	v_pk_fma_f32 v[2:3], v[2:3], s[6:7], v[116:117] op_sel:[0,0,1] op_sel_hi:[1,0,0]
	s_waitcnt lgkmcnt(1)
	v_pk_add_f32 v[116:117], v[4:5], v[118:119]
	v_pk_add_f32 v[4:5], v[4:5], v[118:119] neg_lo:[0,1] neg_hi:[0,1]
	s_mov_b32 s4, s21
	v_pk_mul_f32 v[118:119], v[4:5], s[18:19]
	s_mov_b32 s35, s30
	v_pk_fma_f32 v[4:5], v[4:5], s[30:31], v[118:119] op_sel:[0,0,1] op_sel_hi:[1,0,0]
	v_pk_add_f32 v[118:119], v[6:7], v[60:61]
	v_pk_add_f32 v[6:7], v[6:7], v[60:61] neg_lo:[0,1] neg_hi:[0,1]
	s_mov_b32 s8, s19
	v_pk_mul_f32 v[60:61], v[6:7], s[20:21]
	s_mov_b32 s77, s6
	v_pk_fma_f32 v[6:7], v[6:7], s[86:87], v[60:61] op_sel:[0,0,1] op_sel_hi:[1,0,0]
	v_pk_add_f32 v[60:61], v[8:9], v[94:95]
	v_pk_add_f32 v[8:9], v[8:9], v[94:95] neg_lo:[0,1] neg_hi:[0,1]
	s_mov_b32 s26, s17
	v_pk_mul_f32 v[94:95], v[8:9], s[10:11]
	s_nop 0
	v_pk_fma_f32 v[8:9], v[8:9], s[14:15], v[94:95] op_sel:[0,0,1] op_sel_hi:[1,0,0]
	v_pk_add_f32 v[94:95], v[10:11], v[96:97]
	v_pk_add_f32 v[10:11], v[10:11], v[96:97] neg_lo:[0,1] neg_hi:[0,1]
	s_nop 0
	v_pk_mul_f32 v[96:97], v[10:11], s[12:13]
	s_nop 0
	v_pk_fma_f32 v[10:11], v[10:11], s[4:5], v[96:97] op_sel:[0,0,1] op_sel_hi:[1,0,0]
	v_pk_add_f32 v[96:97], v[12:13], v[98:99]
	v_pk_add_f32 v[12:13], v[12:13], v[98:99] neg_lo:[0,1] neg_hi:[0,1]
	s_nop 0
	v_pk_mul_f32 v[98:99], v[12:13], s[34:35]
	s_nop 0
	v_pk_fma_f32 v[12:13], v[12:13], s[8:9], v[98:99] op_sel:[0,0,1] op_sel_hi:[1,0,0]
	v_pk_add_f32 v[98:99], v[14:15], v[100:101]
	v_pk_add_f32 v[14:15], v[14:15], v[100:101] neg_lo:[0,1] neg_hi:[0,1]
	s_nop 0
	v_pk_mul_f32 v[100:101], v[14:15], s[76:77]
	s_nop 0
	v_pk_fma_f32 v[14:15], v[14:15], s[26:27], v[100:101] op_sel:[0,0,1] op_sel_hi:[1,0,0]
	v_pk_add_f32 v[100:101], v[16:17], v[102:103]
	v_pk_add_f32 v[16:17], v[16:17], v[102:103] neg_lo:[0,1] neg_hi:[0,1]
	v_pk_add_f32 v[102:103], v[18:19], v[104:105]
	v_pk_add_f32 v[18:19], v[18:19], v[104:105] neg_lo:[0,1] neg_hi:[0,1]
	s_nop 0
	v_pk_mul_f32 v[104:105], v[18:19], s[76:77]
	s_nop 0
	v_pk_fma_f32 v[18:19], v[18:19], s[26:27], v[104:105] op_sel:[0,0,1] op_sel_hi:[1,0,0] neg_lo:[1,0,0] neg_hi:[1,0,0]
	v_pk_add_f32 v[104:105], v[20:21], v[106:107]
	v_pk_add_f32 v[20:21], v[20:21], v[106:107] neg_lo:[0,1] neg_hi:[0,1]
	s_nop 0
	v_pk_mul_f32 v[106:107], v[20:21], s[34:35]
	s_nop 0
	v_pk_fma_f32 v[20:21], v[20:21], s[8:9], v[106:107] op_sel:[0,0,1] op_sel_hi:[1,0,0] neg_lo:[1,0,0] neg_hi:[1,0,0]
	v_pk_add_f32 v[106:107], v[22:23], v[108:109]
	v_pk_add_f32 v[22:23], v[22:23], v[108:109] neg_lo:[0,1] neg_hi:[0,1]
	s_nop 0
	v_pk_mul_f32 v[108:109], v[22:23], s[12:13]
	s_nop 0
	v_pk_fma_f32 v[22:23], v[22:23], s[4:5], v[108:109] op_sel:[0,0,1] op_sel_hi:[1,0,0] neg_lo:[1,0,0] neg_hi:[1,0,0]
	v_pk_add_f32 v[108:109], v[24:25], v[110:111]
	v_pk_add_f32 v[24:25], v[24:25], v[110:111] neg_lo:[0,1] neg_hi:[0,1]
	s_nop 0
	v_pk_mul_f32 v[110:111], v[24:25], s[10:11]
	s_nop 0
	v_pk_fma_f32 v[24:25], v[24:25], s[14:15], v[110:111] op_sel:[0,0,1] op_sel_hi:[1,0,0] neg_lo:[1,0,0] neg_hi:[1,0,0]
	v_pk_add_f32 v[110:111], v[26:27], v[112:113]
	v_pk_add_f32 v[26:27], v[26:27], v[112:113] neg_lo:[0,1] neg_hi:[0,1]
	s_nop 0
	v_pk_mul_f32 v[112:113], v[26:27], s[20:21]
	s_nop 0
	v_pk_fma_f32 v[26:27], v[26:27], s[86:87], v[112:113] op_sel:[0,0,1] op_sel_hi:[1,0,0] neg_lo:[1,0,0] neg_hi:[1,0,0]
	v_pk_add_f32 v[112:113], v[28:29], v[114:115]
	v_pk_add_f32 v[28:29], v[28:29], v[114:115] neg_lo:[0,1] neg_hi:[0,1]
	s_nop 0
	v_pk_mul_f32 v[114:115], v[28:29], s[18:19]
	s_nop 0
	v_pk_fma_f32 v[28:29], v[28:29], s[30:31], v[114:115] op_sel:[0,0,1] op_sel_hi:[1,0,0] neg_lo:[1,0,0] neg_hi:[1,0,0]
	s_waitcnt lgkmcnt(0)
	v_pk_add_f32 v[114:115], v[30:31], v[120:121]
	v_pk_add_f32 v[30:31], v[30:31], v[120:121] neg_lo:[0,1] neg_hi:[0,1]
	s_nop 0
	v_pk_mul_f32 v[120:121], v[30:31], s[16:17]
	s_nop 0
	v_pk_fma_f32 v[30:31], v[30:31], s[6:7], v[120:121] op_sel:[0,0,1] op_sel_hi:[1,0,0] neg_lo:[1,0,0] neg_hi:[1,0,0]
	v_pk_add_f32 v[120:121], v[124:125], v[100:101]
	v_pk_add_f32 v[100:101], v[124:125], v[100:101] neg_lo:[0,1] neg_hi:[0,1]
	v_pk_add_f32 v[124:125], v[58:59], v[102:103]
	v_pk_add_f32 v[58:59], v[58:59], v[102:103] neg_lo:[0,1] neg_hi:[0,1]
	s_nop 0
	v_pk_mul_f32 v[102:103], v[58:59], s[18:19]
	s_nop 0
	v_pk_fma_f32 v[58:59], v[58:59], s[30:31], v[102:103] op_sel:[0,0,1] op_sel_hi:[1,0,0]
	v_pk_add_f32 v[102:103], v[116:117], v[104:105]
	v_pk_add_f32 v[104:105], v[116:117], v[104:105] neg_lo:[0,1] neg_hi:[0,1]
	s_nop 0
	v_pk_mul_f32 v[116:117], v[104:105], s[10:11]
	s_nop 0
	v_pk_fma_f32 v[104:105], v[104:105], s[14:15], v[116:117] op_sel:[0,0,1] op_sel_hi:[1,0,0]
	v_pk_add_f32 v[116:117], v[118:119], v[106:107]
	v_pk_add_f32 v[106:107], v[118:119], v[106:107] neg_lo:[0,1] neg_hi:[0,1]
	s_nop 0
	v_pk_mul_f32 v[118:119], v[106:107], s[34:35]
	s_nop 0
	v_pk_fma_f32 v[106:107], v[106:107], s[8:9], v[118:119] op_sel:[0,0,1] op_sel_hi:[1,0,0]
	v_pk_add_f32 v[118:119], v[60:61], v[108:109]
	v_pk_add_f32 v[60:61], v[60:61], v[108:109] neg_lo:[0,1] neg_hi:[0,1]
	v_pk_add_f32 v[108:109], v[94:95], v[110:111]
	v_pk_add_f32 v[94:95], v[94:95], v[110:111] neg_lo:[0,1] neg_hi:[0,1]
	s_nop 0
	v_pk_mul_f32 v[110:111], v[94:95], s[34:35]
	s_nop 0
	v_pk_fma_f32 v[94:95], v[94:95], s[8:9], v[110:111] op_sel:[0,0,1] op_sel_hi:[1,0,0] neg_lo:[1,0,0] neg_hi:[1,0,0]
	v_pk_add_f32 v[110:111], v[96:97], v[112:113]
	v_pk_add_f32 v[96:97], v[96:97], v[112:113] neg_lo:[0,1] neg_hi:[0,1]
	s_nop 0
	v_pk_mul_f32 v[112:113], v[96:97], s[10:11]
	s_nop 0
	v_pk_fma_f32 v[96:97], v[96:97], s[14:15], v[112:113] op_sel:[0,0,1] op_sel_hi:[1,0,0] neg_lo:[1,0,0] neg_hi:[1,0,0]
	v_pk_add_f32 v[112:113], v[98:99], v[114:115]
	v_pk_add_f32 v[98:99], v[98:99], v[114:115] neg_lo:[0,1] neg_hi:[0,1]
	s_nop 0
	v_pk_mul_f32 v[114:115], v[98:99], s[18:19]
	s_nop 0
	v_pk_fma_f32 v[98:99], v[98:99], s[30:31], v[114:115] op_sel:[0,0,1] op_sel_hi:[1,0,0] neg_lo:[1,0,0] neg_hi:[1,0,0]
	v_pk_add_f32 v[114:115], v[0:1], v[16:17] op_sel:[0,1] op_sel_hi:[1,0] neg_hi:[0,1]
	v_pk_add_f32 v[0:1], v[0:1], v[16:17] op_sel:[0,1] op_sel_hi:[1,0] neg_lo:[0,1]
	v_pk_add_f32 v[16:17], v[2:3], v[18:19]
	v_pk_add_f32 v[2:3], v[2:3], v[18:19] neg_lo:[0,1] neg_hi:[0,1]
	s_nop 0
	v_pk_mul_f32 v[18:19], v[2:3], s[18:19]
	s_nop 0
	v_pk_fma_f32 v[2:3], v[2:3], s[30:31], v[18:19] op_sel:[0,0,1] op_sel_hi:[1,0,0]
	v_pk_add_f32 v[18:19], v[4:5], v[20:21]
	v_pk_add_f32 v[4:5], v[4:5], v[20:21] neg_lo:[0,1] neg_hi:[0,1]
	s_nop 0
	v_pk_mul_f32 v[20:21], v[4:5], s[10:11]
	s_nop 0
	v_pk_fma_f32 v[4:5], v[4:5], s[14:15], v[20:21] op_sel:[0,0,1] op_sel_hi:[1,0,0]
	v_pk_add_f32 v[20:21], v[6:7], v[22:23]
	v_pk_add_f32 v[6:7], v[6:7], v[22:23] neg_lo:[0,1] neg_hi:[0,1]
	s_nop 0
	v_pk_mul_f32 v[22:23], v[6:7], s[34:35]
	s_nop 0
	v_pk_fma_f32 v[6:7], v[6:7], s[8:9], v[22:23] op_sel:[0,0,1] op_sel_hi:[1,0,0]
	v_pk_add_f32 v[22:23], v[8:9], v[24:25]
	v_pk_add_f32 v[8:9], v[8:9], v[24:25] neg_lo:[0,1] neg_hi:[0,1]
	v_pk_add_f32 v[24:25], v[10:11], v[26:27]
	v_pk_add_f32 v[10:11], v[10:11], v[26:27] neg_lo:[0,1] neg_hi:[0,1]
	s_nop 0
	v_pk_mul_f32 v[26:27], v[10:11], s[34:35]
	s_nop 0
	v_pk_fma_f32 v[10:11], v[10:11], s[8:9], v[26:27] op_sel:[0,0,1] op_sel_hi:[1,0,0] neg_lo:[1,0,0] neg_hi:[1,0,0]
	v_pk_add_f32 v[26:27], v[12:13], v[28:29]
	v_pk_add_f32 v[12:13], v[12:13], v[28:29] neg_lo:[0,1] neg_hi:[0,1]
	s_nop 0
	v_pk_mul_f32 v[28:29], v[12:13], s[10:11]
	s_nop 0
	v_pk_fma_f32 v[12:13], v[12:13], s[14:15], v[28:29] op_sel:[0,0,1] op_sel_hi:[1,0,0] neg_lo:[1,0,0] neg_hi:[1,0,0]
	v_pk_add_f32 v[28:29], v[14:15], v[30:31]
	v_pk_add_f32 v[14:15], v[14:15], v[30:31] neg_lo:[0,1] neg_hi:[0,1]
	s_nop 0
	v_pk_mul_f32 v[30:31], v[14:15], s[18:19]
	s_nop 0
	v_pk_fma_f32 v[14:15], v[14:15], s[30:31], v[30:31] op_sel:[0,0,1] op_sel_hi:[1,0,0] neg_lo:[1,0,0] neg_hi:[1,0,0]
	v_pk_add_f32 v[30:31], v[120:121], v[118:119]
	v_pk_add_f32 v[118:119], v[120:121], v[118:119] neg_lo:[0,1] neg_hi:[0,1]
	v_pk_add_f32 v[120:121], v[124:125], v[108:109]
	v_pk_add_f32 v[108:109], v[124:125], v[108:109] neg_lo:[0,1] neg_hi:[0,1]
	s_nop 0
	v_pk_mul_f32 v[124:125], v[108:109], s[10:11]
	s_nop 0
	v_pk_fma_f32 v[108:109], v[108:109], s[14:15], v[124:125] op_sel:[0,0,1] op_sel_hi:[1,0,0]
	v_pk_add_f32 v[124:125], v[102:103], v[110:111]
	v_pk_add_f32 v[102:103], v[102:103], v[110:111] neg_lo:[0,1] neg_hi:[0,1]
	v_pk_add_f32 v[110:111], v[116:117], v[112:113]
	v_pk_add_f32 v[112:113], v[116:117], v[112:113] neg_lo:[0,1] neg_hi:[0,1]
	s_nop 0
	v_pk_mul_f32 v[116:117], v[112:113], s[10:11]
	s_nop 0
	v_pk_fma_f32 v[112:113], v[112:113], s[14:15], v[116:117] op_sel:[0,0,1] op_sel_hi:[1,0,0] neg_lo:[1,0,0] neg_hi:[1,0,0]
	v_pk_add_f32 v[116:117], v[100:101], v[60:61] op_sel:[0,1] op_sel_hi:[1,0] neg_hi:[0,1]
	v_pk_add_f32 v[60:61], v[100:101], v[60:61] op_sel:[0,1] op_sel_hi:[1,0] neg_lo:[0,1]
	v_pk_add_f32 v[100:101], v[58:59], v[94:95]
	v_pk_add_f32 v[58:59], v[58:59], v[94:95] neg_lo:[0,1] neg_hi:[0,1]
	v_pk_add_f32 v[126:127], v[108:109], v[112:113]
	v_pk_mul_f32 v[94:95], v[58:59], s[10:11]
	s_nop 0
	v_pk_fma_f32 v[58:59], v[58:59], s[14:15], v[94:95] op_sel:[0,0,1] op_sel_hi:[1,0,0]
	v_pk_add_f32 v[94:95], v[104:105], v[96:97]
	v_pk_add_f32 v[96:97], v[104:105], v[96:97] neg_lo:[0,1] neg_hi:[0,1]
	v_pk_add_f32 v[104:105], v[106:107], v[98:99]
	v_pk_add_f32 v[98:99], v[106:107], v[98:99] neg_lo:[0,1] neg_hi:[0,1]
	s_nop 0
	v_pk_mul_f32 v[106:107], v[98:99], s[10:11]
	v_pk_add_f32 v[130:131], v[60:61], v[96:97] op_sel:[0,1] op_sel_hi:[1,0] neg_hi:[0,1]
	v_pk_fma_f32 v[98:99], v[98:99], s[14:15], v[106:107] op_sel:[0,0,1] op_sel_hi:[1,0,0] neg_lo:[1,0,0] neg_hi:[1,0,0]
	v_pk_add_f32 v[106:107], v[114:115], v[22:23]
	v_pk_add_f32 v[22:23], v[114:115], v[22:23] neg_lo:[0,1] neg_hi:[0,1]
	v_pk_add_f32 v[114:115], v[16:17], v[24:25]
	v_pk_add_f32 v[16:17], v[16:17], v[24:25] neg_lo:[0,1] neg_hi:[0,1]
	v_pk_add_f32 v[132:133], v[60:61], v[96:97] op_sel:[0,1] op_sel_hi:[1,0] neg_lo:[0,1]
	v_pk_mul_f32 v[24:25], v[16:17], s[10:11]
	v_pk_add_f32 v[60:61], v[58:59], v[98:99]
	v_pk_fma_f32 v[16:17], v[16:17], s[14:15], v[24:25] op_sel:[0,0,1] op_sel_hi:[1,0,0]
	v_pk_add_f32 v[24:25], v[18:19], v[26:27]
	v_pk_add_f32 v[18:19], v[18:19], v[26:27] neg_lo:[0,1] neg_hi:[0,1]
	v_pk_add_f32 v[26:27], v[20:21], v[28:29]
	v_pk_add_f32 v[20:21], v[20:21], v[28:29] neg_lo:[0,1] neg_hi:[0,1]
	s_nop 0
	v_pk_mul_f32 v[28:29], v[20:21], s[10:11]
	v_pk_add_f32 v[58:59], v[58:59], v[98:99] neg_lo:[0,1] neg_hi:[0,1]
	v_pk_fma_f32 v[20:21], v[20:21], s[14:15], v[28:29] op_sel:[0,0,1] op_sel_hi:[1,0,0] neg_lo:[1,0,0] neg_hi:[1,0,0]
	v_pk_add_f32 v[28:29], v[0:1], v[8:9] op_sel:[0,1] op_sel_hi:[1,0] neg_hi:[0,1]
	v_pk_add_f32 v[0:1], v[0:1], v[8:9] op_sel:[0,1] op_sel_hi:[1,0] neg_lo:[0,1]
	v_pk_add_f32 v[8:9], v[2:3], v[10:11]
	v_pk_add_f32 v[2:3], v[2:3], v[10:11] neg_lo:[0,1] neg_hi:[0,1]
	v_pk_add_f32 v[134:135], v[106:107], v[24:25]
	v_pk_mul_f32 v[10:11], v[2:3], s[10:11]
	v_pk_add_f32 v[106:107], v[106:107], v[24:25] neg_lo:[0,1] neg_hi:[0,1]
	v_pk_fma_f32 v[2:3], v[2:3], s[14:15], v[10:11] op_sel:[0,0,1] op_sel_hi:[1,0,0]
	v_pk_add_f32 v[10:11], v[4:5], v[12:13]
	v_pk_add_f32 v[4:5], v[4:5], v[12:13] neg_lo:[0,1] neg_hi:[0,1]
	v_pk_add_f32 v[12:13], v[6:7], v[14:15]
	v_pk_add_f32 v[6:7], v[6:7], v[14:15] neg_lo:[0,1] neg_hi:[0,1]
	s_nop 0
	v_pk_mul_f32 v[14:15], v[6:7], s[10:11]
	v_pk_add_f32 v[24:25], v[114:115], v[26:27] neg_lo:[0,1] neg_hi:[0,1]
	v_pk_fma_f32 v[6:7], v[6:7], s[14:15], v[14:15] op_sel:[0,0,1] op_sel_hi:[1,0,0] neg_lo:[1,0,0] neg_hi:[1,0,0]
	v_pk_add_f32 v[14:15], v[30:31], v[124:125]
	v_pk_add_f32 v[30:31], v[30:31], v[124:125] neg_lo:[0,1] neg_hi:[0,1]
	v_pk_add_f32 v[124:125], v[120:121], v[110:111]
	v_pk_add_f32 v[110:111], v[120:121], v[110:111] neg_lo:[0,1] neg_hi:[0,1]
	v_pk_add_f32 v[120:121], v[118:119], v[102:103] op_sel:[0,1] op_sel_hi:[1,0] neg_hi:[0,1]
	v_pk_add_f32 v[118:119], v[118:119], v[102:103] op_sel:[0,1] op_sel_hi:[1,0] neg_lo:[0,1]
	v_pk_add_f32 v[102:103], v[108:109], v[112:113] neg_lo:[0,1] neg_hi:[0,1]
	v_pk_add_f32 v[112:113], v[116:117], v[94:95]
	v_pk_add_f32 v[94:95], v[116:117], v[94:95] neg_lo:[0,1] neg_hi:[0,1]
	v_pk_add_f32 v[116:117], v[100:101], v[104:105]
	v_pk_add_f32 v[100:101], v[100:101], v[104:105] neg_lo:[0,1] neg_hi:[0,1]
	v_pk_add_f32 v[138:139], v[22:23], v[18:19] op_sel:[0,1] op_sel_hi:[1,0] neg_hi:[0,1]
	v_pk_add_f32 v[140:141], v[22:23], v[18:19] op_sel:[0,1] op_sel_hi:[1,0] neg_lo:[0,1]
	v_pk_add_f32 v[18:19], v[16:17], v[20:21]
	v_pk_add_f32 v[16:17], v[16:17], v[20:21] neg_lo:[0,1] neg_hi:[0,1]
	v_pk_add_f32 v[144:145], v[28:29], v[10:11]
	v_pk_add_f32 v[158:159], v[28:29], v[10:11] neg_lo:[0,1] neg_hi:[0,1]
	v_pk_add_f32 v[10:11], v[8:9], v[12:13]
	v_pk_add_f32 v[8:9], v[8:9], v[12:13] neg_lo:[0,1] neg_hi:[0,1]
	v_pk_add_f32 v[162:163], v[0:1], v[4:5] op_sel:[0,1] op_sel_hi:[1,0] neg_hi:[0,1]
	v_pk_add_f32 v[164:165], v[0:1], v[4:5] op_sel:[0,1] op_sel_hi:[1,0] neg_lo:[0,1]
	v_pk_add_f32 v[0:1], v[2:3], v[6:7] neg_lo:[0,1] neg_hi:[0,1]
	v_pk_mul_f32 v[108:109], v[102:103], s[22:23]
	v_pk_mul_f32 v[128:129], v[100:101], s[22:23]
	v_pk_add_f32 v[136:137], v[114:115], v[26:27]
	v_pk_mul_f32 v[114:115], v[24:25], s[22:23]
	v_pk_mul_f32 v[142:143], v[16:17], s[22:23]
	v_pk_mul_f32 v[160:161], v[8:9], s[22:23]
	v_pk_add_f32 v[166:167], v[2:3], v[6:7]
	v_pk_mul_f32 v[168:169], v[0:1], s[22:23]
	v_pk_add_f32 v[28:29], v[14:15], v[124:125]
	v_pk_add_f32 v[104:105], v[14:15], v[124:125] neg_lo:[0,1] neg_hi:[0,1]
	v_pk_add_f32 v[24:25], v[30:31], v[110:111] op_sel:[0,1] op_sel_hi:[1,0] neg_hi:[0,1]
	v_pk_add_f32 v[102:103], v[30:31], v[110:111] op_sel:[0,1] op_sel_hi:[1,0] neg_lo:[0,1]
	v_pk_add_f32 v[20:21], v[120:121], v[126:127]
	v_pk_add_f32 v[100:101], v[120:121], v[126:127] neg_lo:[0,1] neg_hi:[0,1]
	v_pk_add_f32 v[16:17], v[118:119], v[108:109] op_sel:[0,1] op_sel_hi:[1,0]
	v_pk_add_f32 v[98:99], v[118:119], v[108:109] op_sel:[0,1] op_sel_hi:[1,0] neg_lo:[0,1] neg_hi:[0,1]
	v_pk_add_f32 v[12:13], v[112:113], v[116:117]
	v_pk_add_f32 v[96:97], v[112:113], v[116:117] neg_lo:[0,1] neg_hi:[0,1]
	v_pk_add_f32 v[8:9], v[94:95], v[128:129] op_sel:[0,1] op_sel_hi:[1,0]
	v_pk_add_f32 v[94:95], v[94:95], v[128:129] op_sel:[0,1] op_sel_hi:[1,0] neg_lo:[0,1] neg_hi:[0,1]
	v_pk_add_f32 v[4:5], v[130:131], v[60:61]
	v_pk_add_f32 v[60:61], v[130:131], v[60:61] neg_lo:[0,1] neg_hi:[0,1]
	v_pk_add_f32 v[0:1], v[132:133], v[58:59] op_sel:[0,1] op_sel_hi:[1,0] neg_hi:[0,1]
	v_pk_add_f32 v[58:59], v[132:133], v[58:59] op_sel:[0,1] op_sel_hi:[1,0] neg_lo:[0,1]
	v_pk_add_f32 v[30:31], v[134:135], v[136:137]
	v_pk_add_f32 v[120:121], v[134:135], v[136:137] neg_lo:[0,1] neg_hi:[0,1]
	v_pk_add_f32 v[26:27], v[106:107], v[114:115] op_sel:[0,1] op_sel_hi:[1,0]
	v_pk_add_f32 v[118:119], v[106:107], v[114:115] op_sel:[0,1] op_sel_hi:[1,0] neg_lo:[0,1] neg_hi:[0,1]
	v_pk_add_f32 v[22:23], v[138:139], v[18:19]
	v_pk_add_f32 v[116:117], v[138:139], v[18:19] neg_lo:[0,1] neg_hi:[0,1]
	v_pk_add_f32 v[18:19], v[140:141], v[142:143] op_sel:[0,1] op_sel_hi:[1,0]
	v_pk_add_f32 v[114:115], v[140:141], v[142:143] op_sel:[0,1] op_sel_hi:[1,0] neg_lo:[0,1] neg_hi:[0,1]
	v_pk_add_f32 v[14:15], v[144:145], v[10:11]
	v_pk_add_f32 v[112:113], v[144:145], v[10:11] neg_lo:[0,1] neg_hi:[0,1]
	v_pk_add_f32 v[10:11], v[158:159], v[160:161] op_sel:[0,1] op_sel_hi:[1,0]
	v_pk_add_f32 v[110:111], v[158:159], v[160:161] op_sel:[0,1] op_sel_hi:[1,0] neg_lo:[0,1] neg_hi:[0,1]
	v_pk_add_f32 v[6:7], v[162:163], v[166:167]
	v_pk_add_f32 v[108:109], v[162:163], v[166:167] neg_lo:[0,1] neg_hi:[0,1]
	v_pk_add_f32 v[2:3], v[164:165], v[168:169] op_sel:[0,1] op_sel_hi:[1,0]
	v_pk_add_f32 v[106:107], v[164:165], v[168:169] op_sel:[0,1] op_sel_hi:[1,0] neg_lo:[0,1] neg_hi:[0,1]

.LBB0_670:
	v_add_u32_e32 v160, 0x11000, v155
	v_lshlrev_b32_e32 v161, 3, v154
	v_add_u32_e32 v161, 0x2200, v161
	v_add_u32_e32 v162, 0x11100, v156
	v_cmp_ne_u32_e32 vcc, 0, v32
	v_cndmask_b32_e32 v163, 0, v154, vcc
	v_lshlrev_b32_e32 v163, 3, v163
	v_add_u32_e32 v163, 0x11000, v163
	s_mov_b32 s100, 0x38800000
	s_mov_b32 s101, 0xb8800000
	ds_read_b64 v[214:215], v160 offset:0
	ds_read_b64 v[216:217], v163
	ds_read_b64 v[218:219], v160 offset:4352
	ds_read_b64 v[220:221], v162 offset:60928
	ds_read_b64 v[222:223], v160 offset:8704
	ds_read_b64 v[224:225], v161 offset:52224
	ds_read_b64 v[226:227], v160 offset:13056
	ds_read_b64 v[228:229], v162 offset:52224
	s_waitcnt lgkmcnt(6)
	v_sub_f32_e32 v216, v216, v214
	v_add_f32_e32 v214, v215, v217
	v_pk_mul_f32 v[216:217], v[6:7], v[216:217] op_sel:[1,0] op_sel_hi:[0,0]
	v_pk_fma_f32 v[158:159], v[6:7], v[214:215], v[216:217] neg_lo:[0,0,1] neg_hi:[0,0,1]
	v_pk_fma_f32 v[214:215], v[6:7], v[214:215], v[216:217] op_sel_hi:[1,0,1]
	s_nop 0
	v_mov_b32_e32 v159, v215
	v_pk_mul_f32 v[6:7], v[158:159], s[100:101]
	ds_write_b64 v155, v[6:7] offset:0
	s_waitcnt lgkmcnt(5)
	v_sub_f32_e32 v220, v220, v218
	v_add_f32_e32 v218, v219, v221
	v_pk_mul_f32 v[220:221], v[18:19], v[220:221] op_sel:[1,0] op_sel_hi:[0,0]
	v_pk_fma_f32 v[158:159], v[18:19], v[218:219], v[220:221] neg_lo:[0,0,1] neg_hi:[0,0,1]
	v_pk_fma_f32 v[218:219], v[18:19], v[218:219], v[220:221] op_sel_hi:[1,0,1]
	s_nop 0
	v_mov_b32_e32 v159, v219
	v_pk_mul_f32 v[18:19], v[158:159], s[100:101]
	ds_write_b64 v155, v[18:19] offset:4352
	ds_read_b64 v[230:231], v160 offset:17408
	ds_read_b64 v[232:233], v161 offset:43520
	ds_read_b64 v[234:235], v160 offset:21760
	ds_read_b64 v[236:237], v162 offset:43520
	s_waitcnt lgkmcnt(8)
	v_sub_f32_e32 v224, v224, v222
	v_add_f32_e32 v222, v223, v225
	v_pk_mul_f32 v[224:225], v[28:29], v[224:225] op_sel:[1,0] op_sel_hi:[0,0]
	v_pk_fma_f32 v[158:159], v[28:29], v[222:223], v[224:225] neg_lo:[0,0,1] neg_hi:[0,0,1]
	v_pk_fma_f32 v[222:223], v[28:29], v[222:223], v[224:225] op_sel_hi:[1,0,1]
	s_nop 0
	v_mov_b32_e32 v159, v223
	v_pk_mul_f32 v[28:29], v[158:159], s[100:101]
	ds_write_b64 v155, v[28:29] offset:8704
	s_waitcnt lgkmcnt(7)
	v_sub_f32_e32 v228, v228, v226
	v_add_f32_e32 v226, v227, v229
	v_pk_mul_f32 v[228:229], v[10:11], v[228:229] op_sel:[1,0] op_sel_hi:[0,0]
	v_pk_fma_f32 v[158:159], v[10:11], v[226:227], v[228:229] neg_lo:[0,0,1] neg_hi:[0,0,1]
	v_pk_fma_f32 v[226:227], v[10:11], v[226:227], v[228:229] op_sel_hi:[1,0,1]
	s_nop 0
	v_mov_b32_e32 v159, v227
	v_pk_mul_f32 v[10:11], v[158:159], s[100:101]
	ds_write_b64 v155, v[10:11] offset:13056
	ds_read_b64 v[214:215], v160 offset:26112
	ds_read_b64 v[216:217], v161 offset:34816
	ds_read_b64 v[218:219], v160 offset:30464
	ds_read_b64 v[220:221], v162 offset:34816
	s_waitcnt lgkmcnt(8)
	v_sub_f32_e32 v232, v232, v230
	v_add_f32_e32 v230, v231, v233
	v_pk_mul_f32 v[232:233], v[26:27], v[232:233] op_sel:[1,0] op_sel_hi:[0,0]
	v_pk_fma_f32 v[158:159], v[26:27], v[230:231], v[232:233] neg_lo:[0,0,1] neg_hi:[0,0,1]
	v_pk_fma_f32 v[230:231], v[26:27], v[230:231], v[232:233] op_sel_hi:[1,0,1]
	s_nop 0
	v_mov_b32_e32 v159, v231
	v_pk_mul_f32 v[26:27], v[158:159], s[100:101]
	ds_write_b64 v155, v[26:27] offset:17408
	s_waitcnt lgkmcnt(7)
	v_sub_f32_e32 v236, v236, v234
	v_add_f32_e32 v234, v235, v237
	v_pk_mul_f32 v[236:237], v[30:31], v[236:237] op_sel:[1,0] op_sel_hi:[0,0]
	v_pk_fma_f32 v[158:159], v[30:31], v[234:235], v[236:237] neg_lo:[0,0,1] neg_hi:[0,0,1]
	v_pk_fma_f32 v[234:235], v[30:31], v[234:235], v[236:237] op_sel_hi:[1,0,1]
	s_nop 0
	v_mov_b32_e32 v159, v235
	v_pk_mul_f32 v[30:31], v[158:159], s[100:101]
	ds_write_b64 v155, v[30:31] offset:21760
	ds_read_b64 v[222:223], v160 offset:34816
	ds_read_b64 v[224:225], v161 offset:26112
	ds_read_b64 v[226:227], v160 offset:39168
	ds_read_b64 v[228:229], v162 offset:26112
	s_waitcnt lgkmcnt(8)
	v_sub_f32_e32 v216, v216, v214
	v_add_f32_e32 v214, v215, v217
	v_pk_mul_f32 v[216:217], v[58:59], v[216:217] op_sel:[1,0] op_sel_hi:[0,0]
	v_pk_fma_f32 v[158:159], v[58:59], v[214:215], v[216:217] neg_lo:[0,0,1] neg_hi:[0,0,1]
	v_pk_fma_f32 v[214:215], v[58:59], v[214:215], v[216:217] op_sel_hi:[1,0,1]
	s_nop 0
	v_mov_b32_e32 v159, v215
	v_pk_mul_f32 v[58:59], v[158:159], s[100:101]
	ds_write_b64 v155, v[58:59] offset:26112
	s_waitcnt lgkmcnt(7)
	v_sub_f32_e32 v220, v220, v218
	v_add_f32_e32 v218, v219, v221
	v_pk_mul_f32 v[220:221], v[12:13], v[220:221] op_sel:[1,0] op_sel_hi:[0,0]
	v_pk_fma_f32 v[158:159], v[12:13], v[218:219], v[220:221] neg_lo:[0,0,1] neg_hi:[0,0,1]
	v_pk_fma_f32 v[218:219], v[12:13], v[218:219], v[220:221] op_sel_hi:[1,0,1]
	s_nop 0
	v_mov_b32_e32 v159, v219
	v_pk_mul_f32 v[12:13], v[158:159], s[100:101]
	ds_write_b64 v155, v[12:13] offset:30464
	ds_read_b64 v[230:231], v160 offset:43520
	ds_read_b64 v[232:233], v161 offset:17408
	ds_read_b64 v[234:235], v160 offset:47872
	ds_read_b64 v[236:237], v162 offset:17408
	s_waitcnt lgkmcnt(8)
	v_sub_f32_e32 v224, v224, v222
	v_add_f32_e32 v222, v223, v225
	v_pk_mul_f32 v[224:225], v[14:15], v[224:225] op_sel:[1,0] op_sel_hi:[0,0]
	v_pk_fma_f32 v[158:159], v[14:15], v[222:223], v[224:225] neg_lo:[0,0,1] neg_hi:[0,0,1]
	v_pk_fma_f32 v[222:223], v[14:15], v[222:223], v[224:225] op_sel_hi:[1,0,1]
	s_nop 0
	v_mov_b32_e32 v159, v223
	v_pk_mul_f32 v[14:15], v[158:159], s[100:101]
	ds_write_b64 v155, v[14:15] offset:34816
	s_waitcnt lgkmcnt(7)
	v_sub_f32_e32 v228, v228, v226
	v_add_f32_e32 v226, v227, v229
	v_pk_mul_f32 v[228:229], v[20:21], v[228:229] op_sel:[1,0] op_sel_hi:[0,0]
	v_pk_fma_f32 v[158:159], v[20:21], v[226:227], v[228:229] neg_lo:[0,0,1] neg_hi:[0,0,1]
	v_pk_fma_f32 v[226:227], v[20:21], v[226:227], v[228:229] op_sel_hi:[1,0,1]
	s_nop 0
	v_mov_b32_e32 v159, v227
	v_pk_mul_f32 v[20:21], v[158:159], s[100:101]
	ds_write_b64 v155, v[20:21] offset:39168
	ds_read_b64 v[214:215], v160 offset:52224
	ds_read_b64 v[216:217], v161 offset:8704
	ds_read_b64 v[218:219], v160 offset:56576
	ds_read_b64 v[220:221], v162 offset:8704
	s_waitcnt lgkmcnt(8)
	v_sub_f32_e32 v232, v232, v230
	v_add_f32_e32 v230, v231, v233
	v_pk_mul_f32 v[232:233], v[22:23], v[232:233] op_sel:[1,0] op_sel_hi:[0,0]
	v_pk_fma_f32 v[158:159], v[22:23], v[230:231], v[232:233] neg_lo:[0,0,1] neg_hi:[0,0,1]
	v_pk_fma_f32 v[230:231], v[22:23], v[230:231], v[232:233] op_sel_hi:[1,0,1]
	s_nop 0
	v_mov_b32_e32 v159, v231
	v_pk_mul_f32 v[22:23], v[158:159], s[100:101]
	ds_write_b64 v155, v[22:23] offset:43520
	s_waitcnt lgkmcnt(7)
	v_sub_f32_e32 v236, v236, v234
	v_add_f32_e32 v234, v235, v237
	v_pk_mul_f32 v[236:237], v[4:5], v[236:237] op_sel:[1,0] op_sel_hi:[0,0]
	v_pk_fma_f32 v[158:159], v[4:5], v[234:235], v[236:237] neg_lo:[0,0,1] neg_hi:[0,0,1]
	v_pk_fma_f32 v[234:235], v[4:5], v[234:235], v[236:237] op_sel_hi:[1,0,1]
	s_nop 0
	v_mov_b32_e32 v159, v235
	v_pk_mul_f32 v[4:5], v[158:159], s[100:101]
	ds_write_b64 v155, v[4:5] offset:47872
	ds_read_b64 v[222:223], v160 offset:60928
	ds_read_b64 v[224:225], v161 offset:0
	ds_read_b64 v[226:227], v160 offset:65280
	ds_read_b64 v[228:229], v162 offset:0
	s_waitcnt lgkmcnt(8)
	v_sub_f32_e32 v216, v216, v214
	v_add_f32_e32 v214, v215, v217
	v_pk_mul_f32 v[216:217], v[24:25], v[216:217] op_sel:[1,0] op_sel_hi:[0,0]
	v_pk_fma_f32 v[158:159], v[24:25], v[214:215], v[216:217] neg_lo:[0,0,1] neg_hi:[0,0,1]
	v_pk_fma_f32 v[214:215], v[24:25], v[214:215], v[216:217] op_sel_hi:[1,0,1]
	s_nop 0
	v_mov_b32_e32 v159, v215
	v_pk_mul_f32 v[24:25], v[158:159], s[100:101]
	ds_write_b64 v155, v[24:25] offset:52224
	s_waitcnt lgkmcnt(7)
	v_sub_f32_e32 v220, v220, v218
	v_add_f32_e32 v218, v219, v221
	v_pk_mul_f32 v[220:221], v[8:9], v[220:221] op_sel:[1,0] op_sel_hi:[0,0]
	v_pk_fma_f32 v[158:159], v[8:9], v[218:219], v[220:221] neg_lo:[0,0,1] neg_hi:[0,0,1]
	v_pk_fma_f32 v[218:219], v[8:9], v[218:219], v[220:221] op_sel_hi:[1,0,1]
	s_nop 0
	v_mov_b32_e32 v159, v219
	v_pk_mul_f32 v[8:9], v[158:159], s[100:101]
	ds_write_b64 v155, v[8:9] offset:56576
	s_waitcnt lgkmcnt(4)
	v_sub_f32_e32 v224, v224, v222
	v_add_f32_e32 v222, v223, v225
	v_pk_mul_f32 v[224:225], v[16:17], v[224:225] op_sel:[1,0] op_sel_hi:[0,0]
	v_pk_fma_f32 v[158:159], v[16:17], v[222:223], v[224:225] neg_lo:[0,0,1] neg_hi:[0,0,1]
	v_pk_fma_f32 v[222:223], v[16:17], v[222:223], v[224:225] op_sel_hi:[1,0,1]
	s_nop 0
	v_mov_b32_e32 v159, v223
	v_pk_mul_f32 v[16:17], v[158:159], s[100:101]
	ds_write_b64 v155, v[16:17] offset:60928
	s_waitcnt lgkmcnt(3)
	v_sub_f32_e32 v228, v228, v226
	v_add_f32_e32 v226, v227, v229
	v_pk_mul_f32 v[228:229], v[0:1], v[228:229] op_sel:[1,0] op_sel_hi:[0,0]
	v_pk_fma_f32 v[158:159], v[0:1], v[226:227], v[228:229] neg_lo:[0,0,1] neg_hi:[0,0,1]
	v_pk_fma_f32 v[226:227], v[0:1], v[226:227], v[228:229] op_sel_hi:[1,0,1]
	s_nop 0
	v_mov_b32_e32 v159, v227
	v_pk_mul_f32 v[0:1], v[158:159], s[100:101]
	ds_write_b64 v155, v[0:1] offset:65280
	s_mov_b32 s4, 16
	s_cmp_lg_u32 s4, 16
	s_waitcnt lgkmcnt(0)
	s_barrier
	s_and_saveexec_b64 s[28:29], s[40:41]
	s_cbranch_execz .LBB0_673
	ds_read_b64 v[0:1], v153
	ds_read_b64 v[2:3], v153 offset:2176
	ds_read_b64 v[4:5], v153 offset:4352
	ds_read_b64 v[6:7], v153 offset:6528
	ds_read_b64 v[8:9], v153 offset:8704
	ds_read_b64 v[10:11], v153 offset:10880
	ds_read_b64 v[12:13], v153 offset:13056
	ds_read_b64 v[14:15], v153 offset:15232
	ds_read_b64 v[16:17], v153 offset:17408
	ds_read_b64 v[18:19], v153 offset:19584
	ds_read_b64 v[20:21], v153 offset:21760
	ds_read_b64 v[22:23], v153 offset:23936
	ds_read_b64 v[24:25], v153 offset:26112
	ds_read_b64 v[26:27], v153 offset:28288
	ds_read_b64 v[28:29], v153 offset:30464
	ds_read_b64 v[30:31], v153 offset:32640
	ds_read_b64 v[58:59], v153 offset:34816
	ds_read_b64 v[60:61], v153 offset:41344
	ds_read_b64 v[94:95], v153 offset:43520
	ds_read_b64 v[96:97], v153 offset:45696
	ds_read_b64 v[98:99], v153 offset:47872
	ds_read_b64 v[100:101], v153 offset:50048
	ds_read_b64 v[102:103], v153 offset:52224
	ds_read_b64 v[104:105], v153 offset:54400
	ds_read_b64 v[106:107], v153 offset:56576
	ds_read_b64 v[108:109], v153 offset:58752
	ds_read_b64 v[110:111], v153 offset:60928
	ds_read_b64 v[112:113], v153 offset:63104
	ds_read_b64 v[114:115], v153 offset:65280
	ds_read_b64 v[116:117], v153 offset:36992
	ds_read_b64 v[118:119], v153 offset:39168
	ds_read_b64 v[120:121], v33
	s_waitcnt lgkmcnt(14)
	v_pk_add_f32 v[124:125], v[0:1], v[58:59]
	v_pk_add_f32 v[0:1], v[0:1], v[58:59] neg_lo:[0,1] neg_hi:[0,1]
	s_waitcnt lgkmcnt(2)
	v_pk_add_f32 v[58:59], v[2:3], v[116:117]
	v_pk_add_f32 v[2:3], v[2:3], v[116:117] neg_lo:[0,1] neg_hi:[0,1]
	s_mov_b32 s11, s14
	v_pk_mul_f32 v[116:117], v[2:3], s[16:17]
	s_mov_b32 s13, s86
	v_pk_fma_f32 v[2:3], v[2:3], s[6:7], v[116:117] op_sel:[0,0,1] op_sel_hi:[1,0,0]
	s_waitcnt lgkmcnt(1)
	v_pk_add_f32 v[116:117], v[4:5], v[118:119]
	v_pk_add_f32 v[4:5], v[4:5], v[118:119] neg_lo:[0,1] neg_hi:[0,1]
	s_mov_b32 s4, s21
	v_pk_mul_f32 v[118:119], v[4:5], s[18:19]
	s_mov_b32 s35, s30
	v_pk_fma_f32 v[4:5], v[4:5], s[30:31], v[118:119] op_sel:[0,0,1] op_sel_hi:[1,0,0]
	v_pk_add_f32 v[118:119], v[6:7], v[60:61]
	v_pk_add_f32 v[6:7], v[6:7], v[60:61] neg_lo:[0,1] neg_hi:[0,1]
	s_mov_b32 s8, s19
	v_pk_mul_f32 v[60:61], v[6:7], s[20:21]
	s_mov_b32 s77, s6
	v_pk_fma_f32 v[6:7], v[6:7], s[86:87], v[60:61] op_sel:[0,0,1] op_sel_hi:[1,0,0]
	v_pk_add_f32 v[60:61], v[8:9], v[94:95]
	v_pk_add_f32 v[8:9], v[8:9], v[94:95] neg_lo:[0,1] neg_hi:[0,1]
	s_mov_b32 s26, s17
	v_pk_mul_f32 v[94:95], v[8:9], s[10:11]
	s_nop 0
	v_pk_fma_f32 v[8:9], v[8:9], s[14:15], v[94:95] op_sel:[0,0,1] op_sel_hi:[1,0,0]
	v_pk_add_f32 v[94:95], v[10:11], v[96:97]
	v_pk_add_f32 v[10:11], v[10:11], v[96:97] neg_lo:[0,1] neg_hi:[0,1]
	s_nop 0
	v_pk_mul_f32 v[96:97], v[10:11], s[12:13]
	s_nop 0
	v_pk_fma_f32 v[10:11], v[10:11], s[4:5], v[96:97] op_sel:[0,0,1] op_sel_hi:[1,0,0]
	v_pk_add_f32 v[96:97], v[12:13], v[98:99]
	v_pk_add_f32 v[12:13], v[12:13], v[98:99] neg_lo:[0,1] neg_hi:[0,1]
	s_nop 0
	v_pk_mul_f32 v[98:99], v[12:13], s[34:35]
	s_nop 0
	v_pk_fma_f32 v[12:13], v[12:13], s[8:9], v[98:99] op_sel:[0,0,1] op_sel_hi:[1,0,0]
	v_pk_add_f32 v[98:99], v[14:15], v[100:101]
	v_pk_add_f32 v[14:15], v[14:15], v[100:101] neg_lo:[0,1] neg_hi:[0,1]
	s_nop 0
	v_pk_mul_f32 v[100:101], v[14:15], s[76:77]
	s_nop 0
	v_pk_fma_f32 v[14:15], v[14:15], s[26:27], v[100:101] op_sel:[0,0,1] op_sel_hi:[1,0,0]
	v_pk_add_f32 v[100:101], v[16:17], v[102:103]
	v_pk_add_f32 v[16:17], v[16:17], v[102:103] neg_lo:[0,1] neg_hi:[0,1]
	v_pk_add_f32 v[102:103], v[18:19], v[104:105]
	v_pk_add_f32 v[18:19], v[18:19], v[104:105] neg_lo:[0,1] neg_hi:[0,1]
	s_nop 0
	v_pk_mul_f32 v[104:105], v[18:19], s[76:77]
	s_nop 0
	v_pk_fma_f32 v[18:19], v[18:19], s[26:27], v[104:105] op_sel:[0,0,1] op_sel_hi:[1,0,0] neg_lo:[1,0,0] neg_hi:[1,0,0]
	v_pk_add_f32 v[104:105], v[20:21], v[106:107]
	v_pk_add_f32 v[20:21], v[20:21], v[106:107] neg_lo:[0,1] neg_hi:[0,1]
	s_nop 0
	v_pk_mul_f32 v[106:107], v[20:21], s[34:35]
	s_nop 0
	v_pk_fma_f32 v[20:21], v[20:21], s[8:9], v[106:107] op_sel:[0,0,1] op_sel_hi:[1,0,0] neg_lo:[1,0,0] neg_hi:[1,0,0]
	v_pk_add_f32 v[106:107], v[22:23], v[108:109]
	v_pk_add_f32 v[22:23], v[22:23], v[108:109] neg_lo:[0,1] neg_hi:[0,1]
	s_nop 0
	v_pk_mul_f32 v[108:109], v[22:23], s[12:13]
	s_nop 0
	v_pk_fma_f32 v[22:23], v[22:23], s[4:5], v[108:109] op_sel:[0,0,1] op_sel_hi:[1,0,0] neg_lo:[1,0,0] neg_hi:[1,0,0]
	v_pk_add_f32 v[108:109], v[24:25], v[110:111]
	v_pk_add_f32 v[24:25], v[24:25], v[110:111] neg_lo:[0,1] neg_hi:[0,1]
	s_nop 0
	v_pk_mul_f32 v[110:111], v[24:25], s[10:11]
	s_nop 0
	v_pk_fma_f32 v[24:25], v[24:25], s[14:15], v[110:111] op_sel:[0,0,1] op_sel_hi:[1,0,0] neg_lo:[1,0,0] neg_hi:[1,0,0]
	v_pk_add_f32 v[110:111], v[26:27], v[112:113]
	v_pk_add_f32 v[26:27], v[26:27], v[112:113] neg_lo:[0,1] neg_hi:[0,1]
	s_nop 0
	v_pk_mul_f32 v[112:113], v[26:27], s[20:21]
	s_nop 0
	v_pk_fma_f32 v[26:27], v[26:27], s[86:87], v[112:113] op_sel:[0,0,1] op_sel_hi:[1,0,0] neg_lo:[1,0,0] neg_hi:[1,0,0]
	v_pk_add_f32 v[112:113], v[28:29], v[114:115]
	v_pk_add_f32 v[28:29], v[28:29], v[114:115] neg_lo:[0,1] neg_hi:[0,1]
	s_nop 0
	v_pk_mul_f32 v[114:115], v[28:29], s[18:19]
	s_nop 0
	v_pk_fma_f32 v[28:29], v[28:29], s[30:31], v[114:115] op_sel:[0,0,1] op_sel_hi:[1,0,0] neg_lo:[1,0,0] neg_hi:[1,0,0]
	s_waitcnt lgkmcnt(0)
	v_pk_add_f32 v[114:115], v[30:31], v[120:121]
	v_pk_add_f32 v[30:31], v[30:31], v[120:121] neg_lo:[0,1] neg_hi:[0,1]
	s_nop 0
	v_pk_mul_f32 v[120:121], v[30:31], s[16:17]
	s_nop 0
	v_pk_fma_f32 v[30:31], v[30:31], s[6:7], v[120:121] op_sel:[0,0,1] op_sel_hi:[1,0,0] neg_lo:[1,0,0] neg_hi:[1,0,0]
	v_pk_add_f32 v[120:121], v[124:125], v[100:101]
	v_pk_add_f32 v[100:101], v[124:125], v[100:101] neg_lo:[0,1] neg_hi:[0,1]
	v_pk_add_f32 v[124:125], v[58:59], v[102:103]
	v_pk_add_f32 v[58:59], v[58:59], v[102:103] neg_lo:[0,1] neg_hi:[0,1]
	s_nop 0
	v_pk_mul_f32 v[102:103], v[58:59], s[18:19]
	s_nop 0
	v_pk_fma_f32 v[58:59], v[58:59], s[30:31], v[102:103] op_sel:[0,0,1] op_sel_hi:[1,0,0]
	v_pk_add_f32 v[102:103], v[116:117], v[104:105]
	v_pk_add_f32 v[104:105], v[116:117], v[104:105] neg_lo:[0,1] neg_hi:[0,1]
	s_nop 0
	v_pk_mul_f32 v[116:117], v[104:105], s[10:11]
	s_nop 0
	v_pk_fma_f32 v[104:105], v[104:105], s[14:15], v[116:117] op_sel:[0,0,1] op_sel_hi:[1,0,0]
	v_pk_add_f32 v[116:117], v[118:119], v[106:107]
	v_pk_add_f32 v[106:107], v[118:119], v[106:107] neg_lo:[0,1] neg_hi:[0,1]
	s_nop 0
	v_pk_mul_f32 v[118:119], v[106:107], s[34:35]
	s_nop 0
	v_pk_fma_f32 v[106:107], v[106:107], s[8:9], v[118:119] op_sel:[0,0,1] op_sel_hi:[1,0,0]
	v_pk_add_f32 v[118:119], v[60:61], v[108:109]
	v_pk_add_f32 v[60:61], v[60:61], v[108:109] neg_lo:[0,1] neg_hi:[0,1]
	v_pk_add_f32 v[108:109], v[94:95], v[110:111]
	v_pk_add_f32 v[94:95], v[94:95], v[110:111] neg_lo:[0,1] neg_hi:[0,1]
	s_nop 0
	v_pk_mul_f32 v[110:111], v[94:95], s[34:35]
	s_nop 0
	v_pk_fma_f32 v[94:95], v[94:95], s[8:9], v[110:111] op_sel:[0,0,1] op_sel_hi:[1,0,0] neg_lo:[1,0,0] neg_hi:[1,0,0]
	v_pk_add_f32 v[110:111], v[96:97], v[112:113]
	v_pk_add_f32 v[96:97], v[96:97], v[112:113] neg_lo:[0,1] neg_hi:[0,1]
	s_nop 0
	v_pk_mul_f32 v[112:113], v[96:97], s[10:11]
	s_nop 0
	v_pk_fma_f32 v[96:97], v[96:97], s[14:15], v[112:113] op_sel:[0,0,1] op_sel_hi:[1,0,0] neg_lo:[1,0,0] neg_hi:[1,0,0]
	v_pk_add_f32 v[112:113], v[98:99], v[114:115]
	v_pk_add_f32 v[98:99], v[98:99], v[114:115] neg_lo:[0,1] neg_hi:[0,1]
	s_nop 0
	v_pk_mul_f32 v[114:115], v[98:99], s[18:19]
	s_nop 0
	v_pk_fma_f32 v[98:99], v[98:99], s[30:31], v[114:115] op_sel:[0,0,1] op_sel_hi:[1,0,0] neg_lo:[1,0,0] neg_hi:[1,0,0]
	v_pk_add_f32 v[114:115], v[0:1], v[16:17] op_sel:[0,1] op_sel_hi:[1,0] neg_hi:[0,1]
	v_pk_add_f32 v[0:1], v[0:1], v[16:17] op_sel:[0,1] op_sel_hi:[1,0] neg_lo:[0,1]
	v_pk_add_f32 v[16:17], v[2:3], v[18:19]
	v_pk_add_f32 v[2:3], v[2:3], v[18:19] neg_lo:[0,1] neg_hi:[0,1]
	s_nop 0
	v_pk_mul_f32 v[18:19], v[2:3], s[18:19]
	s_nop 0
	v_pk_fma_f32 v[2:3], v[2:3], s[30:31], v[18:19] op_sel:[0,0,1] op_sel_hi:[1,0,0]
	v_pk_add_f32 v[18:19], v[4:5], v[20:21]
	v_pk_add_f32 v[4:5], v[4:5], v[20:21] neg_lo:[0,1] neg_hi:[0,1]
	s_nop 0
	v_pk_mul_f32 v[20:21], v[4:5], s[10:11]
	s_nop 0
	v_pk_fma_f32 v[4:5], v[4:5], s[14:15], v[20:21] op_sel:[0,0,1] op_sel_hi:[1,0,0]
	v_pk_add_f32 v[20:21], v[6:7], v[22:23]
	v_pk_add_f32 v[6:7], v[6:7], v[22:23] neg_lo:[0,1] neg_hi:[0,1]
	s_nop 0
	v_pk_mul_f32 v[22:23], v[6:7], s[34:35]
	s_nop 0
	v_pk_fma_f32 v[6:7], v[6:7], s[8:9], v[22:23] op_sel:[0,0,1] op_sel_hi:[1,0,0]
	v_pk_add_f32 v[22:23], v[8:9], v[24:25]
	v_pk_add_f32 v[8:9], v[8:9], v[24:25] neg_lo:[0,1] neg_hi:[0,1]
	v_pk_add_f32 v[24:25], v[10:11], v[26:27]
	v_pk_add_f32 v[10:11], v[10:11], v[26:27] neg_lo:[0,1] neg_hi:[0,1]
	s_nop 0
	v_pk_mul_f32 v[26:27], v[10:11], s[34:35]
	s_nop 0
	v_pk_fma_f32 v[10:11], v[10:11], s[8:9], v[26:27] op_sel:[0,0,1] op_sel_hi:[1,0,0] neg_lo:[1,0,0] neg_hi:[1,0,0]
	v_pk_add_f32 v[26:27], v[12:13], v[28:29]
	v_pk_add_f32 v[12:13], v[12:13], v[28:29] neg_lo:[0,1] neg_hi:[0,1]
	s_nop 0
	v_pk_mul_f32 v[28:29], v[12:13], s[10:11]
	s_nop 0
	v_pk_fma_f32 v[12:13], v[12:13], s[14:15], v[28:29] op_sel:[0,0,1] op_sel_hi:[1,0,0] neg_lo:[1,0,0] neg_hi:[1,0,0]
	v_pk_add_f32 v[28:29], v[14:15], v[30:31]
	v_pk_add_f32 v[14:15], v[14:15], v[30:31] neg_lo:[0,1] neg_hi:[0,1]
	s_nop 0
	v_pk_mul_f32 v[30:31], v[14:15], s[18:19]
	s_nop 0
	v_pk_fma_f32 v[14:15], v[14:15], s[30:31], v[30:31] op_sel:[0,0,1] op_sel_hi:[1,0,0] neg_lo:[1,0,0] neg_hi:[1,0,0]
	v_pk_add_f32 v[30:31], v[120:121], v[118:119]
	v_pk_add_f32 v[118:119], v[120:121], v[118:119] neg_lo:[0,1] neg_hi:[0,1]
	v_pk_add_f32 v[120:121], v[124:125], v[108:109]
	v_pk_add_f32 v[108:109], v[124:125], v[108:109] neg_lo:[0,1] neg_hi:[0,1]
	s_nop 0
	v_pk_mul_f32 v[124:125], v[108:109], s[10:11]
	s_nop 0
	v_pk_fma_f32 v[108:109], v[108:109], s[14:15], v[124:125] op_sel:[0,0,1] op_sel_hi:[1,0,0]
	v_pk_add_f32 v[124:125], v[102:103], v[110:111]
	v_pk_add_f32 v[102:103], v[102:103], v[110:111] neg_lo:[0,1] neg_hi:[0,1]
	v_pk_add_f32 v[110:111], v[116:117], v[112:113]
	v_pk_add_f32 v[112:113], v[116:117], v[112:113] neg_lo:[0,1] neg_hi:[0,1]
	s_nop 0
	v_pk_mul_f32 v[116:117], v[112:113], s[10:11]
	s_nop 0
	v_pk_fma_f32 v[112:113], v[112:113], s[14:15], v[116:117] op_sel:[0,0,1] op_sel_hi:[1,0,0] neg_lo:[1,0,0] neg_hi:[1,0,0]
	v_pk_add_f32 v[116:117], v[100:101], v[60:61] op_sel:[0,1] op_sel_hi:[1,0] neg_hi:[0,1]
	v_pk_add_f32 v[60:61], v[100:101], v[60:61] op_sel:[0,1] op_sel_hi:[1,0] neg_lo:[0,1]
	v_pk_add_f32 v[100:101], v[58:59], v[94:95]
	v_pk_add_f32 v[58:59], v[58:59], v[94:95] neg_lo:[0,1] neg_hi:[0,1]
	v_pk_add_f32 v[126:127], v[108:109], v[112:113]
	v_pk_mul_f32 v[94:95], v[58:59], s[10:11]
	s_nop 0
	v_pk_fma_f32 v[58:59], v[58:59], s[14:15], v[94:95] op_sel:[0,0,1] op_sel_hi:[1,0,0]
	v_pk_add_f32 v[94:95], v[104:105], v[96:97]
	v_pk_add_f32 v[96:97], v[104:105], v[96:97] neg_lo:[0,1] neg_hi:[0,1]
	v_pk_add_f32 v[104:105], v[106:107], v[98:99]
	v_pk_add_f32 v[98:99], v[106:107], v[98:99] neg_lo:[0,1] neg_hi:[0,1]
	s_nop 0
	v_pk_mul_f32 v[106:107], v[98:99], s[10:11]
	v_pk_add_f32 v[130:131], v[60:61], v[96:97] op_sel:[0,1] op_sel_hi:[1,0] neg_hi:[0,1]
	v_pk_fma_f32 v[98:99], v[98:99], s[14:15], v[106:107] op_sel:[0,0,1] op_sel_hi:[1,0,0] neg_lo:[1,0,0] neg_hi:[1,0,0]
	v_pk_add_f32 v[106:107], v[114:115], v[22:23]
	v_pk_add_f32 v[22:23], v[114:115], v[22:23] neg_lo:[0,1] neg_hi:[0,1]
	v_pk_add_f32 v[114:115], v[16:17], v[24:25]
	v_pk_add_f32 v[16:17], v[16:17], v[24:25] neg_lo:[0,1] neg_hi:[0,1]
	v_pk_add_f32 v[132:133], v[60:61], v[96:97] op_sel:[0,1] op_sel_hi:[1,0] neg_lo:[0,1]
	v_pk_mul_f32 v[24:25], v[16:17], s[10:11]
	v_pk_add_f32 v[60:61], v[58:59], v[98:99]
	v_pk_fma_f32 v[16:17], v[16:17], s[14:15], v[24:25] op_sel:[0,0,1] op_sel_hi:[1,0,0]
	v_pk_add_f32 v[24:25], v[18:19], v[26:27]
	v_pk_add_f32 v[18:19], v[18:19], v[26:27] neg_lo:[0,1] neg_hi:[0,1]
	v_pk_add_f32 v[26:27], v[20:21], v[28:29]
	v_pk_add_f32 v[20:21], v[20:21], v[28:29] neg_lo:[0,1] neg_hi:[0,1]
	s_nop 0
	v_pk_mul_f32 v[28:29], v[20:21], s[10:11]
	v_pk_add_f32 v[58:59], v[58:59], v[98:99] neg_lo:[0,1] neg_hi:[0,1]
	v_pk_fma_f32 v[20:21], v[20:21], s[14:15], v[28:29] op_sel:[0,0,1] op_sel_hi:[1,0,0] neg_lo:[1,0,0] neg_hi:[1,0,0]
	v_pk_add_f32 v[28:29], v[0:1], v[8:9] op_sel:[0,1] op_sel_hi:[1,0] neg_hi:[0,1]
	v_pk_add_f32 v[0:1], v[0:1], v[8:9] op_sel:[0,1] op_sel_hi:[1,0] neg_lo:[0,1]
	v_pk_add_f32 v[8:9], v[2:3], v[10:11]
	v_pk_add_f32 v[2:3], v[2:3], v[10:11] neg_lo:[0,1] neg_hi:[0,1]
	v_pk_add_f32 v[134:135], v[106:107], v[24:25]
	v_pk_mul_f32 v[10:11], v[2:3], s[10:11]
	v_pk_add_f32 v[106:107], v[106:107], v[24:25] neg_lo:[0,1] neg_hi:[0,1]
	v_pk_fma_f32 v[2:3], v[2:3], s[14:15], v[10:11] op_sel:[0,0,1] op_sel_hi:[1,0,0]
	v_pk_add_f32 v[10:11], v[4:5], v[12:13]
	v_pk_add_f32 v[4:5], v[4:5], v[12:13] neg_lo:[0,1] neg_hi:[0,1]
	v_pk_add_f32 v[12:13], v[6:7], v[14:15]
	v_pk_add_f32 v[6:7], v[6:7], v[14:15] neg_lo:[0,1] neg_hi:[0,1]
	s_nop 0
	v_pk_mul_f32 v[14:15], v[6:7], s[10:11]
	v_pk_add_f32 v[24:25], v[114:115], v[26:27] neg_lo:[0,1] neg_hi:[0,1]
	v_pk_fma_f32 v[6:7], v[6:7], s[14:15], v[14:15] op_sel:[0,0,1] op_sel_hi:[1,0,0] neg_lo:[1,0,0] neg_hi:[1,0,0]
	v_pk_add_f32 v[14:15], v[30:31], v[124:125]
	v_pk_add_f32 v[30:31], v[30:31], v[124:125] neg_lo:[0,1] neg_hi:[0,1]
	v_pk_add_f32 v[124:125], v[120:121], v[110:111]
	v_pk_add_f32 v[110:111], v[120:121], v[110:111] neg_lo:[0,1] neg_hi:[0,1]
	v_pk_add_f32 v[120:121], v[118:119], v[102:103] op_sel:[0,1] op_sel_hi:[1,0] neg_hi:[0,1]
	v_pk_add_f32 v[118:119], v[118:119], v[102:103] op_sel:[0,1] op_sel_hi:[1,0] neg_lo:[0,1]
	v_pk_add_f32 v[102:103], v[108:109], v[112:113] neg_lo:[0,1] neg_hi:[0,1]
	v_pk_add_f32 v[112:113], v[116:117], v[94:95]
	v_pk_add_f32 v[94:95], v[116:117], v[94:95] neg_lo:[0,1] neg_hi:[0,1]
	v_pk_add_f32 v[116:117], v[100:101], v[104:105]
	v_pk_add_f32 v[100:101], v[100:101], v[104:105] neg_lo:[0,1] neg_hi:[0,1]
	v_pk_add_f32 v[138:139], v[22:23], v[18:19] op_sel:[0,1] op_sel_hi:[1,0] neg_hi:[0,1]
	v_pk_add_f32 v[140:141], v[22:23], v[18:19] op_sel:[0,1] op_sel_hi:[1,0] neg_lo:[0,1]
	v_pk_add_f32 v[18:19], v[16:17], v[20:21]
	v_pk_add_f32 v[16:17], v[16:17], v[20:21] neg_lo:[0,1] neg_hi:[0,1]
	v_pk_add_f32 v[144:145], v[28:29], v[10:11]
	v_pk_add_f32 v[158:159], v[28:29], v[10:11] neg_lo:[0,1] neg_hi:[0,1]
	v_pk_add_f32 v[10:11], v[8:9], v[12:13]
	v_pk_add_f32 v[8:9], v[8:9], v[12:13] neg_lo:[0,1] neg_hi:[0,1]
	v_pk_add_f32 v[162:163], v[0:1], v[4:5] op_sel:[0,1] op_sel_hi:[1,0] neg_hi:[0,1]
	v_pk_add_f32 v[164:165], v[0:1], v[4:5] op_sel:[0,1] op_sel_hi:[1,0] neg_lo:[0,1]
	v_pk_add_f32 v[0:1], v[2:3], v[6:7] neg_lo:[0,1] neg_hi:[0,1]
	v_pk_mul_f32 v[108:109], v[102:103], s[22:23]
	v_pk_mul_f32 v[128:129], v[100:101], s[22:23]
	v_pk_add_f32 v[136:137], v[114:115], v[26:27]
	v_pk_mul_f32 v[114:115], v[24:25], s[22:23]
	v_pk_mul_f32 v[142:143], v[16:17], s[22:23]
	v_pk_mul_f32 v[160:161], v[8:9], s[22:23]
	v_pk_add_f32 v[166:167], v[2:3], v[6:7]
	v_pk_mul_f32 v[168:169], v[0:1], s[22:23]
	v_pk_add_f32 v[28:29], v[14:15], v[124:125]
	v_pk_add_f32 v[104:105], v[14:15], v[124:125] neg_lo:[0,1] neg_hi:[0,1]
	v_pk_add_f32 v[24:25], v[30:31], v[110:111] op_sel:[0,1] op_sel_hi:[1,0] neg_hi:[0,1]
	v_pk_add_f32 v[102:103], v[30:31], v[110:111] op_sel:[0,1] op_sel_hi:[1,0] neg_lo:[0,1]
	v_pk_add_f32 v[20:21], v[120:121], v[126:127]
	v_pk_add_f32 v[100:101], v[120:121], v[126:127] neg_lo:[0,1] neg_hi:[0,1]
	v_pk_add_f32 v[16:17], v[118:119], v[108:109] op_sel:[0,1] op_sel_hi:[1,0]
	v_pk_add_f32 v[98:99], v[118:119], v[108:109] op_sel:[0,1] op_sel_hi:[1,0] neg_lo:[0,1] neg_hi:[0,1]
	v_pk_add_f32 v[12:13], v[112:113], v[116:117]
	v_pk_add_f32 v[96:97], v[112:113], v[116:117] neg_lo:[0,1] neg_hi:[0,1]
	v_pk_add_f32 v[8:9], v[94:95], v[128:129] op_sel:[0,1] op_sel_hi:[1,0]
	v_pk_add_f32 v[94:95], v[94:95], v[128:129] op_sel:[0,1] op_sel_hi:[1,0] neg_lo:[0,1] neg_hi:[0,1]
	v_pk_add_f32 v[4:5], v[130:131], v[60:61]
	v_pk_add_f32 v[60:61], v[130:131], v[60:61] neg_lo:[0,1] neg_hi:[0,1]
	v_pk_add_f32 v[0:1], v[132:133], v[58:59] op_sel:[0,1] op_sel_hi:[1,0] neg_hi:[0,1]
	v_pk_add_f32 v[58:59], v[132:133], v[58:59] op_sel:[0,1] op_sel_hi:[1,0] neg_lo:[0,1]
	v_pk_add_f32 v[30:31], v[134:135], v[136:137]
	v_pk_add_f32 v[120:121], v[134:135], v[136:137] neg_lo:[0,1] neg_hi:[0,1]
	v_pk_add_f32 v[26:27], v[106:107], v[114:115] op_sel:[0,1] op_sel_hi:[1,0]
	v_pk_add_f32 v[118:119], v[106:107], v[114:115] op_sel:[0,1] op_sel_hi:[1,0] neg_lo:[0,1] neg_hi:[0,1]
	v_pk_add_f32 v[22:23], v[138:139], v[18:19]
	v_pk_add_f32 v[116:117], v[138:139], v[18:19] neg_lo:[0,1] neg_hi:[0,1]
	v_pk_add_f32 v[18:19], v[140:141], v[142:143] op_sel:[0,1] op_sel_hi:[1,0]
	v_pk_add_f32 v[114:115], v[140:141], v[142:143] op_sel:[0,1] op_sel_hi:[1,0] neg_lo:[0,1] neg_hi:[0,1]
	v_pk_add_f32 v[14:15], v[144:145], v[10:11]
	v_pk_add_f32 v[112:113], v[144:145], v[10:11] neg_lo:[0,1] neg_hi:[0,1]
	v_pk_add_f32 v[10:11], v[158:159], v[160:161] op_sel:[0,1] op_sel_hi:[1,0]
	v_pk_add_f32 v[110:111], v[158:159], v[160:161] op_sel:[0,1] op_sel_hi:[1,0] neg_lo:[0,1] neg_hi:[0,1]
	v_pk_add_f32 v[6:7], v[162:163], v[166:167]
	v_pk_add_f32 v[108:109], v[162:163], v[166:167] neg_lo:[0,1] neg_hi:[0,1]
	v_pk_add_f32 v[2:3], v[164:165], v[168:169] op_sel:[0,1] op_sel_hi:[1,0]
	v_pk_add_f32 v[106:107], v[164:165], v[168:169] op_sel:[0,1] op_sel_hi:[1,0] neg_lo:[0,1] neg_hi:[0,1]
